# v25 plus half-tile last round (rows split over CU pairs) in the four gate_up GEMM phases
# baseline (speedup 1.0000x reference)
;     __device__ bool next(int i, Unit& u) const { if (i > 0) return false; const int t = c - first; if (t < 0 || t >= nM * nN) return false; u.pm = t % nM; u.pn = t / nM; return true; }
;     __host__ __device__ bool next(int i, Unit& u) const {
;         const long L = (long)i * G + c; if (L >= nwg) return false;
;         int wgid = (int)L; { const int q = nwg / NXCD, r = nwg % NXCD, xcd = wgid % NXCD, off = wgid / NXCD; wgid = (xcd < r ? xcd * (q + 1) : r * (q + 1) + (xcd - r) * q) + off; }
;         const int nig = WGM * nN, gid = wgid / nig, fm = gid * WGM, gsz = (nM - fm) < WGM ? (nM - fm) : WGM;
;         u.pm = fm + ((wgid % nig) % gsz); u.pn = (wgid % nig) / gsz; return true;
; template <class Epi, class Sched, bool ALIGN_EPI = false, bool SP2 = false>
; __device__ __forceinline__ void gemm_phase(PG8_LAS unsigned char* lds, const Gemm g, const Sched& S, const Epi& E, int tid_in) {
;     ...
; #pragma unroll
;         for (int a = 0; a < 2; ++a)
; #pragma unroll
;             for (int b = 0; b < 2; ++b)
; #pragma unroll
;                 for (int m = 0; m < 4; ++m)
; #pragma unroll
;                     for (int n = 0; n < 2; ++n) acc[a][b][m][n] = (f32x4){0.f, 0.f, 0.f, 0.f};
;         cur = nxt; cA = nA; cB = nB; ++ui;
.LBB0_517:
	s_add_i32 s49, s49, 1
	s_mul_i32 s10, s49, s52
	s_mul_hi_u32 s11, s49, s53
	s_add_i32 s11, s11, s10
	s_mul_i32 s10, s49, s53
	s_add_u32 s26, s10, s2
	s_addc_u32 s27, s11, s31
	s_cmp_ge_u32 s26, 0x580
	s_cselect_b32 s99, 0x40000, 0
	s_cselect_b32 s98, 0x80, 0
	s_sub_u32 s26, s26, s98
	v_cmp_gt_i64_e32 vcc, s[26:27], v[144:145]
	v_cmp_lt_i64_e64 s[10:11], s[26:27], v[142:143]
	s_cbranch_vccnz .LBB0_519
	s_ashr_i32 s22, s26, 31
	s_lshr_b32 s22, s22, 29
	s_add_i32 s22, s26, s22
	s_ashr_i32 s23, s22, 3
	s_and_b32 s22, s22, -8
	s_sub_i32 s22, s26, s22
	s_cmp_lt_i32 s22, 0
	s_cselect_b32 s24, s33, 0xb0
	s_mul_i32 s22, s24, s22
	s_add_i32 s22, s22, s23
	s_mul_hi_i32 s23, s22, 0x2e8ba2e9
	s_lshr_b32 s24, s23, 31
	s_ashr_i32 s23, s23, 5
	s_add_i32 s23, s23, s24
	s_lshl_b32 s24, s23, 3
	s_sub_i32 s25, 64, s24
	s_min_i32 s25, s25, 8
	s_abs_i32 s26, s25
	v_cvt_f32_u32_e32 v0, s26
	s_sub_i32 s34, 0, s26
	s_mulk_i32 s23, 0xb0
	s_sub_i32 s23, s22, s23
	v_rcp_iflag_f32_e32 v0, v0
	s_abs_i32 s22, s23
	s_xor_b32 s27, s23, s25
	s_ashr_i32 s27, s27, 31
	v_mul_f32_e32 v0, 0x4f7ffffe, v0
	v_cvt_u32_f32_e32 v0, v0
	s_nop 0
	v_readfirstlane_b32 s35, v0
	s_mul_i32 s34, s34, s35
	s_mul_hi_u32 s34, s35, s34
	s_add_i32 s35, s35, s34
	s_mul_hi_u32 s34, s22, s35
	s_mul_i32 s35, s34, s26
	s_sub_i32 s22, s22, s35
	s_add_i32 s44, s34, 1
	s_sub_i32 s35, s22, s26
	s_cmp_ge_u32 s22, s26
	s_cselect_b32 s34, s44, s34
	s_cselect_b32 s22, s35, s22
	s_add_i32 s35, s34, 1
	s_cmp_ge_u32 s22, s26
	s_cselect_b32 s22, s35, s34
	s_xor_b32 s22, s22, s27
	s_sub_i32 s22, s22, s27
	s_mul_i32 s25, s22, s25
	s_sub_i32 s23, s23, s25
	s_add_i32 s24, s23, s24
.LBB0_519:
	s_ashr_i32 s25, s24, 31
	s_lshl_b64 s[26:27], s[24:25], 19
	s_add_u32 s26, s1, s26
	s_addc_u32 s27, s3, s27
	s_add_u32 s26, s26, s99
	s_addc_u32 s27, s27, 0
	s_and_b64 s[34:35], s[10:11], exec
	s_cselect_b32 s25, s27, s41
	s_cselect_b32 s58, s26, s40
	s_ashr_i32 s23, s22, 31
	s_lshl_b64 s[34:35], s[22:23], 19
	s_add_u32 s34, s4, s34
	s_addc_u32 s35, s5, s35
	s_and_b64 s[44:45], s[10:11], exec
	s_cselect_b32 s23, s35, s39
	s_cselect_b32 s59, s34, s38
	s_add_u32 s60, s38, 0x100
	s_addc_u32 s61, s39, 0
	s_add_u32 s38, s40, 0x40080
	v_mov_b32_e32 v0, 0
	s_addc_u32 s39, s41, 0
	s_mov_b32 s62, -2
	v_mov_b32_e32 v1, v0
	v_mov_b32_e32 v2, v0
	v_mov_b32_e32 v3, v0
	v_mov_b32_e32 v4, v0
	v_mov_b32_e32 v5, v0
	v_mov_b32_e32 v6, v0
	v_mov_b32_e32 v7, v0
	v_mov_b32_e32 v16, v0
	v_mov_b32_e32 v17, v0
	v_mov_b32_e32 v18, v0
	v_mov_b32_e32 v19, v0
	v_mov_b32_e32 v20, v0
	v_mov_b32_e32 v21, v0
	v_mov_b32_e32 v22, v0
	v_mov_b32_e32 v23, v0
	v_mov_b32_e32 v32, v0
	v_mov_b32_e32 v33, v0
	v_mov_b32_e32 v34, v0
	v_mov_b32_e32 v35, v0
	v_mov_b32_e32 v36, v0
	v_mov_b32_e32 v37, v0
	v_mov_b32_e32 v38, v0
	v_mov_b32_e32 v39, v0
	v_mov_b32_e32 v48, v0
	v_mov_b32_e32 v49, v0
	v_mov_b32_e32 v50, v0
	v_mov_b32_e32 v51, v0
	v_mov_b32_e32 v52, v0
	v_mov_b32_e32 v53, v0
	v_mov_b32_e32 v54, v0
	v_mov_b32_e32 v55, v0
	v_mov_b32_e32 v8, v0
	v_mov_b32_e32 v9, v0
	v_mov_b32_e32 v10, v0
	v_mov_b32_e32 v11, v0
	v_mov_b32_e32 v12, v0
	v_mov_b32_e32 v13, v0
	v_mov_b32_e32 v14, v0
	v_mov_b32_e32 v15, v0
	v_mov_b32_e32 v24, v0
	v_mov_b32_e32 v25, v0
	v_mov_b32_e32 v26, v0
	v_mov_b32_e32 v27, v0
	v_mov_b32_e32 v28, v0
	v_mov_b32_e32 v29, v0
	v_mov_b32_e32 v30, v0
	v_mov_b32_e32 v31, v0
	v_mov_b32_e32 v40, v0
	v_mov_b32_e32 v41, v0
	v_mov_b32_e32 v42, v0
	v_mov_b32_e32 v43, v0
	v_mov_b32_e32 v44, v0
	v_mov_b32_e32 v45, v0
	v_mov_b32_e32 v46, v0
	v_mov_b32_e32 v47, v0
	v_mov_b32_e32 v56, v0
	v_mov_b32_e32 v57, v0
	v_mov_b32_e32 v58, v0
	v_mov_b32_e32 v59, v0
	v_mov_b32_e32 v60, v0
	v_mov_b32_e32 v61, v0
	v_mov_b32_e32 v62, v0
	v_mov_b32_e32 v63, v0
	v_mov_b32_e32 v64, v0
	v_mov_b32_e32 v65, v0
	v_mov_b32_e32 v66, v0
	v_mov_b32_e32 v67, v0
	v_mov_b32_e32 v68, v0
	v_mov_b32_e32 v69, v0
	v_mov_b32_e32 v70, v0
	v_mov_b32_e32 v71, v0
	v_mov_b32_e32 v80, v0
	v_mov_b32_e32 v81, v0
	v_mov_b32_e32 v82, v0
	v_mov_b32_e32 v83, v0
	v_mov_b32_e32 v84, v0
	v_mov_b32_e32 v85, v0
	v_mov_b32_e32 v86, v0
	v_mov_b32_e32 v87, v0
	v_mov_b32_e32 v96, v0
	v_mov_b32_e32 v97, v0
	v_mov_b32_e32 v98, v0
	v_mov_b32_e32 v99, v0
	v_mov_b32_e32 v100, v0
	v_mov_b32_e32 v101, v0
	v_mov_b32_e32 v102, v0
	v_mov_b32_e32 v103, v0
	v_mov_b32_e32 v112, v0
	v_mov_b32_e32 v113, v0
	v_mov_b32_e32 v114, v0
	v_mov_b32_e32 v115, v0
	v_mov_b32_e32 v116, v0
	v_mov_b32_e32 v117, v0
	v_mov_b32_e32 v118, v0
	v_mov_b32_e32 v119, v0
	v_mov_b32_e32 v72, v0
	v_mov_b32_e32 v73, v0
	v_mov_b32_e32 v74, v0
	v_mov_b32_e32 v75, v0
	v_mov_b32_e32 v76, v0
	v_mov_b32_e32 v77, v0
	v_mov_b32_e32 v78, v0
	v_mov_b32_e32 v79, v0
	v_mov_b32_e32 v88, v0
	v_mov_b32_e32 v89, v0
	v_mov_b32_e32 v90, v0
	v_mov_b32_e32 v91, v0
	v_mov_b32_e32 v92, v0
	v_mov_b32_e32 v93, v0
	v_mov_b32_e32 v94, v0
	v_mov_b32_e32 v95, v0
	v_mov_b32_e32 v104, v0
	v_mov_b32_e32 v105, v0
	v_mov_b32_e32 v106, v0
	v_mov_b32_e32 v107, v0
	v_mov_b32_e32 v108, v0
	v_mov_b32_e32 v109, v0
	v_mov_b32_e32 v110, v0
	v_mov_b32_e32 v111, v0
	v_mov_b32_e32 v120, v0
	v_mov_b32_e32 v121, v0
	v_mov_b32_e32 v122, v0
	v_mov_b32_e32 v123, v0
	v_mov_b32_e32 v124, v0
	v_mov_b32_e32 v125, v0
	v_mov_b32_e32 v126, v0
	v_mov_b32_e32 v127, v0
	v_readlane_b32 s98, v252, 5
	s_nop 1
	s_lshl_b32 s98, s98, 5
	s_add_i32 m0, s98, 0x20080
	s_lshl_b32 s98, s36, 14
	s_add_u32 s98, s100, s98
	s_addc_u32 s99, s101, 0
	global_load_lds_dwordx4 v238, s[98:99]
	global_load_lds_dwordx4 v238, s[98:99] offset:1024
	s_cmp_eq_u32 s49, 6
	s_cbranch_scc1 .Lhh0_520

; #define PG8_STAGE(bufoff, gbase, voff) do { _Pragma("unroll") for (int _i = 0; _i < 2; ++_i) \
;         __builtin_amdgcn_global_load_lds((const unsigned*)((const char*)(gbase) + (voff)[_i]), (PG8_LAS unsigned*)(lds + (bufoff) + ldsw + _i * 8192), 16, 0, 0); } while (0)
; #define PG8_LDA(dst, b, h) do { _Pragma("unroll") for (int m = 0; m < 4; ++m) _Pragma("unroll") for (int k = 0; k < 2; ++k) dst[m][k] = *(const PG8_LAS bf16x8*)(lds + PG8_SA(b, h) + aoff + m * 2048 + k * 1024); } while (0)
; #define PG8_WAIT_V(n) asm volatile("s_waitcnt vmcnt(" #n ")" ::: "memory")
; #define PG8_WAIT_L(n) asm volatile("s_waitcnt lgkmcnt(" #n ")" ::: "memory")
; #define PG8_BAR __builtin_amdgcn_s_barrier()
; template <class Epi, class Sched, bool ALIGN_EPI = false, bool SP2 = false>
; __device__ __forceinline__ void gemm_phase(PG8_LAS unsigned char* lds, const Gemm g, const Sched& S, const Epi& E, int tid_in) {
;     ...
;         for (int t = 0; t < nt; t += 2) {
;             const bool last = (t == nt - 2);
;             const char* a1 = cA + (size_t)(t + 1) * kstep;
;             const char* a2 = last ? nA : cA + (size_t)(t + 2) * kstep; const char* b2 = last ? nB : cB + (size_t)(t + 2) * kstep;
;             const char* a3 = a2 + kstep; const char* b3 = b2 + kstep;
;             if (last && has_next) S.a_ready(nxt);
;             if constexpr (SP2) {
;             PG8_LDB(B0, 0, 0); PG8_LDB(B1, 0, 1); PG8_SCHED; PG8_LDA(At, 0, 0); PG8_STAGE(PG8_SA(1, 1), a1 + hstep, voffA);
;             PG8_WAIT_V(8); PG8_WAIT_L(0); PG8_BAR; PG8_MMA(0, 0, At, B0); PG8_MMA(0, 1, At, B1); PG8_BAR; PG8_SCHED;
;             PG8_LDA(At, 0, 1); PG8_STAGE(PG8_SB(0, 0), b2, voffB); PG8_STAGE(PG8_SB(0, 1), b2 + hstep, voffB); PG8_STAGE(PG8_SA(0, 0), a2, voffA);
;             PG8_WAIT_V(8); PG8_WAIT_L(0); PG8_BAR; PG8_MMA(1, 0, At, B0); PG8_MMA(1, 1, At, B1); PG8_BAR; PG8_SCHED;
;             PG8_LDB(B0, 1, 0); PG8_LDB(B1, 1, 1); PG8_SCHED; PG8_LDA(At, 1, 0); PG8_STAGE(PG8_SA(0, 1), a2 + hstep, voffA);
;             PG8_WAIT_V(8); PG8_WAIT_L(0); PG8_BAR; PG8_MMA(0, 0, At, B0); PG8_MMA(0, 1, At, B1); PG8_BAR; PG8_SCHED;
;             PG8_LDA(At, 1, 1); PG8_STAGE(PG8_SB(1, 0), b3, voffB); PG8_STAGE(PG8_SB(1, 1), b3 + hstep, voffB); PG8_STAGE(PG8_SA(1, 0), a3, voffA);
;             PG8_WAIT_V(8); PG8_WAIT_L(0); PG8_BAR; PG8_MMA(1, 0, At, B0); PG8_MMA(1, 1, At, B1); PG8_BAR; PG8_SCHED;
.Lhh0_520:
	ds_read_b128 v[146:149], v165
	ds_read_b128 v[176:179], v165 offset:1024
	ds_read_b128 v[180:183], v165 offset:2048
	ds_read_b128 v[184:187], v165 offset:3072
	ds_read_b128 v[188:191], v169
	ds_read_b128 v[192:195], v169 offset:1024
	ds_read_b128 v[196:199], v169 offset:2048
	ds_read_b128 v[202:205], v169 offset:3072
	s_add_u32 s40, s38, 0xfffc0080
	s_addc_u32 s41, s39, -1
	s_cmp_eq_u32 s62, 12
	s_cselect_b32 s45, s25, s41
	s_cselect_b32 s44, s58, s40
	s_cselect_b32 s41, s23, s61
	s_cselect_b32 s40, s59, s60
	v_lshl_add_u64 v[150:151], s[38:39], 0, v[140:141]
	s_add_i32 m0, s37, 0xc000
	ds_read_b128 v[206:209], v173
	ds_read_b128 v[210:213], v173 offset:1024
	ds_read_b128 v[214:217], v173 offset:2048
	ds_read_b128 v[218:221], v173 offset:3072
	ds_read_b128 v[222:225], v173 offset:4096
	ds_read_b128 v[226:229], v173 offset:5120
	ds_read_b128 v[230:233], v173 offset:6144
	ds_read_b128 v[234:237], v173 offset:7168
	global_load_lds_dwordx4 v[150:151], off
	v_lshl_add_u64 v[150:151], s[38:39], 0, v[138:139]
	s_add_i32 m0, s37, 0xe000
	s_nop 0
	global_load_lds_dwordx4 v[150:151], off
	s_waitcnt vmcnt(8)
	s_waitcnt lgkmcnt(0)
	s_barrier
	s_setprio 1
	s_waitcnt lgkmcnt(0)
	v_mfma_f32_16x16x32_bf16 v[124:127], v[146:149], v[206:209], v[124:127]
	v_mfma_f32_16x16x32_bf16 v[120:123], v[180:183], v[206:209], v[120:123]
	v_mfma_f32_16x16x32_bf16 v[108:111], v[146:149], v[214:217], v[108:111]
	v_mfma_f32_16x16x32_bf16 v[104:107], v[180:183], v[214:217], v[104:107]
	v_mfma_f32_16x16x32_bf16 v[92:95], v[146:149], v[222:225], v[92:95]
	v_mfma_f32_16x16x32_bf16 v[88:91], v[180:183], v[222:225], v[88:91]
	v_mfma_f32_16x16x32_bf16 v[76:79], v[146:149], v[230:233], v[76:79]
	v_mfma_f32_16x16x32_bf16 v[72:75], v[180:183], v[230:233], v[72:75]
	v_mfma_f32_16x16x32_bf16 v[124:127], v[176:179], v[210:213], v[124:127]
	v_mfma_f32_16x16x32_bf16 v[120:123], v[184:187], v[210:213], v[120:123]
	v_mfma_f32_16x16x32_bf16 v[108:111], v[176:179], v[218:221], v[108:111]
	v_mfma_f32_16x16x32_bf16 v[104:107], v[184:187], v[218:221], v[104:107]
	v_mfma_f32_16x16x32_bf16 v[92:95], v[176:179], v[226:229], v[92:95]
	v_mfma_f32_16x16x32_bf16 v[88:91], v[184:187], v[226:229], v[88:91]
	v_mfma_f32_16x16x32_bf16 v[76:79], v[176:179], v[234:237], v[76:79]
	v_mfma_f32_16x16x32_bf16 v[72:75], v[184:187], v[234:237], v[72:75]
	s_setprio 0
	s_setprio 1
	v_mfma_f32_16x16x32_bf16 v[116:119], v[188:191], v[206:209], v[116:119]
	v_mfma_f32_16x16x32_bf16 v[112:115], v[196:199], v[206:209], v[112:115]
	v_mfma_f32_16x16x32_bf16 v[100:103], v[188:191], v[214:217], v[100:103]
	v_mfma_f32_16x16x32_bf16 v[96:99], v[196:199], v[214:217], v[96:99]
	v_mfma_f32_16x16x32_bf16 v[84:87], v[188:191], v[222:225], v[84:87]
	v_mfma_f32_16x16x32_bf16 v[80:83], v[196:199], v[222:225], v[80:83]
	v_mfma_f32_16x16x32_bf16 v[68:71], v[188:191], v[230:233], v[68:71]
	v_mfma_f32_16x16x32_bf16 v[64:67], v[196:199], v[230:233], v[64:67]
	v_mfma_f32_16x16x32_bf16 v[116:119], v[192:195], v[210:213], v[116:119]
	v_mfma_f32_16x16x32_bf16 v[112:115], v[202:205], v[210:213], v[112:115]
	v_mfma_f32_16x16x32_bf16 v[100:103], v[192:195], v[218:221], v[100:103]
	v_mfma_f32_16x16x32_bf16 v[96:99], v[202:205], v[218:221], v[96:99]
	v_mfma_f32_16x16x32_bf16 v[84:87], v[192:195], v[226:229], v[84:87]
	v_mfma_f32_16x16x32_bf16 v[80:83], v[202:205], v[226:229], v[80:83]
	v_mfma_f32_16x16x32_bf16 v[68:71], v[192:195], v[234:237], v[68:71]
	v_mfma_f32_16x16x32_bf16 v[64:67], v[202:205], v[234:237], v[64:67]
	s_setprio 0
	s_barrier
	s_add_i32 s63, s54, s30
	v_lshl_add_u64 v[150:151], s[40:41], 0, v[132:133]
	s_mov_b32 m0, s63
	s_nop 0
	global_load_lds_dwordx4 v[150:151], off
	s_add_i32 m0, s63, 0x2000
	s_add_u32 s64, s40, 0x40000
	v_lshl_add_u64 v[154:155], s[40:41], 0, v[128:129]
	s_addc_u32 s65, s41, 0
	s_add_i32 s63, s55, s30
	global_load_lds_dwordx4 v[154:155], off
	v_lshl_add_u64 v[158:159], s[64:65], 0, v[132:133]
	s_mov_b32 m0, s63
	v_lshl_add_u64 v[162:163], s[44:45], 0, v[130:131]
	global_load_lds_dwordx4 v[158:159], off
	v_lshl_add_u64 v[158:159], s[64:65], 0, v[128:129]
	s_add_i32 m0, s63, 0x2000
	s_nop 0
	global_load_lds_dwordx4 v[158:159], off
	v_lshl_add_u64 v[158:159], s[44:45], 0, v[134:135]
	s_mov_b32 m0, s37
	s_nop 0
	global_load_lds_dwordx4 v[158:159], off
	s_mov_b32 m0, s46
	s_nop 0
	global_load_lds_dwordx4 v[162:163], off
	s_waitcnt vmcnt(8)
	s_waitcnt lgkmcnt(0)
	s_barrier
	s_setprio 1
	s_waitcnt lgkmcnt(0)
	s_setprio 0
	s_setprio 1
	s_setprio 0
	s_barrier
	s_add_i32 s63, 0, 0x18000
	v_add_u32_e32 v152, s63, v157
	s_add_i32 s64, 0, 0x1c000
	ds_read_b128 v[146:149], v152
	ds_read_b128 v[176:179], v152 offset:1024
	ds_read_b128 v[180:183], v152 offset:2048
	ds_read_b128 v[184:187], v152 offset:3072
	v_add_u32_e32 v152, s64, v157
	ds_read_b128 v[188:191], v152
	ds_read_b128 v[192:195], v152 offset:1024
	ds_read_b128 v[196:199], v152 offset:2048
	ds_read_b128 v[202:205], v152 offset:3072
	s_add_u32 s44, s44, 0x40000
	s_addc_u32 s45, s45, 0
	s_mov_b32 m0, s47
	v_lshl_add_u64 v[166:167], s[44:45], 0, v[134:135]
	ds_read_b128 v[206:209], v173 offset:32768
	ds_read_b128 v[210:213], v173 offset:33792
	ds_read_b128 v[214:217], v173 offset:34816
	ds_read_b128 v[218:221], v173 offset:35840
	ds_read_b128 v[222:225], v173 offset:36864
	ds_read_b128 v[226:229], v173 offset:37888
	ds_read_b128 v[230:233], v173 offset:38912
	ds_read_b128 v[234:237], v173 offset:39936
	global_load_lds_dwordx4 v[166:167], off
	v_lshl_add_u64 v[166:167], s[44:45], 0, v[130:131]
	s_mov_b32 m0, s48
	s_nop 0
	global_load_lds_dwordx4 v[166:167], off
	s_waitcnt vmcnt(8)
	s_waitcnt lgkmcnt(0)
	s_barrier
; __device__ __forceinline__ float row_part(const float* ss, int row, int fq) { const f32x4 a = ((const f32x4*)(ss + (size_t)row * 16))[fq]; return (a[0] + a[1]) + (a[2] + a[3]); }
; __device__ __forceinline__ float row_finish(float t) { t += shx(t, 16); t += shx(t, 32); return __builtin_amdgcn_rsqf(t * (1.0f / 1024.0f) + RMS_EPS); }
; #define PG8_LDA(dst, b, h) do { _Pragma("unroll") for (int m = 0; m < 4; ++m) _Pragma("unroll") for (int k = 0; k < 2; ++k) dst[m][k] = *(const PG8_LAS bf16x8*)(lds + PG8_SA(b, h) + aoff + m * 2048 + k * 1024); } while (0)
;     __device__ __forceinline__ void operator()(const f32x4 (&acc)[2][2][4][2], const Unit& u, int wr, int wc, int fr, int fq) const {
;         const int col0 = u.pn * 128 + 32 * wc + 8 * fq;
;         float rs[2][4];
; #pragma unroll
;         for (int ai = 0; ai < 2; ++ai)
; #pragma unroll
;             for (int m = 0; m < 4; ++m) rs[ai][m] = row_part(ss, u.pm * BM + ai * HALF + wr * 64 + m * 16 + fr, fq);
; #pragma unroll
;         for (int ai = 0; ai < 2; ++ai)
; #pragma unroll
;             for (int m = 0; m < 4; ++m) rs[ai][m] = row_finish(rs[ai][m]);
; template <class Epi, class Sched, bool ALIGN_EPI = false, bool SP2 = false>
; __device__ __forceinline__ void gemm_phase(PG8_LAS unsigned char* lds, const Gemm g, const Sched& S, const Epi& E, int tid_in) {
;     ...
;             PG8_LDB(B0, 0, 0); PG8_LDB(B1, 0, 1); PG8_SCHED; PG8_LDA(At, 0, 0); PG8_STAGE(PG8_SA(1, 1), a1 + hstep, voffA);
;             PG8_WAIT_V(8); PG8_WAIT_L(0); PG8_BAR; PG8_MMA(0, 0, At, B0); PG8_MMA(0, 1, At, B1); PG8_BAR; PG8_SCHED;
;             PG8_LDA(At, 0, 1); PG8_STAGE(PG8_SB(0, 0), b2, voffB); PG8_STAGE(PG8_SB(0, 1), b2 + hstep, voffB); PG8_STAGE(PG8_SA(0, 0), a2, voffA);
;             PG8_WAIT_V(8); PG8_WAIT_L(0); PG8_BAR; PG8_MMA(1, 0, At, B0); PG8_MMA(1, 1, At, B1); PG8_BAR; PG8_SCHED;
;             PG8_LDB(B0, 1, 0); PG8_LDB(B1, 1, 1); PG8_SCHED; PG8_LDA(At, 1, 0); PG8_STAGE(PG8_SA(0, 1), a2 + hstep, voffA);
;             PG8_WAIT_V(8); PG8_WAIT_L(0); PG8_BAR; PG8_MMA(0, 0, At, B0); PG8_MMA(0, 1, At, B1); PG8_BAR; PG8_SCHED;
;             PG8_LDA(At, 1, 1); PG8_STAGE(PG8_SB(1, 0), b3, voffB); PG8_STAGE(PG8_SB(1, 1), b3 + hstep, voffB); PG8_STAGE(PG8_SA(1, 0), a3, voffA);
;             PG8_WAIT_V(8); PG8_WAIT_L(0); PG8_BAR; PG8_MMA(1, 0, At, B0); PG8_MMA(1, 1, At, B1); PG8_BAR; PG8_SCHED;
	s_setprio 1
	s_waitcnt lgkmcnt(0)
	v_mfma_f32_16x16x32_bf16 v[124:127], v[146:149], v[206:209], v[124:127]
	v_mfma_f32_16x16x32_bf16 v[120:123], v[180:183], v[206:209], v[120:123]
	v_mfma_f32_16x16x32_bf16 v[108:111], v[146:149], v[214:217], v[108:111]
	v_mfma_f32_16x16x32_bf16 v[104:107], v[180:183], v[214:217], v[104:107]
	v_mfma_f32_16x16x32_bf16 v[92:95], v[146:149], v[222:225], v[92:95]
	v_mfma_f32_16x16x32_bf16 v[88:91], v[180:183], v[222:225], v[88:91]
	v_mfma_f32_16x16x32_bf16 v[76:79], v[146:149], v[230:233], v[76:79]
	v_mfma_f32_16x16x32_bf16 v[72:75], v[180:183], v[230:233], v[72:75]
	v_mfma_f32_16x16x32_bf16 v[124:127], v[176:179], v[210:213], v[124:127]
	v_mfma_f32_16x16x32_bf16 v[120:123], v[184:187], v[210:213], v[120:123]
	v_mfma_f32_16x16x32_bf16 v[108:111], v[176:179], v[218:221], v[108:111]
	v_mfma_f32_16x16x32_bf16 v[104:107], v[184:187], v[218:221], v[104:107]
	v_mfma_f32_16x16x32_bf16 v[92:95], v[176:179], v[226:229], v[92:95]
	v_mfma_f32_16x16x32_bf16 v[88:91], v[184:187], v[226:229], v[88:91]
	v_mfma_f32_16x16x32_bf16 v[76:79], v[176:179], v[234:237], v[76:79]
	v_mfma_f32_16x16x32_bf16 v[72:75], v[184:187], v[234:237], v[72:75]
	s_setprio 0
	s_setprio 1
	v_mfma_f32_16x16x32_bf16 v[116:119], v[188:191], v[206:209], v[116:119]
	v_mfma_f32_16x16x32_bf16 v[112:115], v[196:199], v[206:209], v[112:115]
	v_mfma_f32_16x16x32_bf16 v[100:103], v[188:191], v[214:217], v[100:103]
	v_mfma_f32_16x16x32_bf16 v[96:99], v[196:199], v[214:217], v[96:99]
	v_mfma_f32_16x16x32_bf16 v[84:87], v[188:191], v[222:225], v[84:87]
	v_mfma_f32_16x16x32_bf16 v[80:83], v[196:199], v[222:225], v[80:83]
	v_mfma_f32_16x16x32_bf16 v[68:71], v[188:191], v[230:233], v[68:71]
	v_mfma_f32_16x16x32_bf16 v[64:67], v[196:199], v[230:233], v[64:67]
	v_mfma_f32_16x16x32_bf16 v[116:119], v[192:195], v[210:213], v[116:119]
	v_mfma_f32_16x16x32_bf16 v[112:115], v[202:205], v[210:213], v[112:115]
	v_mfma_f32_16x16x32_bf16 v[100:103], v[192:195], v[218:221], v[100:103]
	v_mfma_f32_16x16x32_bf16 v[96:99], v[202:205], v[218:221], v[96:99]
	v_mfma_f32_16x16x32_bf16 v[84:87], v[192:195], v[226:229], v[84:87]
	v_mfma_f32_16x16x32_bf16 v[80:83], v[202:205], v[226:229], v[80:83]
	v_mfma_f32_16x16x32_bf16 v[68:71], v[192:195], v[234:237], v[68:71]
	v_mfma_f32_16x16x32_bf16 v[64:67], v[202:205], v[234:237], v[64:67]
	s_setprio 0
	s_barrier
	s_add_i32 s44, s63, s30
	v_lshl_add_u64 v[150:151], v[150:151], 0, s[16:17]
	s_mov_b32 m0, s44
	s_nop 0
	global_load_lds_dwordx4 v[150:151], off
	s_add_i32 m0, s44, 0x2000
	s_add_u32 s40, s40, 0x40080
	v_lshl_add_u64 v[150:151], v[154:155], 0, s[16:17]
	s_addc_u32 s41, s41, 0
	s_add_i32 s44, s64, s30
	global_load_lds_dwordx4 v[150:151], off
	v_lshl_add_u64 v[150:151], s[40:41], 0, v[132:133]
	s_mov_b32 m0, s44
	s_nop 0
	global_load_lds_dwordx4 v[150:151], off
	v_lshl_add_u64 v[150:151], s[40:41], 0, v[128:129]
	s_add_i32 m0, s44, 0x2000
	s_nop 0
	global_load_lds_dwordx4 v[150:151], off
	v_lshl_add_u64 v[150:151], v[158:159], 0, s[16:17]
	s_mov_b32 m0, s50
	s_nop 0
	global_load_lds_dwordx4 v[150:151], off
	v_lshl_add_u64 v[150:151], v[162:163], 0, s[16:17]
	s_mov_b32 m0, s51
	s_nop 0
	global_load_lds_dwordx4 v[150:151], off
	s_waitcnt vmcnt(8)
	s_waitcnt lgkmcnt(0)
	s_barrier
	s_setprio 1
	s_waitcnt lgkmcnt(0)
	s_setprio 0
	s_setprio 1
	s_setprio 0
	s_barrier
	s_add_i32 s62, s62, 2
	s_add_u32 s60, s60, 0x100
	s_addc_u32 s61, s61, 0
	s_add_u32 s38, s38, 0x100
	s_addc_u32 s39, s39, 0
	s_cmp_gt_u32 s62, 13
	s_cbranch_scc0 .Lhh0_520
	s_and_b64 vcc, exec, s[18:19]
	s_cbranch_vccz .Lhh0_523
	s_barrier
.Lhh0_523:
	v_lshl_add_u32 v170, s36, 8, v153
	s_cmp_ge_u32 s2, 0x80
	s_cselect_b32 s98, 0x80, 0
	v_add_u32_e32 v170, s98, v170
	s_lshl_b32 s99, s98, 6
	v_add_u32_e32 v241, s99, v239
	v_ashrrev_i32_e32 v171, 31, v170
	v_or_b32_e32 v166, 16, v170
	v_lshlrev_b64 v[146:147], 6, v[170:171]
	v_ashrrev_i32_e32 v167, 31, v166
	v_lshl_add_u64 v[146:147], v[136:137], 0, v[146:147]
	v_lshlrev_b64 v[148:149], 6, v[166:167]
	v_lshl_add_u64 v[148:149], v[136:137], 0, v[148:149]
	ds_read_b128 v[176:179], v241
	ds_read_b128 v[180:183], v241 offset:1024
	v_or_b32_e32 v162, 32, v170
	v_ashrrev_i32_e32 v163, 31, v162
	v_or_b32_e32 v158, 48, v170
	v_lshlrev_b64 v[146:147], 6, v[162:163]
	v_ashrrev_i32_e32 v159, 31, v158
	v_lshl_add_u64 v[146:147], v[136:137], 0, v[146:147]
	v_lshlrev_b64 v[148:149], 6, v[158:159]
	v_lshl_add_u64 v[148:149], v[136:137], 0, v[148:149]
	ds_read_b128 v[184:187], v241 offset:2048
	ds_read_b128 v[188:191], v241 offset:3072
	v_add_u32_e32 v154, 0x80, v170
	v_ashrrev_i32_e32 v155, 31, v154
	v_add_u32_e32 v150, 0x90, v170
	v_lshlrev_b64 v[146:147], 6, v[154:155]
	v_ashrrev_i32_e32 v151, 31, v150
	v_lshl_add_u64 v[146:147], v[136:137], 0, v[146:147]
	v_lshlrev_b64 v[148:149], 6, v[150:151]
	v_lshl_add_u64 v[148:149], v[136:137], 0, v[148:149]
	ds_read_b128 v[192:195], v241 offset:8192
	ds_read_b128 v[196:199], v241 offset:9216
	v_add_u32_e32 v148, 0xa0, v170
	v_ashrrev_i32_e32 v149, 31, v148
	v_lshlrev_b64 v[146:147], 6, v[148:149]
	v_lshl_add_u64 v[146:147], v[136:137], 0, v[146:147]
	ds_read_b128 v[202:205], v241 offset:10240
	v_add_u32_e32 v146, 0xb0, v170
	v_ashrrev_i32_e32 v147, 31, v146
	v_lshlrev_b64 v[206:207], 6, v[146:147]
	v_lshl_add_u64 v[206:207], v[136:137], 0, v[206:207]
	ds_read_b128 v[206:209], v241 offset:11264
	v_mov_b32_e32 v147, v201
	v_mov_b32_e32 v149, v201
	v_lshlrev_b32_e32 v147, 2, v147
	v_mov_b32_e32 v151, v201
	v_xor_b32_e32 v147, 64, v147
	s_andn2_b64 vcc, exec, s[10:11]
	v_lshlrev_b32_e32 v151, 2, v151
	v_xor_b32_e32 v151, 64, v151
	v_lshlrev_b32_e32 v149, 2, v149
	v_xor_b32_e32 v149, 0x80, v149
	s_mov_b64 s[10:11], -1
	s_waitcnt lgkmcnt(0)
; __device__ __forceinline__ float row_part(const float* ss, int row, int fq) { const f32x4 a = ((const f32x4*)(ss + (size_t)row * 16))[fq]; return (a[0] + a[1]) + (a[2] + a[3]); }
; __device__ __forceinline__ float row_finish(float t) { t += shx(t, 16); t += shx(t, 32); return __builtin_amdgcn_rsqf(t * (1.0f / 1024.0f) + RMS_EPS); }
;     __device__ __forceinline__ void operator()(const f32x4 (&acc)[2][2][4][2], const Unit& u, int wr, int wc, int fr, int fq) const {
;         const int col0 = u.pn * 128 + 32 * wc + 8 * fq;
;         float rs[2][4];
; #pragma unroll
;         for (int ai = 0; ai < 2; ++ai)
; #pragma unroll
;             for (int m = 0; m < 4; ++m) rs[ai][m] = row_part(ss, u.pm * BM + ai * HALF + wr * 64 + m * 16 + fr, fq);
; #pragma unroll
;         for (int ai = 0; ai < 2; ++ai)
; #pragma unroll
;             for (int m = 0; m < 4; ++m) rs[ai][m] = row_finish(rs[ai][m]);
	v_mov_b32_e32 v210, v177
	v_mov_b32_e32 v211, v178
	v_mov_b32_e32 v177, v179
	v_pk_add_f32 v[176:177], v[210:211], v[176:177]
	v_mov_b32_e32 v178, v181
	v_add_f32_e32 v152, v176, v177
	v_mov_b32_e32 v179, v182
	v_mov_b32_e32 v181, v183
	ds_bpermute_b32 v147, v147, v152
	v_pk_add_f32 v[176:177], v[178:179], v[180:181]
	v_mov_b32_e32 v182, v185
	v_add_f32_e32 v155, v176, v177
	ds_bpermute_b32 v151, v151, v155
	s_waitcnt lgkmcnt(1)
	v_add_f32_e32 v147, v152, v147
	v_mov_b32_e32 v152, v201
	ds_bpermute_b32 v149, v149, v147
	s_waitcnt lgkmcnt(1)
	v_add_f32_e32 v151, v155, v151
	v_lshlrev_b32_e32 v152, 2, v152
	v_xor_b32_e32 v152, 0x80, v152
	ds_bpermute_b32 v152, v152, v151
	s_waitcnt lgkmcnt(1)
	v_add_f32_e32 v147, v147, v149
	v_mov_b32_e32 v149, v201
	v_mov_b32_e32 v183, v186
	v_mov_b32_e32 v185, v187
	v_pk_add_f32 v[178:179], v[182:183], v[184:185]
	v_fmamk_f32 v147, v147, 0x3a800000, v175
	v_lshlrev_b32_e32 v149, 2, v149
	v_add_f32_e32 v156, v178, v179
	v_rsq_f32_e32 v176, v147
	s_waitcnt lgkmcnt(0)
	v_add_f32_e32 v147, v151, v152
	v_xor_b32_e32 v149, 64, v149
	v_mov_b32_e32 v151, v201
	v_mov_b32_e32 v152, v201
	v_mov_b32_e32 v186, v189
	v_mov_b32_e32 v187, v190
	v_mov_b32_e32 v189, v191
	ds_bpermute_b32 v149, v149, v156
	v_pk_add_f32 v[180:181], v[186:187], v[188:189]
	v_lshlrev_b32_e32 v152, 2, v152
	v_add_f32_e32 v159, v180, v181
	v_xor_b32_e32 v152, 64, v152
	ds_bpermute_b32 v152, v152, v159
	s_waitcnt lgkmcnt(1)
	v_add_f32_e32 v149, v156, v149
	v_lshlrev_b32_e32 v151, 2, v151
	v_mov_b32_e32 v156, v201
	v_xor_b32_e32 v151, 0x80, v151
	ds_bpermute_b32 v151, v151, v149
	v_lshlrev_b32_e32 v156, 2, v156
	s_waitcnt lgkmcnt(1)
	v_add_f32_e32 v152, v159, v152
	v_xor_b32_e32 v156, 0x80, v156
	ds_bpermute_b32 v156, v156, v152
	v_fmamk_f32 v147, v147, 0x3a800000, v175
	v_rsq_f32_e32 v174, v147
	s_waitcnt lgkmcnt(1)
	v_add_f32_e32 v147, v149, v151
	v_mov_b32_e32 v149, v201
	v_mov_b32_e32 v190, v193
	v_mov_b32_e32 v191, v194
	v_mov_b32_e32 v193, v195
	v_fmamk_f32 v147, v147, 0x3a800000, v175
	v_pk_add_f32 v[182:183], v[190:191], v[192:193]
	v_rsq_f32_e32 v172, v147
	s_waitcnt lgkmcnt(0)
	v_add_f32_e32 v147, v152, v156
	v_lshlrev_b32_e32 v149, 2, v149
	v_mov_b32_e32 v151, v201
	v_mov_b32_e32 v152, v201
	v_mov_b32_e32 v194, v197
	v_mov_b32_e32 v195, v198
	v_mov_b32_e32 v197, v199
	v_add_f32_e32 v160, v182, v183
	v_xor_b32_e32 v149, 64, v149
	v_pk_add_f32 v[184:185], v[194:195], v[196:197]
	ds_bpermute_b32 v149, v149, v160
	v_lshlrev_b32_e32 v152, 2, v152
	v_add_f32_e32 v163, v184, v185
	v_xor_b32_e32 v152, 64, v152
	ds_bpermute_b32 v152, v152, v163
	v_lshlrev_b32_e32 v151, 2, v151
	v_mov_b32_e32 v156, v201
	s_waitcnt lgkmcnt(1)
	v_add_f32_e32 v149, v160, v149
	v_xor_b32_e32 v151, 0x80, v151
	ds_bpermute_b32 v151, v151, v149
	v_lshlrev_b32_e32 v156, 2, v156
	s_waitcnt lgkmcnt(1)
	v_add_f32_e32 v152, v163, v152
	v_xor_b32_e32 v156, 0x80, v156
	ds_bpermute_b32 v156, v156, v152
	v_fmamk_f32 v147, v147, 0x3a800000, v175
	v_rsq_f32_e32 v168, v147
	s_waitcnt lgkmcnt(1)
	v_add_f32_e32 v147, v149, v151
	v_fmamk_f32 v147, v147, 0x3a800000, v175
	v_rsq_f32_e32 v164, v147
	s_waitcnt lgkmcnt(0)
	v_add_f32_e32 v147, v152, v156
	v_mov_b32_e32 v149, v201
	v_mov_b32_e32 v151, v201
	v_mov_b32_e32 v152, v201
	v_mov_b32_e32 v198, v203
	v_mov_b32_e32 v199, v204
	v_mov_b32_e32 v203, v205
	v_mov_b32_e32 v204, v207
	v_mov_b32_e32 v205, v208
	v_mov_b32_e32 v207, v209
	v_pk_add_f32 v[188:189], v[204:205], v[206:207]
	v_lshlrev_b32_e32 v152, 2, v152
	v_pk_add_f32 v[186:187], v[198:199], v[202:203]
	v_add_f32_e32 v155, v188, v189
	v_lshlrev_b32_e32 v149, 2, v149
	v_xor_b32_e32 v152, 64, v152
	v_add_f32_e32 v167, v186, v187
	v_xor_b32_e32 v149, 64, v149
	ds_bpermute_b32 v152, v152, v155
	ds_bpermute_b32 v149, v149, v167
	v_lshlrev_b32_e32 v151, 2, v151
	v_xor_b32_e32 v151, 0x80, v151
	v_fmamk_f32 v147, v147, 0x3a800000, v175
	s_waitcnt lgkmcnt(1)
	v_add_f32_e32 v152, v155, v152
	v_mov_b32_e32 v155, v201
	s_waitcnt lgkmcnt(0)
	v_add_f32_e32 v149, v167, v149
	ds_bpermute_b32 v151, v151, v149
	v_lshlrev_b32_e32 v155, 2, v155
	v_xor_b32_e32 v155, 0x80, v155
	ds_bpermute_b32 v155, v155, v152
	v_rsq_f32_e32 v160, v147
	s_waitcnt lgkmcnt(1)
	v_add_f32_e32 v147, v149, v151
	v_fmamk_f32 v147, v147, 0x3a800000, v175
	v_rsq_f32_e32 v156, v147
	s_waitcnt lgkmcnt(0)
; __device__ __forceinline__ f32x4 silu4(f32x4 v) { return (f32x4){silu_f(v[0]), silu_f(v[1]), silu_f(v[2]), silu_f(v[3])}; }
; __device__ __forceinline__ u32x4 pack8(f32x4 a, f32x4 b) { u32x4 w; w.x = cvt_pk_bf16(a[0], a[1]); w.y = cvt_pk_bf16(a[2], a[3]); w.z = cvt_pk_bf16(b[0], b[1]); w.w = cvt_pk_bf16(b[2], b[3]); return w; }
; __device__ __forceinline__ float silu_f(float v) { return v * __builtin_amdgcn_rcpf(1.0f + __builtin_amdgcn_exp2f(v * -1.4426950408889634f)); }
;     __device__ __forceinline__ void operator()(const f32x4 (&acc)[2][2][4][2], const Unit& u, int wr, int wc, int fr, int fq) const {
;     ...
;         for (int ai = 0; ai < 2; ++ai)
; #pragma unroll
;             for (int m = 0; m < 4; ++m) {
;                 const int row = u.pm * BM + ai * HALF + wr * 64 + m * 16 + fr;
;                 const float rstd = rs[ai][m];
;                 const f32x4 a0 = silu4(acc[ai][0][m][0] * rstd) * (acc[ai][1][m][0] * rstd);
;                 const f32x4 a1 = silu4(acc[ai][0][m][1] * rstd) * (acc[ai][1][m][1] * rstd);
;                 *(u32x4*)(ACT + (size_t)row * 2816 + col0) = pack8(a0, a1);
;             }
	v_add_f32_e32 v147, v152, v155
	v_fmamk_f32 v147, v147, 0x3a800000, v175
	v_pk_mul_f32 v[124:125], v[124:125], v[176:177] op_sel_hi:[1,0]
	v_rsq_f32_e32 v152, v147
	v_mul_f32_e32 v147, 0xbfb8aa3b, v124
	v_exp_f32_e32 v147, v147
	v_mul_f32_e32 v149, 0xbfb8aa3b, v125
	v_exp_f32_e32 v149, v149
	v_pk_mul_f32 v[126:127], v[126:127], v[176:177] op_sel_hi:[1,0]
	v_add_f32_e32 v147, 1.0, v147
	v_rcp_f32_e32 v178, v147
	v_add_f32_e32 v147, 1.0, v149
	v_mul_f32_e32 v149, 0xbfb8aa3b, v126
	v_exp_f32_e32 v149, v149
	v_mul_f32_e32 v151, 0xbfb8aa3b, v127
	v_exp_f32_e32 v151, v151
	v_rcp_f32_e32 v179, v147
	v_add_f32_e32 v147, 1.0, v149
	v_rcp_f32_e32 v180, v147
	v_add_f32_e32 v147, 1.0, v151
	v_pk_mul_f32 v[120:121], v[120:121], v[176:177] op_sel_hi:[1,0]
	v_rcp_f32_e32 v181, v147
	v_mul_f32_e32 v147, 0xbfb8aa3b, v120
	v_exp_f32_e32 v147, v147
	v_mul_f32_e32 v149, 0xbfb8aa3b, v121
	v_exp_f32_e32 v149, v149
	v_pk_mul_f32 v[122:123], v[122:123], v[176:177] op_sel_hi:[1,0]
	v_add_f32_e32 v147, 1.0, v147
	v_pk_mul_f32 v[124:125], v[124:125], v[178:179]
	v_rcp_f32_e32 v178, v147
	v_add_f32_e32 v147, 1.0, v149
	v_mul_f32_e32 v149, 0xbfb8aa3b, v122
	v_exp_f32_e32 v149, v149
	v_mul_f32_e32 v151, 0xbfb8aa3b, v123
	v_exp_f32_e32 v151, v151
	v_rcp_f32_e32 v179, v147
	v_add_f32_e32 v147, 1.0, v149
	v_pk_mul_f32 v[126:127], v[126:127], v[180:181]
	v_rcp_f32_e32 v180, v147
	v_add_f32_e32 v147, 1.0, v151
	v_rcp_f32_e32 v181, v147
	v_pk_mul_f32 v[116:117], v[116:117], v[176:177] op_sel_hi:[1,0]
	v_pk_mul_f32 v[118:119], v[118:119], v[176:177] op_sel_hi:[1,0]
	v_pk_mul_f32 v[120:121], v[120:121], v[178:179]
	v_pk_mul_f32 v[112:113], v[112:113], v[176:177] op_sel_hi:[1,0]
	v_lshl_or_b32 v182, s57, 7, v161
	v_pk_mul_f32 v[118:119], v[118:119], v[126:127]
	v_pk_mul_f32 v[116:117], v[116:117], v[124:125]
	v_pk_mul_f32 v[122:123], v[122:123], v[180:181]
	v_pk_mul_f32 v[114:115], v[114:115], v[176:177] op_sel_hi:[1,0]
	v_pk_mul_f32 v[112:113], v[112:113], v[120:121]
	v_ashrrev_i32_e32 v183, 31, v182
	v_pk_mul_f32 v[114:115], v[114:115], v[122:123]
	v_cvt_pk_bf16_f32 v116, v116, v117
	v_cvt_pk_bf16_f32 v117, v118, v119
	v_cvt_pk_bf16_f32 v118, v112, v113
	v_mov_b64_e32 v[112:113], s[14:15]
	v_cvt_pk_bf16_f32 v119, v114, v115
	v_mad_i64_i32 v[120:121], s[38:39], v170, s56, v[112:113]
	v_lshlrev_b64 v[114:115], 1, v[182:183]
	v_pk_mul_f32 v[108:109], v[108:109], v[174:175] op_sel_hi:[1,0]
	v_pk_mul_f32 v[110:111], v[110:111], v[174:175] op_sel_hi:[1,0]
	v_mul_f32_e32 v122, 0xbfb8aa3b, v108
	v_mul_f32_e32 v123, 0xbfb8aa3b, v109
	v_lshl_add_u64 v[120:121], v[120:121], 0, v[114:115]
	v_pk_mul_f32 v[104:105], v[104:105], v[174:175] op_sel_hi:[1,0]
	v_pk_mul_f32 v[106:107], v[106:107], v[174:175] op_sel_hi:[1,0]
	v_exp_f32_e32 v122, v122
	v_exp_f32_e32 v123, v123
	v_mul_f32_e32 v124, 0xbfb8aa3b, v110
	v_mul_f32_e32 v125, 0xbfb8aa3b, v111
	global_store_dwordx4 v[120:121], v[116:119], off
	v_exp_f32_e32 v124, v124
	v_exp_f32_e32 v125, v125
	v_mul_f32_e32 v116, 0xbfb8aa3b, v104
	v_mul_f32_e32 v117, 0xbfb8aa3b, v105
	v_mul_f32_e32 v118, 0xbfb8aa3b, v106
	v_mul_f32_e32 v119, 0xbfb8aa3b, v107
	v_exp_f32_e32 v116, v116
	v_exp_f32_e32 v117, v117
	v_exp_f32_e32 v118, v118
	v_exp_f32_e32 v119, v119
	v_add_f32_e32 v122, 1.0, v122
	v_add_f32_e32 v123, 1.0, v123
	v_rcp_f32_e32 v122, v122
	v_rcp_f32_e32 v123, v123
	v_add_f32_e32 v124, 1.0, v124
	v_add_f32_e32 v125, 1.0, v125
	v_add_f32_e32 v116, 1.0, v116
	v_add_f32_e32 v117, 1.0, v117
	v_add_f32_e32 v118, 1.0, v118
	v_add_f32_e32 v119, 1.0, v119
	v_rcp_f32_e32 v124, v124
	v_rcp_f32_e32 v125, v125
	v_rcp_f32_e32 v116, v116
	v_rcp_f32_e32 v117, v117
	v_rcp_f32_e32 v118, v118
	v_rcp_f32_e32 v119, v119
	v_pk_mul_f32 v[108:109], v[108:109], v[122:123]
	v_pk_mul_f32 v[100:101], v[100:101], v[174:175] op_sel_hi:[1,0]
	v_pk_mul_f32 v[110:111], v[110:111], v[124:125]
	v_pk_mul_f32 v[102:103], v[102:103], v[174:175] op_sel_hi:[1,0]
	v_pk_mul_f32 v[100:101], v[100:101], v[108:109]
	v_pk_mul_f32 v[104:105], v[104:105], v[116:117]
	v_pk_mul_f32 v[106:107], v[106:107], v[118:119]
	v_pk_mul_f32 v[96:97], v[96:97], v[174:175] op_sel_hi:[1,0]
	v_pk_mul_f32 v[98:99], v[98:99], v[174:175] op_sel_hi:[1,0]
	v_pk_mul_f32 v[102:103], v[102:103], v[110:111]
	v_pk_mul_f32 v[106:107], v[98:99], v[106:107]
	v_pk_mul_f32 v[98:99], v[96:97], v[104:105]
	v_cvt_pk_bf16_f32 v96, v100, v101
	v_mad_i64_i32 v[100:101], s[38:39], v166, s56, v[112:113]
	v_pk_mul_f32 v[92:93], v[92:93], v[172:173] op_sel_hi:[1,0]
	v_cvt_pk_bf16_f32 v97, v102, v103
	v_cvt_pk_bf16_f32 v98, v98, v99
	v_cvt_pk_bf16_f32 v99, v106, v107
	v_pk_mul_f32 v[94:95], v[94:95], v[172:173] op_sel_hi:[1,0]
	v_mul_f32_e32 v102, 0xbfb8aa3b, v92
	v_mul_f32_e32 v103, 0xbfb8aa3b, v93
	v_lshl_add_u64 v[100:101], v[100:101], 0, v[114:115]
	v_pk_mul_f32 v[88:89], v[88:89], v[172:173] op_sel_hi:[1,0]
	v_pk_mul_f32 v[90:91], v[90:91], v[172:173] op_sel_hi:[1,0]
	v_exp_f32_e32 v102, v102
	v_exp_f32_e32 v103, v103
	v_mul_f32_e32 v104, 0xbfb8aa3b, v94
	v_mul_f32_e32 v105, 0xbfb8aa3b, v95
	global_store_dwordx4 v[100:101], v[96:99], off
	v_exp_f32_e32 v104, v104
	v_exp_f32_e32 v105, v105
	v_mul_f32_e32 v96, 0xbfb8aa3b, v88
	v_mul_f32_e32 v97, 0xbfb8aa3b, v89
	v_mul_f32_e32 v98, 0xbfb8aa3b, v90
	v_mul_f32_e32 v99, 0xbfb8aa3b, v91
	v_exp_f32_e32 v96, v96
	v_exp_f32_e32 v97, v97
	v_exp_f32_e32 v98, v98
	v_exp_f32_e32 v99, v99
	v_add_f32_e32 v102, 1.0, v102
	v_add_f32_e32 v103, 1.0, v103
	v_rcp_f32_e32 v102, v102
	v_rcp_f32_e32 v103, v103
	v_add_f32_e32 v104, 1.0, v104
	v_add_f32_e32 v105, 1.0, v105
	v_add_f32_e32 v96, 1.0, v96
	v_add_f32_e32 v97, 1.0, v97
	v_add_f32_e32 v98, 1.0, v98
	v_add_f32_e32 v99, 1.0, v99
	v_rcp_f32_e32 v104, v104
; __device__ __forceinline__ f32x4 silu4(f32x4 v) { return (f32x4){silu_f(v[0]), silu_f(v[1]), silu_f(v[2]), silu_f(v[3])}; }
; __device__ __forceinline__ u32x4 pack8(f32x4 a, f32x4 b) { u32x4 w; w.x = cvt_pk_bf16(a[0], a[1]); w.y = cvt_pk_bf16(a[2], a[3]); w.z = cvt_pk_bf16(b[0], b[1]); w.w = cvt_pk_bf16(b[2], b[3]); return w; }
;     __device__ __forceinline__ void operator()(const f32x4 (&acc)[2][2][4][2], const Unit& u, int wr, int wc, int fr, int fq) const {
;     ...
;         for (int ai = 0; ai < 2; ++ai)
; #pragma unroll
;             for (int m = 0; m < 4; ++m) {
;                 const int row = u.pm * BM + ai * HALF + wr * 64 + m * 16 + fr;
;                 const float rstd = rs[ai][m];
;                 const f32x4 a0 = silu4(acc[ai][0][m][0] * rstd) * (acc[ai][1][m][0] * rstd);
;                 const f32x4 a1 = silu4(acc[ai][0][m][1] * rstd) * (acc[ai][1][m][1] * rstd);
;                 *(u32x4*)(ACT + (size_t)row * 2816 + col0) = pack8(a0, a1);
;             }
	v_rcp_f32_e32 v105, v105
	v_rcp_f32_e32 v96, v96
	v_rcp_f32_e32 v97, v97
	v_rcp_f32_e32 v98, v98
	v_rcp_f32_e32 v99, v99
	v_pk_mul_f32 v[92:93], v[92:93], v[102:103]
	v_pk_mul_f32 v[84:85], v[84:85], v[172:173] op_sel_hi:[1,0]
	v_pk_mul_f32 v[94:95], v[94:95], v[104:105]
	v_pk_mul_f32 v[86:87], v[86:87], v[172:173] op_sel_hi:[1,0]
	v_pk_mul_f32 v[84:85], v[84:85], v[92:93]
	v_pk_mul_f32 v[88:89], v[88:89], v[96:97]
	v_pk_mul_f32 v[90:91], v[90:91], v[98:99]
	v_pk_mul_f32 v[80:81], v[80:81], v[172:173] op_sel_hi:[1,0]
	v_pk_mul_f32 v[82:83], v[82:83], v[172:173] op_sel_hi:[1,0]
	v_pk_mul_f32 v[86:87], v[86:87], v[94:95]
	v_pk_mul_f32 v[90:91], v[82:83], v[90:91]
	v_pk_mul_f32 v[82:83], v[80:81], v[88:89]
	v_cvt_pk_bf16_f32 v80, v84, v85
	v_mad_i64_i32 v[84:85], s[38:39], v162, s56, v[112:113]
	v_pk_mul_f32 v[76:77], v[76:77], v[168:169] op_sel_hi:[1,0]
	v_cvt_pk_bf16_f32 v81, v86, v87
	v_cvt_pk_bf16_f32 v82, v82, v83
	v_cvt_pk_bf16_f32 v83, v90, v91
	v_pk_mul_f32 v[78:79], v[78:79], v[168:169] op_sel_hi:[1,0]
	v_mul_f32_e32 v86, 0xbfb8aa3b, v76
	v_mul_f32_e32 v87, 0xbfb8aa3b, v77
	v_lshl_add_u64 v[84:85], v[84:85], 0, v[114:115]
	v_pk_mul_f32 v[72:73], v[72:73], v[168:169] op_sel_hi:[1,0]
	v_pk_mul_f32 v[74:75], v[74:75], v[168:169] op_sel_hi:[1,0]
	v_exp_f32_e32 v86, v86
	v_exp_f32_e32 v87, v87
	v_mul_f32_e32 v88, 0xbfb8aa3b, v78
	v_mul_f32_e32 v89, 0xbfb8aa3b, v79
	global_store_dwordx4 v[84:85], v[80:83], off
	v_exp_f32_e32 v88, v88
	v_exp_f32_e32 v89, v89
	v_mul_f32_e32 v80, 0xbfb8aa3b, v72
	v_mul_f32_e32 v81, 0xbfb8aa3b, v73
	v_mul_f32_e32 v82, 0xbfb8aa3b, v74
	v_mul_f32_e32 v83, 0xbfb8aa3b, v75
	v_exp_f32_e32 v80, v80
	v_exp_f32_e32 v81, v81
	v_exp_f32_e32 v82, v82
	v_exp_f32_e32 v83, v83
	v_add_f32_e32 v86, 1.0, v86
	v_add_f32_e32 v87, 1.0, v87
	v_rcp_f32_e32 v86, v86
	v_rcp_f32_e32 v87, v87
	v_add_f32_e32 v88, 1.0, v88
	v_add_f32_e32 v89, 1.0, v89
	v_add_f32_e32 v80, 1.0, v80
	v_add_f32_e32 v81, 1.0, v81
	v_add_f32_e32 v82, 1.0, v82
	v_add_f32_e32 v83, 1.0, v83
	v_rcp_f32_e32 v88, v88
	v_rcp_f32_e32 v89, v89
	v_rcp_f32_e32 v80, v80
	v_rcp_f32_e32 v81, v81
	v_rcp_f32_e32 v82, v82
	v_rcp_f32_e32 v83, v83
	v_pk_mul_f32 v[76:77], v[76:77], v[86:87]
	v_pk_mul_f32 v[68:69], v[68:69], v[168:169] op_sel_hi:[1,0]
	v_pk_mul_f32 v[78:79], v[78:79], v[88:89]
	v_pk_mul_f32 v[70:71], v[70:71], v[168:169] op_sel_hi:[1,0]
	v_pk_mul_f32 v[68:69], v[68:69], v[76:77]
	v_pk_mul_f32 v[72:73], v[72:73], v[80:81]
	v_pk_mul_f32 v[74:75], v[74:75], v[82:83]
	v_pk_mul_f32 v[64:65], v[64:65], v[168:169] op_sel_hi:[1,0]
	v_pk_mul_f32 v[66:67], v[66:67], v[168:169] op_sel_hi:[1,0]
	v_pk_mul_f32 v[70:71], v[70:71], v[78:79]
	v_pk_mul_f32 v[74:75], v[66:67], v[74:75]
	v_pk_mul_f32 v[66:67], v[64:65], v[72:73]
	v_cvt_pk_bf16_f32 v64, v68, v69
	v_mad_i64_i32 v[68:69], s[38:39], v158, s56, v[112:113]
	v_pk_mul_f32 v[60:61], v[60:61], v[164:165] op_sel_hi:[1,0]
	v_cvt_pk_bf16_f32 v65, v70, v71
	v_cvt_pk_bf16_f32 v66, v66, v67
	v_cvt_pk_bf16_f32 v67, v74, v75
	v_pk_mul_f32 v[62:63], v[62:63], v[164:165] op_sel_hi:[1,0]
	v_mul_f32_e32 v70, 0xbfb8aa3b, v60
	v_mul_f32_e32 v71, 0xbfb8aa3b, v61
	v_lshl_add_u64 v[68:69], v[68:69], 0, v[114:115]
	v_pk_mul_f32 v[56:57], v[56:57], v[164:165] op_sel_hi:[1,0]
	v_pk_mul_f32 v[58:59], v[58:59], v[164:165] op_sel_hi:[1,0]
	v_exp_f32_e32 v70, v70
	v_exp_f32_e32 v71, v71
	v_mul_f32_e32 v72, 0xbfb8aa3b, v62
	v_mul_f32_e32 v73, 0xbfb8aa3b, v63
	global_store_dwordx4 v[68:69], v[64:67], off
	s_branch .Lhh0_epi_end
	v_exp_f32_e32 v72, v72
	v_exp_f32_e32 v73, v73
	v_mul_f32_e32 v64, 0xbfb8aa3b, v56
	v_mul_f32_e32 v65, 0xbfb8aa3b, v57
	v_mul_f32_e32 v66, 0xbfb8aa3b, v58
	v_mul_f32_e32 v67, 0xbfb8aa3b, v59
	v_exp_f32_e32 v64, v64
	v_exp_f32_e32 v65, v65
	v_exp_f32_e32 v66, v66
	v_exp_f32_e32 v67, v67
	v_add_f32_e32 v70, 1.0, v70
	v_add_f32_e32 v71, 1.0, v71
	v_rcp_f32_e32 v70, v70
	v_rcp_f32_e32 v71, v71
	v_add_f32_e32 v72, 1.0, v72
	v_add_f32_e32 v73, 1.0, v73
	v_add_f32_e32 v64, 1.0, v64
	v_add_f32_e32 v65, 1.0, v65
	v_add_f32_e32 v66, 1.0, v66
	v_add_f32_e32 v67, 1.0, v67
	v_rcp_f32_e32 v72, v72
	v_rcp_f32_e32 v73, v73
	v_rcp_f32_e32 v64, v64
	v_rcp_f32_e32 v65, v65
	v_rcp_f32_e32 v66, v66
	v_rcp_f32_e32 v67, v67
	v_pk_mul_f32 v[60:61], v[60:61], v[70:71]
	v_pk_mul_f32 v[52:53], v[52:53], v[164:165] op_sel_hi:[1,0]
	v_pk_mul_f32 v[62:63], v[62:63], v[72:73]
	v_pk_mul_f32 v[54:55], v[54:55], v[164:165] op_sel_hi:[1,0]
	v_pk_mul_f32 v[52:53], v[52:53], v[60:61]
	v_pk_mul_f32 v[56:57], v[56:57], v[64:65]
	v_pk_mul_f32 v[58:59], v[58:59], v[66:67]
	v_pk_mul_f32 v[48:49], v[48:49], v[164:165] op_sel_hi:[1,0]
	v_pk_mul_f32 v[50:51], v[50:51], v[164:165] op_sel_hi:[1,0]
	v_pk_mul_f32 v[54:55], v[54:55], v[62:63]
	v_pk_mul_f32 v[58:59], v[50:51], v[58:59]
	v_pk_mul_f32 v[50:51], v[48:49], v[56:57]
	v_cvt_pk_bf16_f32 v48, v52, v53
	v_mad_i64_i32 v[52:53], s[38:39], v154, s56, v[112:113]
	v_pk_mul_f32 v[44:45], v[44:45], v[160:161] op_sel_hi:[1,0]
	v_cvt_pk_bf16_f32 v49, v54, v55
	v_cvt_pk_bf16_f32 v50, v50, v51
	v_cvt_pk_bf16_f32 v51, v58, v59
	v_pk_mul_f32 v[46:47], v[46:47], v[160:161] op_sel_hi:[1,0]
	v_mul_f32_e32 v54, 0xbfb8aa3b, v44
	v_mul_f32_e32 v55, 0xbfb8aa3b, v45
	v_lshl_add_u64 v[52:53], v[52:53], 0, v[114:115]
	v_pk_mul_f32 v[40:41], v[40:41], v[160:161] op_sel_hi:[1,0]
	v_pk_mul_f32 v[42:43], v[42:43], v[160:161] op_sel_hi:[1,0]
	v_exp_f32_e32 v54, v54
	v_exp_f32_e32 v55, v55
	v_mul_f32_e32 v56, 0xbfb8aa3b, v46
	v_mul_f32_e32 v57, 0xbfb8aa3b, v47
	global_store_dwordx4 v[52:53], v[48:51], off
	v_exp_f32_e32 v56, v56
	v_exp_f32_e32 v57, v57
	v_mul_f32_e32 v48, 0xbfb8aa3b, v40
	v_mul_f32_e32 v49, 0xbfb8aa3b, v41
; __device__ __forceinline__ f32x4 silu4(f32x4 v) { return (f32x4){silu_f(v[0]), silu_f(v[1]), silu_f(v[2]), silu_f(v[3])}; }
; __device__ __forceinline__ u32x4 pack8(f32x4 a, f32x4 b) { u32x4 w; w.x = cvt_pk_bf16(a[0], a[1]); w.y = cvt_pk_bf16(a[2], a[3]); w.z = cvt_pk_bf16(b[0], b[1]); w.w = cvt_pk_bf16(b[2], b[3]); return w; }
;     __device__ __forceinline__ void operator()(const f32x4 (&acc)[2][2][4][2], const Unit& u, int wr, int wc, int fr, int fq) const {
;     ...
;         for (int ai = 0; ai < 2; ++ai)
; #pragma unroll
;             for (int m = 0; m < 4; ++m) {
;                 const int row = u.pm * BM + ai * HALF + wr * 64 + m * 16 + fr;
;                 const float rstd = rs[ai][m];
;                 const f32x4 a0 = silu4(acc[ai][0][m][0] * rstd) * (acc[ai][1][m][0] * rstd);
;                 const f32x4 a1 = silu4(acc[ai][0][m][1] * rstd) * (acc[ai][1][m][1] * rstd);
;                 *(u32x4*)(ACT + (size_t)row * 2816 + col0) = pack8(a0, a1);
;             }
; template <class Epi, class Sched, bool ALIGN_EPI = false, bool SP2 = false>
; __device__ __forceinline__ void gemm_phase(PG8_LAS unsigned char* lds, const Gemm g, const Sched& S, const Epi& E, int tid_in) {
;     ...
;         if constexpr (!Epi::AFTER_DRAIN) { E(acc, cur, wr, wc, fr, fq); S.done(cur); }
;         if (!has_next) break;
	v_mul_f32_e32 v50, 0xbfb8aa3b, v42
	v_mul_f32_e32 v51, 0xbfb8aa3b, v43
	v_exp_f32_e32 v48, v48
	v_exp_f32_e32 v49, v49
	v_exp_f32_e32 v50, v50
	v_exp_f32_e32 v51, v51
	v_add_f32_e32 v54, 1.0, v54
	v_add_f32_e32 v55, 1.0, v55
	v_rcp_f32_e32 v54, v54
	v_rcp_f32_e32 v55, v55
	v_add_f32_e32 v56, 1.0, v56
	v_add_f32_e32 v57, 1.0, v57
	v_add_f32_e32 v48, 1.0, v48
	v_add_f32_e32 v49, 1.0, v49
	v_add_f32_e32 v50, 1.0, v50
	v_add_f32_e32 v51, 1.0, v51
	v_rcp_f32_e32 v56, v56
	v_rcp_f32_e32 v57, v57
	v_rcp_f32_e32 v48, v48
	v_rcp_f32_e32 v49, v49
	v_rcp_f32_e32 v50, v50
	v_rcp_f32_e32 v51, v51
	v_pk_mul_f32 v[44:45], v[44:45], v[54:55]
	v_pk_mul_f32 v[36:37], v[36:37], v[160:161] op_sel_hi:[1,0]
	v_pk_mul_f32 v[46:47], v[46:47], v[56:57]
	v_pk_mul_f32 v[38:39], v[38:39], v[160:161] op_sel_hi:[1,0]
	v_pk_mul_f32 v[36:37], v[36:37], v[44:45]
	v_pk_mul_f32 v[40:41], v[40:41], v[48:49]
	v_pk_mul_f32 v[42:43], v[42:43], v[50:51]
	v_pk_mul_f32 v[32:33], v[32:33], v[160:161] op_sel_hi:[1,0]
	v_pk_mul_f32 v[34:35], v[34:35], v[160:161] op_sel_hi:[1,0]
	v_pk_mul_f32 v[38:39], v[38:39], v[46:47]
	v_pk_mul_f32 v[42:43], v[34:35], v[42:43]
	v_pk_mul_f32 v[34:35], v[32:33], v[40:41]
	v_cvt_pk_bf16_f32 v32, v36, v37
	v_mad_i64_i32 v[36:37], s[38:39], v150, s56, v[112:113]
	v_pk_mul_f32 v[28:29], v[28:29], v[156:157] op_sel_hi:[1,0]
	v_cvt_pk_bf16_f32 v33, v38, v39
	v_cvt_pk_bf16_f32 v34, v34, v35
	v_cvt_pk_bf16_f32 v35, v42, v43
	v_pk_mul_f32 v[30:31], v[30:31], v[156:157] op_sel_hi:[1,0]
	v_mul_f32_e32 v38, 0xbfb8aa3b, v28
	v_mul_f32_e32 v39, 0xbfb8aa3b, v29
	v_lshl_add_u64 v[36:37], v[36:37], 0, v[114:115]
	v_pk_mul_f32 v[24:25], v[24:25], v[156:157] op_sel_hi:[1,0]
	v_pk_mul_f32 v[26:27], v[26:27], v[156:157] op_sel_hi:[1,0]
	v_exp_f32_e32 v38, v38
	v_exp_f32_e32 v39, v39
	v_mul_f32_e32 v40, 0xbfb8aa3b, v30
	v_mul_f32_e32 v41, 0xbfb8aa3b, v31
	global_store_dwordx4 v[36:37], v[32:35], off
	v_exp_f32_e32 v40, v40
	v_exp_f32_e32 v41, v41
	v_mul_f32_e32 v32, 0xbfb8aa3b, v24
	v_mul_f32_e32 v33, 0xbfb8aa3b, v25
	v_mul_f32_e32 v34, 0xbfb8aa3b, v26
	v_mul_f32_e32 v35, 0xbfb8aa3b, v27
	v_exp_f32_e32 v32, v32
	v_exp_f32_e32 v33, v33
	v_exp_f32_e32 v34, v34
	v_exp_f32_e32 v35, v35
	v_add_f32_e32 v38, 1.0, v38
	v_add_f32_e32 v39, 1.0, v39
	v_rcp_f32_e32 v38, v38
	v_rcp_f32_e32 v39, v39
	v_add_f32_e32 v40, 1.0, v40
	v_add_f32_e32 v41, 1.0, v41
	v_add_f32_e32 v32, 1.0, v32
	v_add_f32_e32 v33, 1.0, v33
	v_add_f32_e32 v34, 1.0, v34
	v_add_f32_e32 v35, 1.0, v35
	v_rcp_f32_e32 v40, v40
	v_rcp_f32_e32 v41, v41
	v_rcp_f32_e32 v32, v32
	v_rcp_f32_e32 v33, v33
	v_rcp_f32_e32 v34, v34
	v_rcp_f32_e32 v35, v35
	v_pk_mul_f32 v[28:29], v[28:29], v[38:39]
	v_pk_mul_f32 v[20:21], v[20:21], v[156:157] op_sel_hi:[1,0]
	v_pk_mul_f32 v[30:31], v[30:31], v[40:41]
	v_pk_mul_f32 v[22:23], v[22:23], v[156:157] op_sel_hi:[1,0]
	v_pk_mul_f32 v[20:21], v[20:21], v[28:29]
	v_pk_mul_f32 v[24:25], v[24:25], v[32:33]
	v_pk_mul_f32 v[26:27], v[26:27], v[34:35]
	v_pk_mul_f32 v[16:17], v[16:17], v[156:157] op_sel_hi:[1,0]
	v_pk_mul_f32 v[18:19], v[18:19], v[156:157] op_sel_hi:[1,0]
	v_pk_mul_f32 v[22:23], v[22:23], v[30:31]
	v_pk_mul_f32 v[26:27], v[18:19], v[26:27]
	v_pk_mul_f32 v[18:19], v[16:17], v[24:25]
	v_cvt_pk_bf16_f32 v16, v20, v21
	v_mad_i64_i32 v[20:21], s[38:39], v148, s56, v[112:113]
	v_pk_mul_f32 v[12:13], v[12:13], v[152:153] op_sel_hi:[1,0]
	v_cvt_pk_bf16_f32 v17, v22, v23
	v_cvt_pk_bf16_f32 v18, v18, v19
	v_cvt_pk_bf16_f32 v19, v26, v27
	v_lshl_add_u64 v[20:21], v[20:21], 0, v[114:115]
	v_mul_f32_e32 v22, 0xbfb8aa3b, v12
	v_mul_f32_e32 v23, 0xbfb8aa3b, v13
	v_pk_mul_f32 v[8:9], v[8:9], v[152:153] op_sel_hi:[1,0]
	v_pk_mul_f32 v[10:11], v[10:11], v[152:153] op_sel_hi:[1,0]
	v_exp_f32_e32 v22, v22
	v_exp_f32_e32 v23, v23
	global_store_dwordx4 v[20:21], v[16:19], off
	v_pk_mul_f32 v[14:15], v[14:15], v[152:153] op_sel_hi:[1,0]
	v_add_f32_e32 v22, 1.0, v22
	v_mul_f32_e32 v16, 0xbfb8aa3b, v8
	v_mul_f32_e32 v17, 0xbfb8aa3b, v9
	v_mul_f32_e32 v18, 0xbfb8aa3b, v10
	v_mul_f32_e32 v19, 0xbfb8aa3b, v11
	v_exp_f32_e32 v16, v16
	v_exp_f32_e32 v17, v17
	v_exp_f32_e32 v18, v18
	v_exp_f32_e32 v19, v19
	v_mul_f32_e32 v24, 0xbfb8aa3b, v14
	v_mul_f32_e32 v25, 0xbfb8aa3b, v15
	v_exp_f32_e32 v24, v24
	v_exp_f32_e32 v25, v25
	v_add_f32_e32 v23, 1.0, v23
	v_rcp_f32_e32 v22, v22
	v_rcp_f32_e32 v23, v23
	v_add_f32_e32 v16, 1.0, v16
	v_add_f32_e32 v17, 1.0, v17
	v_add_f32_e32 v18, 1.0, v18
	v_add_f32_e32 v19, 1.0, v19
	v_rcp_f32_e32 v16, v16
	v_rcp_f32_e32 v17, v17
	v_rcp_f32_e32 v18, v18
	v_rcp_f32_e32 v19, v19
	v_add_f32_e32 v24, 1.0, v24
	v_add_f32_e32 v25, 1.0, v25
	v_rcp_f32_e32 v24, v24
	v_rcp_f32_e32 v25, v25
	v_pk_mul_f32 v[12:13], v[12:13], v[22:23]
	v_pk_mul_f32 v[4:5], v[4:5], v[152:153] op_sel_hi:[1,0]
	v_pk_mul_f32 v[8:9], v[8:9], v[16:17]
	v_pk_mul_f32 v[4:5], v[4:5], v[12:13]
	v_pk_mul_f32 v[10:11], v[10:11], v[18:19]
	v_pk_mul_f32 v[0:1], v[0:1], v[152:153] op_sel_hi:[1,0]
	v_pk_mul_f32 v[2:3], v[2:3], v[152:153] op_sel_hi:[1,0]
	v_pk_mul_f32 v[14:15], v[14:15], v[24:25]
	v_pk_mul_f32 v[10:11], v[2:3], v[10:11]
	v_pk_mul_f32 v[2:3], v[0:1], v[8:9]
	v_cvt_pk_bf16_f32 v0, v4, v5
	v_mad_i64_i32 v[4:5], s[38:39], v146, s56, v[112:113]
	v_pk_mul_f32 v[6:7], v[6:7], v[152:153] op_sel_hi:[1,0]
	v_lshl_add_u64 v[4:5], v[4:5], 0, v[114:115]
	v_pk_mul_f32 v[6:7], v[6:7], v[14:15]
	s_nop 0
	v_cvt_pk_bf16_f32 v1, v6, v7
	v_cvt_pk_bf16_f32 v2, v2, v3
	v_cvt_pk_bf16_f32 v3, v10, v11
	global_store_dwordx4 v[4:5], v[0:3], off
.Lhh0_epi_end:
	s_cbranch_vccnz .LBB0_516
	s_andn2_b64 vcc, exec, s[12:13]
	s_cbranch_vccnz .LBB0_515
	s_barrier
	s_branch .LBB0_515

;     __device__ bool next(int i, Unit& u) const { if (i > 0) return false; const int t = c - first; if (t < 0 || t >= nM * nN) return false; u.pm = t % nM; u.pn = t / nM; return true; }
;     __host__ __device__ bool next(int i, Unit& u) const {
;         const long L = (long)i * G + c; if (L >= nwg) return false;
;         int wgid = (int)L; { const int q = nwg / NXCD, r = nwg % NXCD, xcd = wgid % NXCD, off = wgid / NXCD; wgid = (xcd < r ? xcd * (q + 1) : r * (q + 1) + (xcd - r) * q) + off; }
;         const int nig = WGM * nN, gid = wgid / nig, fm = gid * WGM, gsz = (nM - fm) < WGM ? (nM - fm) : WGM;
;         u.pm = fm + ((wgid % nig) % gsz); u.pn = (wgid % nig) / gsz; return true;
;     }
; template <class Epi, class Sched, bool ALIGN_EPI = false, bool SP2 = false>
; __device__ __forceinline__ void gemm_phase(PG8_LAS unsigned char* lds, const Gemm g, const Sched& S, const Epi& E, int tid_in) {
;     ...
; #pragma unroll
;         for (int a = 0; a < 2; ++a)
; #pragma unroll
;             for (int b = 0; b < 2; ++b)
; #pragma unroll
;                 for (int m = 0; m < 4; ++m)
; #pragma unroll
;                     for (int n = 0; n < 2; ++n) acc[a][b][m][n] = (f32x4){0.f, 0.f, 0.f, 0.f};
;         cur = nxt; cA = nA; cB = nB; ++ui;
.LBB0_993:
	s_add_i32 s61, s61, 1
	s_mul_i32 s4, s61, s64
	s_mul_hi_u32 s5, s61, s65
	s_add_i32 s5, s5, s4
	s_mul_i32 s4, s61, s65
	s_add_u32 s44, s4, s2
	s_addc_u32 s45, s5, s40
	s_cmp_ge_u32 s44, 0x580
	s_cselect_b32 s99, 0x40000, 0
	s_cselect_b32 s98, 0x80, 0
	s_sub_u32 s44, s44, s98
	v_cmp_gt_i64_e32 vcc, s[44:45], v[144:145]
	v_cmp_lt_i64_e64 s[16:17], s[44:45], v[142:143]
	s_cbranch_vccnz .LBB0_995
	s_ashr_i32 s4, s44, 31
	s_lshr_b32 s4, s4, 29
	s_add_i32 s4, s44, s4
	s_ashr_i32 s5, s4, 3
	s_and_b32 s4, s4, -8
	s_sub_i32 s4, s44, s4
	s_cmp_lt_i32 s4, 0
	s_cselect_b32 s14, s56, 0xb0
	s_mul_i32 s4, s14, s4
	s_add_i32 s4, s4, s5
	s_mul_hi_i32 s5, s4, 0x2e8ba2e9
	s_lshr_b32 s14, s5, 31
	s_ashr_i32 s5, s5, 5
	s_add_i32 s5, s5, s14
	s_lshl_b32 s14, s5, 3
	s_sub_i32 s15, 64, s14
	s_min_i32 s15, s15, 8
	s_abs_i32 s26, s15
	v_cvt_f32_u32_e32 v0, s26
	s_sub_i32 s42, 0, s26
	s_mulk_i32 s5, 0xb0
	s_sub_i32 s4, s4, s5
	v_rcp_iflag_f32_e32 v0, v0
	s_abs_i32 s5, s4
	s_xor_b32 s27, s4, s15
	s_ashr_i32 s27, s27, 31
	v_mul_f32_e32 v0, 0x4f7ffffe, v0
	v_cvt_u32_f32_e32 v0, v0
	s_nop 0
	v_readfirstlane_b32 s43, v0
	s_mul_i32 s42, s42, s43
	s_mul_hi_u32 s42, s43, s42
	s_add_i32 s43, s43, s42
	s_mul_hi_u32 s42, s5, s43
	s_mul_i32 s43, s42, s26
	s_sub_i32 s5, s5, s43
	s_add_i32 s44, s42, 1
	s_sub_i32 s43, s5, s26
	s_cmp_ge_u32 s5, s26
	s_cselect_b32 s42, s44, s42
	s_cselect_b32 s5, s43, s5
	s_add_i32 s43, s42, 1
	s_cmp_ge_u32 s5, s26
	s_cselect_b32 s5, s43, s42
	s_xor_b32 s5, s5, s27
	s_sub_i32 s26, s5, s27
	s_mul_i32 s5, s26, s15
	s_sub_i32 s4, s4, s5
	s_add_i32 s42, s4, s14
.LBB0_995:
	s_ashr_i32 s43, s42, 31
	s_lshl_b64 s[14:15], s[42:43], 19
	s_add_u32 s44, s0, s14
	s_addc_u32 s45, s3, s15
	s_add_u32 s44, s44, s99
	s_addc_u32 s45, s45, 0
	s_and_b64 s[14:15], s[16:17], exec
	s_cselect_b32 s43, s45, s53
	s_cselect_b32 s69, s44, s52
	s_ashr_i32 s27, s26, 31
	s_lshl_b64 s[14:15], s[26:27], 19
	s_add_u32 s46, s12, s14
	s_addc_u32 s47, s13, s15
	s_and_b64 s[14:15], s[16:17], exec
	s_cselect_b32 s27, s47, s51
	s_cselect_b32 s70, s46, s50
	s_add_u32 s71, s50, 0x100
	s_addc_u32 s72, s51, 0
	s_add_u32 s50, s52, 0x40080
	v_mov_b32_e32 v0, 0
	s_addc_u32 s51, s53, 0
	s_mov_b32 s73, -2
	v_mov_b32_e32 v1, v0
	v_mov_b32_e32 v2, v0
	v_mov_b32_e32 v3, v0
	v_mov_b32_e32 v4, v0
	v_mov_b32_e32 v5, v0
	v_mov_b32_e32 v6, v0
	v_mov_b32_e32 v7, v0
	v_mov_b32_e32 v16, v0
	v_mov_b32_e32 v17, v0
	v_mov_b32_e32 v18, v0
	v_mov_b32_e32 v19, v0
	v_mov_b32_e32 v20, v0
	v_mov_b32_e32 v21, v0
	v_mov_b32_e32 v22, v0
	v_mov_b32_e32 v23, v0
	v_mov_b32_e32 v32, v0
	v_mov_b32_e32 v33, v0
	v_mov_b32_e32 v34, v0
	v_mov_b32_e32 v35, v0
	v_mov_b32_e32 v36, v0
	v_mov_b32_e32 v37, v0
	v_mov_b32_e32 v38, v0
	v_mov_b32_e32 v39, v0
	v_mov_b32_e32 v48, v0
	v_mov_b32_e32 v49, v0
	v_mov_b32_e32 v50, v0
	v_mov_b32_e32 v51, v0
	v_mov_b32_e32 v52, v0
	v_mov_b32_e32 v53, v0
	v_mov_b32_e32 v54, v0
	v_mov_b32_e32 v55, v0
	v_mov_b32_e32 v8, v0
	v_mov_b32_e32 v9, v0
	v_mov_b32_e32 v10, v0
	v_mov_b32_e32 v11, v0
	v_mov_b32_e32 v12, v0
	v_mov_b32_e32 v13, v0
	v_mov_b32_e32 v14, v0
	v_mov_b32_e32 v15, v0
	v_mov_b32_e32 v24, v0
	v_mov_b32_e32 v25, v0
	v_mov_b32_e32 v26, v0
	v_mov_b32_e32 v27, v0
	v_mov_b32_e32 v28, v0
	v_mov_b32_e32 v29, v0
	v_mov_b32_e32 v30, v0
	v_mov_b32_e32 v31, v0
	v_mov_b32_e32 v40, v0
	v_mov_b32_e32 v41, v0
	v_mov_b32_e32 v42, v0
	v_mov_b32_e32 v43, v0
	v_mov_b32_e32 v44, v0
	v_mov_b32_e32 v45, v0
	v_mov_b32_e32 v46, v0
	v_mov_b32_e32 v47, v0
	v_mov_b32_e32 v56, v0
	v_mov_b32_e32 v57, v0
	v_mov_b32_e32 v58, v0
	v_mov_b32_e32 v59, v0
	v_mov_b32_e32 v60, v0
	v_mov_b32_e32 v61, v0
	v_mov_b32_e32 v62, v0
	v_mov_b32_e32 v63, v0
	v_mov_b32_e32 v64, v0
	v_mov_b32_e32 v65, v0
	v_mov_b32_e32 v66, v0
	v_mov_b32_e32 v67, v0
	v_mov_b32_e32 v68, v0
	v_mov_b32_e32 v69, v0
	v_mov_b32_e32 v70, v0
	v_mov_b32_e32 v71, v0
	v_mov_b32_e32 v80, v0
	v_mov_b32_e32 v81, v0
	v_mov_b32_e32 v82, v0
	v_mov_b32_e32 v83, v0
	v_mov_b32_e32 v84, v0
	v_mov_b32_e32 v85, v0
	v_mov_b32_e32 v86, v0
	v_mov_b32_e32 v87, v0
	v_mov_b32_e32 v96, v0
	v_mov_b32_e32 v97, v0
	v_mov_b32_e32 v98, v0
	v_mov_b32_e32 v99, v0
	v_mov_b32_e32 v100, v0
	v_mov_b32_e32 v101, v0
	v_mov_b32_e32 v102, v0
	v_mov_b32_e32 v103, v0
	v_mov_b32_e32 v112, v0
	v_mov_b32_e32 v113, v0
	v_mov_b32_e32 v114, v0
	v_mov_b32_e32 v115, v0
	v_mov_b32_e32 v116, v0
	v_mov_b32_e32 v117, v0
	v_mov_b32_e32 v118, v0
	v_mov_b32_e32 v119, v0
	v_mov_b32_e32 v72, v0
	v_mov_b32_e32 v73, v0
	v_mov_b32_e32 v74, v0
	v_mov_b32_e32 v75, v0
	v_mov_b32_e32 v76, v0
	v_mov_b32_e32 v77, v0
	v_mov_b32_e32 v78, v0
	v_mov_b32_e32 v79, v0
	v_mov_b32_e32 v88, v0
	v_mov_b32_e32 v89, v0
	v_mov_b32_e32 v90, v0
	v_mov_b32_e32 v91, v0
	v_mov_b32_e32 v92, v0
	v_mov_b32_e32 v93, v0
	v_mov_b32_e32 v94, v0
	v_mov_b32_e32 v95, v0
	v_mov_b32_e32 v104, v0
	v_mov_b32_e32 v105, v0
	v_mov_b32_e32 v106, v0
	v_mov_b32_e32 v107, v0
	v_mov_b32_e32 v108, v0
	v_mov_b32_e32 v109, v0
	v_mov_b32_e32 v110, v0
	v_mov_b32_e32 v111, v0
	v_mov_b32_e32 v120, v0
	v_mov_b32_e32 v121, v0
	v_mov_b32_e32 v122, v0
	v_mov_b32_e32 v123, v0
	v_mov_b32_e32 v124, v0
	v_mov_b32_e32 v125, v0
	v_mov_b32_e32 v126, v0
	v_mov_b32_e32 v127, v0
	v_readlane_b32 s98, v252, 5
	s_nop 1
	s_lshl_b32 s98, s98, 5
	s_add_i32 m0, s98, 0x20080
	s_lshl_b32 s98, s48, 14
	s_add_u32 s98, s100, s98
	s_addc_u32 s99, s101, 0
	global_load_lds_dwordx4 v238, s[98:99]
	global_load_lds_dwordx4 v238, s[98:99] offset:1024
	s_cmp_eq_u32 s61, 6
	s_cbranch_scc1 .Lhh1_996

; #define PG8_STAGE(bufoff, gbase, voff) do { _Pragma("unroll") for (int _i = 0; _i < 2; ++_i) \
;         __builtin_amdgcn_global_load_lds((const unsigned*)((const char*)(gbase) + (voff)[_i]), (PG8_LAS unsigned*)(lds + (bufoff) + ldsw + _i * 8192), 16, 0, 0); } while (0)
; #define PG8_LDA(dst, b, h) do { _Pragma("unroll") for (int m = 0; m < 4; ++m) _Pragma("unroll") for (int k = 0; k < 2; ++k) dst[m][k] = *(const PG8_LAS bf16x8*)(lds + PG8_SA(b, h) + aoff + m * 2048 + k * 1024); } while (0)
; #define PG8_WAIT_V(n) asm volatile("s_waitcnt vmcnt(" #n ")" ::: "memory")
; #define PG8_WAIT_L(n) asm volatile("s_waitcnt lgkmcnt(" #n ")" ::: "memory")
; #define PG8_BAR __builtin_amdgcn_s_barrier()
; template <class Epi, class Sched, bool ALIGN_EPI = false, bool SP2 = false>
; __device__ __forceinline__ void gemm_phase(PG8_LAS unsigned char* lds, const Gemm g, const Sched& S, const Epi& E, int tid_in) {
;     ...
;         for (int t = 0; t < nt; t += 2) {
;             const bool last = (t == nt - 2);
;             const char* a1 = cA + (size_t)(t + 1) * kstep;
;             const char* a2 = last ? nA : cA + (size_t)(t + 2) * kstep; const char* b2 = last ? nB : cB + (size_t)(t + 2) * kstep;
;             const char* a3 = a2 + kstep; const char* b3 = b2 + kstep;
;             if (last && has_next) S.a_ready(nxt);
;             if constexpr (SP2) {
;             PG8_LDB(B0, 0, 0); PG8_LDB(B1, 0, 1); PG8_SCHED; PG8_LDA(At, 0, 0); PG8_STAGE(PG8_SA(1, 1), a1 + hstep, voffA);
;             PG8_WAIT_V(8); PG8_WAIT_L(0); PG8_BAR; PG8_MMA(0, 0, At, B0); PG8_MMA(0, 1, At, B1); PG8_BAR; PG8_SCHED;
;             PG8_LDA(At, 0, 1); PG8_STAGE(PG8_SB(0, 0), b2, voffB); PG8_STAGE(PG8_SB(0, 1), b2 + hstep, voffB); PG8_STAGE(PG8_SA(0, 0), a2, voffA);
;             PG8_WAIT_V(8); PG8_WAIT_L(0); PG8_BAR; PG8_MMA(1, 0, At, B0); PG8_MMA(1, 1, At, B1); PG8_BAR; PG8_SCHED;
;             PG8_LDB(B0, 1, 0); PG8_LDB(B1, 1, 1); PG8_SCHED; PG8_LDA(At, 1, 0); PG8_STAGE(PG8_SA(0, 1), a2 + hstep, voffA);
;             PG8_WAIT_V(8); PG8_WAIT_L(0); PG8_BAR; PG8_MMA(0, 0, At, B0); PG8_MMA(0, 1, At, B1); PG8_BAR; PG8_SCHED;
;             PG8_LDA(At, 1, 1); PG8_STAGE(PG8_SB(1, 0), b3, voffB); PG8_STAGE(PG8_SB(1, 1), b3 + hstep, voffB); PG8_STAGE(PG8_SA(1, 0), a3, voffA);
;             PG8_WAIT_V(8); PG8_WAIT_L(0); PG8_BAR; PG8_MMA(1, 0, At, B0); PG8_MMA(1, 1, At, B1); PG8_BAR; PG8_SCHED;
.Lhh1_996:
	ds_read_b128 v[146:149], v167
	ds_read_b128 v[150:153], v167 offset:1024
	ds_read_b128 v[176:179], v167 offset:2048
	ds_read_b128 v[180:183], v167 offset:3072
	ds_read_b128 v[184:187], v171
	ds_read_b128 v[188:191], v171 offset:1024
	ds_read_b128 v[192:195], v171 offset:2048
	ds_read_b128 v[196:199], v171 offset:3072
	s_add_u32 s4, s50, 0xfffc0080
	s_addc_u32 s5, s51, -1
	s_cmp_eq_u32 s73, 12
	s_cselect_b32 s55, s43, s5
	s_cselect_b32 s54, s69, s4
	s_cselect_b32 s53, s27, s72
	s_cselect_b32 s52, s70, s71
	v_lshl_add_u64 v[156:157], s[50:51], 0, v[140:141]
	s_add_i32 m0, s57, 0xc000
	ds_read_b128 v[202:205], v173
	ds_read_b128 v[206:209], v173 offset:1024
	ds_read_b128 v[210:213], v173 offset:2048
	ds_read_b128 v[214:217], v173 offset:3072
	ds_read_b128 v[218:221], v173 offset:4096
	ds_read_b128 v[222:225], v173 offset:5120
	ds_read_b128 v[226:229], v173 offset:6144
	ds_read_b128 v[230:233], v173 offset:7168
	global_load_lds_dwordx4 v[156:157], off
	v_lshl_add_u64 v[156:157], s[50:51], 0, v[138:139]
	s_add_i32 m0, s57, 0xe000
	s_nop 0
	global_load_lds_dwordx4 v[156:157], off
	s_waitcnt vmcnt(8)
	s_waitcnt lgkmcnt(0)
	s_barrier
	s_setprio 1
	s_waitcnt lgkmcnt(0)
	v_mfma_f32_16x16x32_bf16 v[124:127], v[146:149], v[202:205], v[124:127]
	v_mfma_f32_16x16x32_bf16 v[120:123], v[176:179], v[202:205], v[120:123]
	v_mfma_f32_16x16x32_bf16 v[108:111], v[146:149], v[210:213], v[108:111]
	v_mfma_f32_16x16x32_bf16 v[104:107], v[176:179], v[210:213], v[104:107]
	v_mfma_f32_16x16x32_bf16 v[92:95], v[146:149], v[218:221], v[92:95]
	v_mfma_f32_16x16x32_bf16 v[88:91], v[176:179], v[218:221], v[88:91]
	v_mfma_f32_16x16x32_bf16 v[76:79], v[146:149], v[226:229], v[76:79]
	v_mfma_f32_16x16x32_bf16 v[72:75], v[176:179], v[226:229], v[72:75]
	v_mfma_f32_16x16x32_bf16 v[124:127], v[150:153], v[206:209], v[124:127]
	v_mfma_f32_16x16x32_bf16 v[120:123], v[180:183], v[206:209], v[120:123]
	v_mfma_f32_16x16x32_bf16 v[108:111], v[150:153], v[214:217], v[108:111]
	v_mfma_f32_16x16x32_bf16 v[104:107], v[180:183], v[214:217], v[104:107]
	v_mfma_f32_16x16x32_bf16 v[92:95], v[150:153], v[222:225], v[92:95]
	v_mfma_f32_16x16x32_bf16 v[88:91], v[180:183], v[222:225], v[88:91]
	v_mfma_f32_16x16x32_bf16 v[76:79], v[150:153], v[230:233], v[76:79]
	v_mfma_f32_16x16x32_bf16 v[72:75], v[180:183], v[230:233], v[72:75]
	s_setprio 0
	s_setprio 1
	v_mfma_f32_16x16x32_bf16 v[116:119], v[184:187], v[202:205], v[116:119]
	v_mfma_f32_16x16x32_bf16 v[112:115], v[192:195], v[202:205], v[112:115]
	v_mfma_f32_16x16x32_bf16 v[100:103], v[184:187], v[210:213], v[100:103]
	v_mfma_f32_16x16x32_bf16 v[96:99], v[192:195], v[210:213], v[96:99]
	v_mfma_f32_16x16x32_bf16 v[84:87], v[184:187], v[218:221], v[84:87]
	v_mfma_f32_16x16x32_bf16 v[80:83], v[192:195], v[218:221], v[80:83]
	v_mfma_f32_16x16x32_bf16 v[68:71], v[184:187], v[226:229], v[68:71]
	v_mfma_f32_16x16x32_bf16 v[64:67], v[192:195], v[226:229], v[64:67]
	v_mfma_f32_16x16x32_bf16 v[116:119], v[188:191], v[206:209], v[116:119]
	v_mfma_f32_16x16x32_bf16 v[112:115], v[196:199], v[206:209], v[112:115]
	v_mfma_f32_16x16x32_bf16 v[100:103], v[188:191], v[214:217], v[100:103]
	v_mfma_f32_16x16x32_bf16 v[96:99], v[196:199], v[214:217], v[96:99]
	v_mfma_f32_16x16x32_bf16 v[84:87], v[188:191], v[222:225], v[84:87]
	v_mfma_f32_16x16x32_bf16 v[80:83], v[196:199], v[222:225], v[80:83]
	v_mfma_f32_16x16x32_bf16 v[68:71], v[188:191], v[230:233], v[68:71]
	v_mfma_f32_16x16x32_bf16 v[64:67], v[196:199], v[230:233], v[64:67]
	s_setprio 0
	s_barrier
	s_add_i32 s4, s66, s33
	v_lshl_add_u64 v[156:157], s[52:53], 0, v[132:133]
	s_mov_b32 m0, s4
	s_nop 0
	global_load_lds_dwordx4 v[156:157], off
	s_add_i32 m0, s4, 0x2000
	s_add_u32 s14, s52, 0x40000
	v_lshl_add_u64 v[160:161], s[52:53], 0, v[128:129]
	s_addc_u32 s15, s53, 0
	s_add_i32 s4, s67, s33
	global_load_lds_dwordx4 v[160:161], off
	v_lshl_add_u64 v[164:165], s[14:15], 0, v[132:133]
	s_mov_b32 m0, s4
	v_lshl_add_u64 v[168:169], s[54:55], 0, v[130:131]
	global_load_lds_dwordx4 v[164:165], off
	v_lshl_add_u64 v[164:165], s[14:15], 0, v[128:129]
	s_add_i32 m0, s4, 0x2000
	s_nop 0
	global_load_lds_dwordx4 v[164:165], off
	v_lshl_add_u64 v[164:165], s[54:55], 0, v[134:135]
	s_mov_b32 m0, s57
	s_nop 0
	global_load_lds_dwordx4 v[164:165], off
	s_mov_b32 m0, s58
	s_nop 0
	global_load_lds_dwordx4 v[168:169], off
	s_waitcnt vmcnt(8)
	s_waitcnt lgkmcnt(0)
	s_barrier
	s_setprio 1
	s_waitcnt lgkmcnt(0)
	s_setprio 0
	s_setprio 1
	s_setprio 0
	s_barrier
	s_add_i32 s4, 0, 0x18000
	v_add_u32_e32 v154, s4, v159
	s_add_i32 s5, 0, 0x1c000
	ds_read_b128 v[146:149], v154
	ds_read_b128 v[150:153], v154 offset:1024
	ds_read_b128 v[176:179], v154 offset:2048
	ds_read_b128 v[180:183], v154 offset:3072
	v_add_u32_e32 v154, s5, v159
	ds_read_b128 v[184:187], v154
	ds_read_b128 v[188:191], v154 offset:1024
	ds_read_b128 v[192:195], v154 offset:2048
	ds_read_b128 v[196:199], v154 offset:3072
	s_add_u32 s14, s54, 0x40000
	s_addc_u32 s15, s55, 0
	s_mov_b32 m0, s59
	v_lshl_add_u64 v[234:235], s[14:15], 0, v[134:135]
	ds_read_b128 v[202:205], v173 offset:32768
	ds_read_b128 v[206:209], v173 offset:33792
	ds_read_b128 v[210:213], v173 offset:34816
	ds_read_b128 v[214:217], v173 offset:35840
	ds_read_b128 v[218:221], v173 offset:36864
	ds_read_b128 v[222:225], v173 offset:37888
	ds_read_b128 v[226:229], v173 offset:38912
	ds_read_b128 v[230:233], v173 offset:39936
	global_load_lds_dwordx4 v[234:235], off
	v_lshl_add_u64 v[234:235], s[14:15], 0, v[130:131]
	s_mov_b32 m0, s60
	s_nop 0
	global_load_lds_dwordx4 v[234:235], off
	s_waitcnt vmcnt(8)
	s_waitcnt lgkmcnt(0)
	s_barrier
; __device__ __forceinline__ float row_part(const float* ss, int row, int fq) { const f32x4 a = ((const f32x4*)(ss + (size_t)row * 16))[fq]; return (a[0] + a[1]) + (a[2] + a[3]); }
; __device__ __forceinline__ float row_finish(float t) { t += shx(t, 16); t += shx(t, 32); return __builtin_amdgcn_rsqf(t * (1.0f / 1024.0f) + RMS_EPS); }
; #define PG8_STAGE(bufoff, gbase, voff) do { _Pragma("unroll") for (int _i = 0; _i < 2; ++_i) \
;         __builtin_amdgcn_global_load_lds((const unsigned*)((const char*)(gbase) + (voff)[_i]), (PG8_LAS unsigned*)(lds + (bufoff) + ldsw + _i * 8192), 16, 0, 0); } while (0)
; #define PG8_LDA(dst, b, h) do { _Pragma("unroll") for (int m = 0; m < 4; ++m) _Pragma("unroll") for (int k = 0; k < 2; ++k) dst[m][k] = *(const PG8_LAS bf16x8*)(lds + PG8_SA(b, h) + aoff + m * 2048 + k * 1024); } while (0)
; #define PG8_WAIT_V(n) asm volatile("s_waitcnt vmcnt(" #n ")" ::: "memory")
; #define PG8_WAIT_L(n) asm volatile("s_waitcnt lgkmcnt(" #n ")" ::: "memory")
;     __device__ __forceinline__ void operator()(const f32x4 (&acc)[2][2][4][2], const Unit& u, int wr, int wc, int fr, int fq) const {
;         const int col0 = u.pn * 128 + 32 * wc + 8 * fq;
;         float rs[2][4];
; #pragma unroll
;         for (int ai = 0; ai < 2; ++ai)
; #pragma unroll
;             for (int m = 0; m < 4; ++m) rs[ai][m] = row_part(ss, u.pm * BM + ai * HALF + wr * 64 + m * 16 + fr, fq);
; #pragma unroll
;         for (int ai = 0; ai < 2; ++ai)
; #pragma unroll
;             for (int m = 0; m < 4; ++m) rs[ai][m] = row_finish(rs[ai][m]);
; template <class Epi, class Sched, bool ALIGN_EPI = false, bool SP2 = false>
; __device__ __forceinline__ void gemm_phase(PG8_LAS unsigned char* lds, const Gemm g, const Sched& S, const Epi& E, int tid_in) {
;     ...
;             PG8_WAIT_V(8); PG8_WAIT_L(0); PG8_BAR; PG8_MMA(1, 0, At, B0); PG8_MMA(1, 1, At, B1); PG8_BAR; PG8_SCHED;
;             PG8_LDB(B0, 1, 0); PG8_LDB(B1, 1, 1); PG8_SCHED; PG8_LDA(At, 1, 0); PG8_STAGE(PG8_SA(0, 1), a2 + hstep, voffA);
;             PG8_WAIT_V(8); PG8_WAIT_L(0); PG8_BAR; PG8_MMA(0, 0, At, B0); PG8_MMA(0, 1, At, B1); PG8_BAR; PG8_SCHED;
;             PG8_LDA(At, 1, 1); PG8_STAGE(PG8_SB(1, 0), b3, voffB); PG8_STAGE(PG8_SB(1, 1), b3 + hstep, voffB); PG8_STAGE(PG8_SA(1, 0), a3, voffA);
;             PG8_WAIT_V(8); PG8_WAIT_L(0); PG8_BAR; PG8_MMA(1, 0, At, B0); PG8_MMA(1, 1, At, B1); PG8_BAR; PG8_SCHED;
	s_setprio 1
	s_waitcnt lgkmcnt(0)
	v_mfma_f32_16x16x32_bf16 v[124:127], v[146:149], v[202:205], v[124:127]
	v_mfma_f32_16x16x32_bf16 v[120:123], v[176:179], v[202:205], v[120:123]
	v_mfma_f32_16x16x32_bf16 v[108:111], v[146:149], v[210:213], v[108:111]
	v_mfma_f32_16x16x32_bf16 v[104:107], v[176:179], v[210:213], v[104:107]
	v_mfma_f32_16x16x32_bf16 v[92:95], v[146:149], v[218:221], v[92:95]
	v_mfma_f32_16x16x32_bf16 v[88:91], v[176:179], v[218:221], v[88:91]
	v_mfma_f32_16x16x32_bf16 v[76:79], v[146:149], v[226:229], v[76:79]
	v_mfma_f32_16x16x32_bf16 v[72:75], v[176:179], v[226:229], v[72:75]
	v_mfma_f32_16x16x32_bf16 v[124:127], v[150:153], v[206:209], v[124:127]
	v_mfma_f32_16x16x32_bf16 v[120:123], v[180:183], v[206:209], v[120:123]
	v_mfma_f32_16x16x32_bf16 v[108:111], v[150:153], v[214:217], v[108:111]
	v_mfma_f32_16x16x32_bf16 v[104:107], v[180:183], v[214:217], v[104:107]
	v_mfma_f32_16x16x32_bf16 v[92:95], v[150:153], v[222:225], v[92:95]
	v_mfma_f32_16x16x32_bf16 v[88:91], v[180:183], v[222:225], v[88:91]
	v_mfma_f32_16x16x32_bf16 v[76:79], v[150:153], v[230:233], v[76:79]
	v_mfma_f32_16x16x32_bf16 v[72:75], v[180:183], v[230:233], v[72:75]
	s_setprio 0
	s_setprio 1
	v_mfma_f32_16x16x32_bf16 v[116:119], v[184:187], v[202:205], v[116:119]
	v_mfma_f32_16x16x32_bf16 v[112:115], v[192:195], v[202:205], v[112:115]
	v_mfma_f32_16x16x32_bf16 v[100:103], v[184:187], v[210:213], v[100:103]
	v_mfma_f32_16x16x32_bf16 v[96:99], v[192:195], v[210:213], v[96:99]
	v_mfma_f32_16x16x32_bf16 v[84:87], v[184:187], v[218:221], v[84:87]
	v_mfma_f32_16x16x32_bf16 v[80:83], v[192:195], v[218:221], v[80:83]
	v_mfma_f32_16x16x32_bf16 v[68:71], v[184:187], v[226:229], v[68:71]
	v_mfma_f32_16x16x32_bf16 v[64:67], v[192:195], v[226:229], v[64:67]
	v_mfma_f32_16x16x32_bf16 v[116:119], v[188:191], v[206:209], v[116:119]
	v_mfma_f32_16x16x32_bf16 v[112:115], v[196:199], v[206:209], v[112:115]
	v_mfma_f32_16x16x32_bf16 v[100:103], v[188:191], v[214:217], v[100:103]
	v_mfma_f32_16x16x32_bf16 v[96:99], v[196:199], v[214:217], v[96:99]
	v_mfma_f32_16x16x32_bf16 v[84:87], v[188:191], v[222:225], v[84:87]
	v_mfma_f32_16x16x32_bf16 v[80:83], v[196:199], v[222:225], v[80:83]
	v_mfma_f32_16x16x32_bf16 v[68:71], v[188:191], v[230:233], v[68:71]
	v_mfma_f32_16x16x32_bf16 v[64:67], v[196:199], v[230:233], v[64:67]
	s_setprio 0
	s_barrier
	s_add_i32 s4, s4, s33
	v_lshl_add_u64 v[156:157], v[156:157], 0, s[22:23]
	s_mov_b32 m0, s4
	s_nop 0
	global_load_lds_dwordx4 v[156:157], off
	s_add_i32 m0, s4, 0x2000
	s_add_u32 s14, s52, 0x40080
	v_lshl_add_u64 v[156:157], v[160:161], 0, s[22:23]
	s_addc_u32 s15, s53, 0
	s_add_i32 s4, s5, s33
	global_load_lds_dwordx4 v[156:157], off
	v_lshl_add_u64 v[156:157], s[14:15], 0, v[132:133]
	s_mov_b32 m0, s4
	s_nop 0
	global_load_lds_dwordx4 v[156:157], off
	v_lshl_add_u64 v[156:157], s[14:15], 0, v[128:129]
	s_add_i32 m0, s4, 0x2000
	s_nop 0
	global_load_lds_dwordx4 v[156:157], off
	v_lshl_add_u64 v[156:157], v[164:165], 0, s[22:23]
	s_mov_b32 m0, s62
	s_nop 0
	global_load_lds_dwordx4 v[156:157], off
	v_lshl_add_u64 v[156:157], v[168:169], 0, s[22:23]
	s_mov_b32 m0, s63
	s_nop 0
	global_load_lds_dwordx4 v[156:157], off
	s_waitcnt vmcnt(8)
	s_waitcnt lgkmcnt(0)
	s_barrier
	s_setprio 1
	s_waitcnt lgkmcnt(0)
	s_setprio 0
	s_setprio 1
	s_setprio 0
	s_barrier
	s_add_i32 s73, s73, 2
	s_add_u32 s71, s71, 0x100
	s_addc_u32 s72, s72, 0
	s_add_u32 s50, s50, 0x100
	s_addc_u32 s51, s51, 0
	s_cmp_gt_u32 s73, 13
	s_cbranch_scc0 .Lhh1_996
	s_and_b64 vcc, exec, s[24:25]
	s_cbranch_vccz .Lhh1_999
	s_barrier
.Lhh1_999:
	v_lshl_add_u32 v168, s48, 8, v155
	s_cmp_ge_u32 s2, 0x80
	s_cselect_b32 s98, 0x80, 0
	v_add_u32_e32 v168, s98, v168
	s_lshl_b32 s99, s98, 6
	v_add_u32_e32 v241, s99, v239
	v_ashrrev_i32_e32 v169, 31, v168
	v_lshlrev_b64 v[146:147], 6, v[168:169]
	v_lshl_add_u64 v[146:147], v[136:137], 0, v[146:147]
	ds_read_b128 v[146:149], v241
	v_or_b32_e32 v164, 16, v168
	v_ashrrev_i32_e32 v165, 31, v164
	v_or_b32_e32 v160, 32, v168
	v_ashrrev_i32_e32 v161, 31, v160
	v_or_b32_e32 v156, 48, v168
	v_ashrrev_i32_e32 v157, 31, v156
	v_add_u32_e32 v152, 0x80, v168
	v_ashrrev_i32_e32 v153, 31, v152
	v_mov_b32_e32 v162, v201
	s_andn2_b64 vcc, exec, s[16:17]
	s_waitcnt lgkmcnt(0)
	v_mov_b32_e32 v150, v147
	v_mov_b32_e32 v151, v148
	v_mov_b32_e32 v147, v149
	v_pk_add_f32 v[146:147], v[150:151], v[146:147]
	s_nop 0
	v_add_f32_e32 v154, v146, v147
	v_lshlrev_b64 v[146:147], 6, v[164:165]
	v_lshl_add_u64 v[146:147], v[136:137], 0, v[146:147]
	ds_read_b128 v[146:149], v241 offset:1024
	s_waitcnt lgkmcnt(0)
	v_mov_b32_e32 v150, v147
	v_mov_b32_e32 v151, v148
	v_mov_b32_e32 v147, v149
	v_pk_add_f32 v[146:147], v[150:151], v[146:147]
	s_nop 0
	v_add_f32_e32 v158, v146, v147
	v_lshlrev_b64 v[146:147], 6, v[160:161]
	v_lshl_add_u64 v[146:147], v[136:137], 0, v[146:147]
	ds_read_b128 v[146:149], v241 offset:2048
	s_waitcnt lgkmcnt(0)
	v_mov_b32_e32 v150, v147
	v_mov_b32_e32 v151, v148
	v_mov_b32_e32 v147, v149
	v_pk_add_f32 v[146:147], v[150:151], v[146:147]
	s_nop 0
	v_add_f32_e32 v161, v146, v147
	v_lshlrev_b64 v[146:147], 6, v[156:157]
	v_lshl_add_u64 v[146:147], v[136:137], 0, v[146:147]
	ds_read_b128 v[146:149], v241 offset:3072
	s_waitcnt lgkmcnt(0)
	v_mov_b32_e32 v150, v147
	v_mov_b32_e32 v151, v148
	v_mov_b32_e32 v147, v149
	v_pk_add_f32 v[146:147], v[150:151], v[146:147]
	s_nop 0
	v_add_f32_e32 v157, v146, v147
	v_lshlrev_b64 v[146:147], 6, v[152:153]
	v_lshl_add_u64 v[146:147], v[136:137], 0, v[146:147]
	ds_read_b128 v[146:149], v241 offset:8192
	s_waitcnt lgkmcnt(0)
; __device__ __forceinline__ float row_part(const float* ss, int row, int fq) { const f32x4 a = ((const f32x4*)(ss + (size_t)row * 16))[fq]; return (a[0] + a[1]) + (a[2] + a[3]); }
; __device__ __forceinline__ float row_finish(float t) { t += shx(t, 16); t += shx(t, 32); return __builtin_amdgcn_rsqf(t * (1.0f / 1024.0f) + RMS_EPS); }
;     __device__ __forceinline__ void operator()(const f32x4 (&acc)[2][2][4][2], const Unit& u, int wr, int wc, int fr, int fq) const {
;     ...
;         float rs[2][4];
; #pragma unroll
;         for (int ai = 0; ai < 2; ++ai)
; #pragma unroll
;             for (int m = 0; m < 4; ++m) rs[ai][m] = row_part(ss, u.pm * BM + ai * HALF + wr * 64 + m * 16 + fr, fq);
; #pragma unroll
;         for (int ai = 0; ai < 2; ++ai)
; #pragma unroll
;             for (int m = 0; m < 4; ++m) rs[ai][m] = row_finish(rs[ai][m]);
	v_mov_b32_e32 v150, v147
	v_mov_b32_e32 v151, v148
	v_mov_b32_e32 v147, v149
	v_pk_add_f32 v[146:147], v[150:151], v[146:147]
	v_add_u32_e32 v150, 0x90, v168
	v_ashrrev_i32_e32 v151, 31, v150
	v_add_f32_e32 v153, v146, v147
	v_lshlrev_b64 v[146:147], 6, v[150:151]
	v_lshl_add_u64 v[146:147], v[136:137], 0, v[146:147]
	ds_read_b128 v[146:149], v241 offset:9216
	s_waitcnt lgkmcnt(0)
	v_mov_b32_e32 v176, v147
	v_mov_b32_e32 v177, v148
	v_mov_b32_e32 v147, v149
	v_add_u32_e32 v148, 0xa0, v168
	v_pk_add_f32 v[146:147], v[176:177], v[146:147]
	v_ashrrev_i32_e32 v149, 31, v148
	v_add_f32_e32 v151, v146, v147
	v_lshlrev_b64 v[146:147], 6, v[148:149]
	v_lshl_add_u64 v[146:147], v[136:137], 0, v[146:147]
	ds_read_b128 v[176:179], v241 offset:10240
	s_waitcnt lgkmcnt(0)
	v_mov_b32_e32 v146, v177
	v_mov_b32_e32 v147, v178
	v_mov_b32_e32 v177, v179
	v_pk_add_f32 v[146:147], v[146:147], v[176:177]
	s_nop 0
	v_add_f32_e32 v149, v146, v147
	v_add_u32_e32 v146, 0xb0, v168
	v_ashrrev_i32_e32 v147, 31, v146
	v_lshlrev_b64 v[176:177], 6, v[146:147]
	v_lshl_add_u64 v[176:177], v[136:137], 0, v[176:177]
	ds_read_b128 v[176:179], v241 offset:11264
	s_waitcnt lgkmcnt(0)
	v_mov_b32_e32 v180, v177
	v_lshlrev_b32_e32 v162, 2, v162
	v_xor_b32_e32 v162, 64, v162
	ds_bpermute_b32 v162, v162, v154
	v_mov_b32_e32 v181, v178
	v_mov_b32_e32 v177, v179
	v_pk_add_f32 v[176:177], v[180:181], v[176:177]
	v_lshl_or_b32 v178, s49, 7, v163
	s_waitcnt lgkmcnt(0)
	v_add_f32_e32 v154, v154, v162
	v_mov_b32_e32 v162, v201
	v_add_f32_e32 v147, v176, v177
	v_lshlrev_b32_e32 v162, 2, v162
	v_xor_b32_e32 v162, 0x80, v162
	ds_bpermute_b32 v162, v162, v154
	v_ashrrev_i32_e32 v179, 31, v178
	s_mov_b64 s[48:49], -1
	s_waitcnt lgkmcnt(0)
	v_add_f32_e32 v154, v154, v162
	v_fmamk_f32 v154, v154, 0x3a800000, v175
	v_rsq_f32_e32 v174, v154
	v_mov_b32_e32 v154, v201
	v_pk_mul_f32 v[124:125], v[124:125], v[174:175] op_sel_hi:[1,0]
	v_lshlrev_b32_e32 v154, 2, v154
	v_xor_b32_e32 v154, 64, v154
	ds_bpermute_b32 v154, v154, v158
	v_pk_mul_f32 v[126:127], v[126:127], v[174:175] op_sel_hi:[1,0]
	v_pk_mul_f32 v[116:117], v[116:117], v[174:175] op_sel_hi:[1,0]
	v_pk_mul_f32 v[120:121], v[120:121], v[174:175] op_sel_hi:[1,0]
	v_pk_mul_f32 v[118:119], v[118:119], v[174:175] op_sel_hi:[1,0]
	s_waitcnt lgkmcnt(0)
	v_add_f32_e32 v154, v158, v154
	v_mov_b32_e32 v158, v201
	v_pk_mul_f32 v[122:123], v[122:123], v[174:175] op_sel_hi:[1,0]
	v_lshlrev_b32_e32 v158, 2, v158
	v_xor_b32_e32 v158, 0x80, v158
	ds_bpermute_b32 v158, v158, v154
	v_pk_mul_f32 v[112:113], v[112:113], v[174:175] op_sel_hi:[1,0]
	v_pk_mul_f32 v[114:115], v[114:115], v[174:175] op_sel_hi:[1,0]
	s_waitcnt lgkmcnt(0)
	v_add_f32_e32 v154, v154, v158
	v_fmamk_f32 v154, v154, 0x3a800000, v175
	v_rsq_f32_e32 v176, v154
	v_mov_b32_e32 v154, v201
	v_mov_b32_e32 v158, v201
	v_lshlrev_b32_e32 v154, 2, v154
	v_xor_b32_e32 v154, 64, v154
	ds_bpermute_b32 v154, v154, v161
	v_pk_mul_f32 v[110:111], v[110:111], v[176:177] op_sel_hi:[1,0]
	v_lshlrev_b32_e32 v158, 2, v158
	v_xor_b32_e32 v158, 0x80, v158
	s_waitcnt lgkmcnt(0)
	v_add_f32_e32 v154, v161, v154
	ds_bpermute_b32 v158, v158, v154
	v_pk_mul_f32 v[108:109], v[108:109], v[176:177] op_sel_hi:[1,0]
	v_pk_mul_f32 v[100:101], v[100:101], v[176:177] op_sel_hi:[1,0]
	v_pk_mul_f32 v[102:103], v[102:103], v[176:177] op_sel_hi:[1,0]
	v_pk_mul_f32 v[106:107], v[106:107], v[176:177] op_sel_hi:[1,0]
	s_waitcnt lgkmcnt(0)
	v_add_f32_e32 v154, v154, v158
	v_fmamk_f32 v154, v154, 0x3a800000, v175
	v_rsq_f32_e32 v172, v154
	v_mov_b32_e32 v154, v201
	v_pk_mul_f32 v[104:105], v[104:105], v[176:177] op_sel_hi:[1,0]
	v_lshlrev_b32_e32 v154, 2, v154
	v_xor_b32_e32 v154, 64, v154
	ds_bpermute_b32 v154, v154, v157
	v_pk_mul_f32 v[96:97], v[96:97], v[176:177] op_sel_hi:[1,0]
	v_pk_mul_f32 v[98:99], v[98:99], v[176:177] op_sel_hi:[1,0]
	v_pk_mul_f32 v[94:95], v[94:95], v[172:173] op_sel_hi:[1,0]
	v_pk_mul_f32 v[92:93], v[92:93], v[172:173] op_sel_hi:[1,0]
	s_waitcnt lgkmcnt(0)
	v_add_f32_e32 v154, v157, v154
	v_mov_b32_e32 v157, v201
	v_pk_mul_f32 v[84:85], v[84:85], v[172:173] op_sel_hi:[1,0]
	v_lshlrev_b32_e32 v157, 2, v157
	v_xor_b32_e32 v157, 0x80, v157
	ds_bpermute_b32 v157, v157, v154
	v_pk_mul_f32 v[86:87], v[86:87], v[172:173] op_sel_hi:[1,0]
	v_pk_mul_f32 v[90:91], v[90:91], v[172:173] op_sel_hi:[1,0]
	v_pk_mul_f32 v[88:89], v[88:89], v[172:173] op_sel_hi:[1,0]
	v_pk_mul_f32 v[80:81], v[80:81], v[172:173] op_sel_hi:[1,0]
	s_waitcnt lgkmcnt(0)
	v_add_f32_e32 v154, v154, v157
	v_fmamk_f32 v154, v154, 0x3a800000, v175
	v_rsq_f32_e32 v170, v154
	v_mov_b32_e32 v154, v201
	v_pk_mul_f32 v[82:83], v[82:83], v[172:173] op_sel_hi:[1,0]
	v_lshlrev_b32_e32 v154, 2, v154
	v_xor_b32_e32 v154, 64, v154
	ds_bpermute_b32 v154, v154, v153
	v_pk_mul_f32 v[78:79], v[78:79], v[170:171] op_sel_hi:[1,0]
	v_pk_mul_f32 v[76:77], v[76:77], v[170:171] op_sel_hi:[1,0]
	v_pk_mul_f32 v[68:69], v[68:69], v[170:171] op_sel_hi:[1,0]
	v_pk_mul_f32 v[70:71], v[70:71], v[170:171] op_sel_hi:[1,0]
	s_waitcnt lgkmcnt(0)
	v_add_f32_e32 v153, v153, v154
	v_mov_b32_e32 v154, v201
	v_pk_mul_f32 v[74:75], v[74:75], v[170:171] op_sel_hi:[1,0]
	v_lshlrev_b32_e32 v154, 2, v154
	v_xor_b32_e32 v154, 0x80, v154
	ds_bpermute_b32 v154, v154, v153
	v_pk_mul_f32 v[72:73], v[72:73], v[170:171] op_sel_hi:[1,0]
	v_pk_mul_f32 v[64:65], v[64:65], v[170:171] op_sel_hi:[1,0]
	v_pk_mul_f32 v[66:67], v[66:67], v[170:171] op_sel_hi:[1,0]
	s_waitcnt lgkmcnt(0)
; __device__ __forceinline__ float row_finish(float t) { t += shx(t, 16); t += shx(t, 32); return __builtin_amdgcn_rsqf(t * (1.0f / 1024.0f) + RMS_EPS); }
; __device__ __forceinline__ f32x4 silu4(f32x4 v) { return (f32x4){silu_f(v[0]), silu_f(v[1]), silu_f(v[2]), silu_f(v[3])}; }
; __device__ __forceinline__ u32x4 pack8(f32x4 a, f32x4 b) { u32x4 w; w.x = cvt_pk_bf16(a[0], a[1]); w.y = cvt_pk_bf16(a[2], a[3]); w.z = cvt_pk_bf16(b[0], b[1]); w.w = cvt_pk_bf16(b[2], b[3]); return w; }
;     __device__ __forceinline__ void operator()(const f32x4 (&acc)[2][2][4][2], const Unit& u, int wr, int wc, int fr, int fq) const {
;     ...
;             for (int m = 0; m < 4; ++m) rs[ai][m] = row_finish(rs[ai][m]);
; #pragma unroll
;         for (int ai = 0; ai < 2; ++ai)
; #pragma unroll
;             for (int m = 0; m < 4; ++m) {
;                 const int row = u.pm * BM + ai * HALF + wr * 64 + m * 16 + fr;
;                 const float rstd = rs[ai][m];
;                 const f32x4 a0 = silu4(acc[ai][0][m][0] * rstd) * (acc[ai][1][m][0] * rstd);
;                 const f32x4 a1 = silu4(acc[ai][0][m][1] * rstd) * (acc[ai][1][m][1] * rstd);
;                 *(u32x4*)(ACT + (size_t)row * 2816 + col0) = pack8(a0, a1);
;             }
	v_add_f32_e32 v153, v153, v154
	v_fmamk_f32 v153, v153, 0x3a800000, v175
	v_rsq_f32_e32 v166, v153
	v_mov_b32_e32 v153, v201
	v_pk_mul_f32 v[62:63], v[62:63], v[166:167] op_sel_hi:[1,0]
	v_lshlrev_b32_e32 v153, 2, v153
	v_xor_b32_e32 v153, 64, v153
	ds_bpermute_b32 v153, v153, v151
	v_pk_mul_f32 v[60:61], v[60:61], v[166:167] op_sel_hi:[1,0]
	v_pk_mul_f32 v[52:53], v[52:53], v[166:167] op_sel_hi:[1,0]
	v_pk_mul_f32 v[54:55], v[54:55], v[166:167] op_sel_hi:[1,0]
	v_pk_mul_f32 v[58:59], v[58:59], v[166:167] op_sel_hi:[1,0]
	s_waitcnt lgkmcnt(0)
	v_add_f32_e32 v151, v151, v153
	v_mov_b32_e32 v153, v201
	v_pk_mul_f32 v[56:57], v[56:57], v[166:167] op_sel_hi:[1,0]
	v_lshlrev_b32_e32 v153, 2, v153
	v_xor_b32_e32 v153, 0x80, v153
	ds_bpermute_b32 v153, v153, v151
	v_pk_mul_f32 v[48:49], v[48:49], v[166:167] op_sel_hi:[1,0]
	v_pk_mul_f32 v[50:51], v[50:51], v[166:167] op_sel_hi:[1,0]
	s_waitcnt lgkmcnt(0)
	v_add_f32_e32 v151, v151, v153
	v_fmamk_f32 v151, v151, 0x3a800000, v175
	v_rsq_f32_e32 v162, v151
	v_mov_b32_e32 v151, v201
	v_pk_mul_f32 v[46:47], v[46:47], v[162:163] op_sel_hi:[1,0]
	v_lshlrev_b32_e32 v151, 2, v151
	v_xor_b32_e32 v151, 64, v151
	ds_bpermute_b32 v151, v151, v149
	v_pk_mul_f32 v[44:45], v[44:45], v[162:163] op_sel_hi:[1,0]
	v_pk_mul_f32 v[36:37], v[36:37], v[162:163] op_sel_hi:[1,0]
	v_pk_mul_f32 v[38:39], v[38:39], v[162:163] op_sel_hi:[1,0]
	v_pk_mul_f32 v[42:43], v[42:43], v[162:163] op_sel_hi:[1,0]
	s_waitcnt lgkmcnt(0)
	v_add_f32_e32 v149, v149, v151
	v_mov_b32_e32 v151, v201
	v_pk_mul_f32 v[40:41], v[40:41], v[162:163] op_sel_hi:[1,0]
	v_lshlrev_b32_e32 v151, 2, v151
	v_xor_b32_e32 v151, 0x80, v151
	ds_bpermute_b32 v151, v151, v149
	v_pk_mul_f32 v[32:33], v[32:33], v[162:163] op_sel_hi:[1,0]
	v_pk_mul_f32 v[34:35], v[34:35], v[162:163] op_sel_hi:[1,0]
	s_waitcnt lgkmcnt(0)
	v_add_f32_e32 v149, v149, v151
	v_fmamk_f32 v149, v149, 0x3a800000, v175
	v_rsq_f32_e32 v158, v149
	v_mov_b32_e32 v149, v201
	v_pk_mul_f32 v[30:31], v[30:31], v[158:159] op_sel_hi:[1,0]
	v_lshlrev_b32_e32 v149, 2, v149
	v_xor_b32_e32 v149, 64, v149
	ds_bpermute_b32 v149, v149, v147
	v_pk_mul_f32 v[28:29], v[28:29], v[158:159] op_sel_hi:[1,0]
	v_pk_mul_f32 v[20:21], v[20:21], v[158:159] op_sel_hi:[1,0]
	v_pk_mul_f32 v[22:23], v[22:23], v[158:159] op_sel_hi:[1,0]
	v_pk_mul_f32 v[26:27], v[26:27], v[158:159] op_sel_hi:[1,0]
	s_waitcnt lgkmcnt(0)
	v_add_f32_e32 v147, v147, v149
	v_mov_b32_e32 v149, v201
	v_pk_mul_f32 v[24:25], v[24:25], v[158:159] op_sel_hi:[1,0]
	v_lshlrev_b32_e32 v149, 2, v149
	v_xor_b32_e32 v149, 0x80, v149
	ds_bpermute_b32 v149, v149, v147
	v_pk_mul_f32 v[16:17], v[16:17], v[158:159] op_sel_hi:[1,0]
	v_pk_mul_f32 v[18:19], v[18:19], v[158:159] op_sel_hi:[1,0]
	s_waitcnt lgkmcnt(0)
	v_add_f32_e32 v147, v147, v149
	v_fmamk_f32 v147, v147, 0x3a800000, v175
	v_rsq_f32_e32 v154, v147
	v_mul_f32_e32 v147, 0xbfb8aa3b, v124
	v_exp_f32_e32 v147, v147
	v_pk_mul_f32 v[14:15], v[14:15], v[154:155] op_sel_hi:[1,0]
	v_pk_mul_f32 v[12:13], v[12:13], v[154:155] op_sel_hi:[1,0]
	v_add_f32_e32 v147, 1.0, v147
	v_rcp_f32_e32 v180, v147
	v_mul_f32_e32 v147, 0xbfb8aa3b, v125
	v_exp_f32_e32 v147, v147
	v_pk_mul_f32 v[4:5], v[4:5], v[154:155] op_sel_hi:[1,0]
	v_pk_mul_f32 v[6:7], v[6:7], v[154:155] op_sel_hi:[1,0]
	v_pk_mul_f32 v[10:11], v[10:11], v[154:155] op_sel_hi:[1,0]
	v_add_f32_e32 v147, 1.0, v147
	v_rcp_f32_e32 v181, v147
	v_mul_f32_e32 v147, 0xbfb8aa3b, v126
	v_exp_f32_e32 v147, v147
	v_pk_mul_f32 v[8:9], v[8:9], v[154:155] op_sel_hi:[1,0]
	v_pk_mul_f32 v[124:125], v[124:125], v[180:181]
	v_pk_mul_f32 v[0:1], v[0:1], v[154:155] op_sel_hi:[1,0]
	v_add_f32_e32 v147, 1.0, v147
	v_rcp_f32_e32 v182, v147
	v_mul_f32_e32 v147, 0xbfb8aa3b, v127
	v_exp_f32_e32 v147, v147
	v_pk_mul_f32 v[116:117], v[116:117], v[124:125]
	v_mul_f32_e32 v124, 0xbfb8aa3b, v120
	v_mul_f32_e32 v125, 0xbfb8aa3b, v121
	v_add_f32_e32 v147, 1.0, v147
	v_rcp_f32_e32 v183, v147
	v_exp_f32_e32 v124, v124
	v_exp_f32_e32 v125, v125
	v_cvt_pk_bf16_f32 v116, v116, v117
	v_pk_mul_f32 v[126:127], v[126:127], v[182:183]
	v_add_f32_e32 v124, 1.0, v124
	v_pk_mul_f32 v[118:119], v[118:119], v[126:127]
	v_mul_f32_e32 v126, 0xbfb8aa3b, v122
	v_mul_f32_e32 v127, 0xbfb8aa3b, v123
	v_exp_f32_e32 v126, v126
	v_exp_f32_e32 v127, v127
	v_add_f32_e32 v125, 1.0, v125
	v_rcp_f32_e32 v124, v124
	v_rcp_f32_e32 v125, v125
	v_add_f32_e32 v126, 1.0, v126
	v_add_f32_e32 v127, 1.0, v127
	v_rcp_f32_e32 v126, v126
	v_rcp_f32_e32 v127, v127
	v_pk_mul_f32 v[120:121], v[120:121], v[124:125]
	v_cvt_pk_bf16_f32 v117, v118, v119
	v_pk_mul_f32 v[2:3], v[2:3], v[154:155] op_sel_hi:[1,0]
	v_pk_mul_f32 v[122:123], v[122:123], v[126:127]
	v_pk_mul_f32 v[112:113], v[112:113], v[120:121]
	v_pk_mul_f32 v[114:115], v[114:115], v[122:123]
	v_cvt_pk_bf16_f32 v118, v112, v113
	v_mov_b64_e32 v[112:113], s[20:21]
	v_cvt_pk_bf16_f32 v119, v114, v115
	v_mad_i64_i32 v[120:121], s[14:15], v168, s68, v[112:113]
	v_lshlrev_b64 v[114:115], 1, v[178:179]
	v_lshl_add_u64 v[120:121], v[120:121], 0, v[114:115]
	global_store_dwordx4 v[120:121], v[116:119], off
	s_nop 1
	v_mul_f32_e32 v116, 0xbfb8aa3b, v108
	v_mul_f32_e32 v117, 0xbfb8aa3b, v109
	v_mul_f32_e32 v118, 0xbfb8aa3b, v110
	v_mul_f32_e32 v119, 0xbfb8aa3b, v111
	v_exp_f32_e32 v116, v116
	v_exp_f32_e32 v117, v117
	v_exp_f32_e32 v118, v118
	v_exp_f32_e32 v119, v119
	v_add_f32_e32 v116, 1.0, v116
	v_add_f32_e32 v117, 1.0, v117
	v_add_f32_e32 v118, 1.0, v118
	v_add_f32_e32 v119, 1.0, v119
	v_rcp_f32_e32 v116, v116
	v_rcp_f32_e32 v117, v117
	v_rcp_f32_e32 v118, v118
	v_rcp_f32_e32 v119, v119
	v_pk_mul_f32 v[108:109], v[108:109], v[116:117]
	s_nop 0
	v_pk_mul_f32 v[100:101], v[100:101], v[108:109]
; __device__ __forceinline__ f32x4 silu4(f32x4 v) { return (f32x4){silu_f(v[0]), silu_f(v[1]), silu_f(v[2]), silu_f(v[3])}; }
; __device__ __forceinline__ u32x4 pack8(f32x4 a, f32x4 b) { u32x4 w; w.x = cvt_pk_bf16(a[0], a[1]); w.y = cvt_pk_bf16(a[2], a[3]); w.z = cvt_pk_bf16(b[0], b[1]); w.w = cvt_pk_bf16(b[2], b[3]); return w; }
;     __device__ __forceinline__ void operator()(const f32x4 (&acc)[2][2][4][2], const Unit& u, int wr, int wc, int fr, int fq) const {
;     ...
;         for (int ai = 0; ai < 2; ++ai)
; #pragma unroll
;             for (int m = 0; m < 4; ++m) {
;                 const int row = u.pm * BM + ai * HALF + wr * 64 + m * 16 + fr;
;                 const float rstd = rs[ai][m];
;                 const f32x4 a0 = silu4(acc[ai][0][m][0] * rstd) * (acc[ai][1][m][0] * rstd);
;                 const f32x4 a1 = silu4(acc[ai][0][m][1] * rstd) * (acc[ai][1][m][1] * rstd);
;                 *(u32x4*)(ACT + (size_t)row * 2816 + col0) = pack8(a0, a1);
;             }
	v_pk_mul_f32 v[110:111], v[110:111], v[118:119]
	v_mul_f32_e32 v108, 0xbfb8aa3b, v104
	v_pk_mul_f32 v[102:103], v[102:103], v[110:111]
	v_mul_f32_e32 v109, 0xbfb8aa3b, v105
	v_mul_f32_e32 v110, 0xbfb8aa3b, v106
	v_mul_f32_e32 v111, 0xbfb8aa3b, v107
	v_exp_f32_e32 v108, v108
	v_exp_f32_e32 v109, v109
	v_exp_f32_e32 v110, v110
	v_exp_f32_e32 v111, v111
	v_add_f32_e32 v108, 1.0, v108
	v_add_f32_e32 v109, 1.0, v109
	v_add_f32_e32 v110, 1.0, v110
	v_add_f32_e32 v111, 1.0, v111
	v_rcp_f32_e32 v108, v108
	v_rcp_f32_e32 v109, v109
	v_rcp_f32_e32 v110, v110
	v_rcp_f32_e32 v111, v111
	v_pk_mul_f32 v[104:105], v[104:105], v[108:109]
	v_pk_mul_f32 v[106:107], v[106:107], v[110:111]
	s_nop 0
	v_pk_mul_f32 v[106:107], v[98:99], v[106:107]
	v_pk_mul_f32 v[98:99], v[96:97], v[104:105]
	v_cvt_pk_bf16_f32 v96, v100, v101
	v_mad_i64_i32 v[100:101], s[14:15], v164, s68, v[112:113]
	v_cvt_pk_bf16_f32 v97, v102, v103
	v_cvt_pk_bf16_f32 v98, v98, v99
	v_cvt_pk_bf16_f32 v99, v106, v107
	v_lshl_add_u64 v[100:101], v[100:101], 0, v[114:115]
	global_store_dwordx4 v[100:101], v[96:99], off
	s_nop 1
	v_mul_f32_e32 v96, 0xbfb8aa3b, v92
	v_mul_f32_e32 v97, 0xbfb8aa3b, v93
	v_mul_f32_e32 v98, 0xbfb8aa3b, v94
	v_mul_f32_e32 v99, 0xbfb8aa3b, v95
	v_exp_f32_e32 v96, v96
	v_exp_f32_e32 v97, v97
	v_exp_f32_e32 v98, v98
	v_exp_f32_e32 v99, v99
	v_add_f32_e32 v96, 1.0, v96
	v_add_f32_e32 v97, 1.0, v97
	v_add_f32_e32 v98, 1.0, v98
	v_add_f32_e32 v99, 1.0, v99
	v_rcp_f32_e32 v96, v96
	v_rcp_f32_e32 v97, v97
	v_rcp_f32_e32 v98, v98
	v_rcp_f32_e32 v99, v99
	v_pk_mul_f32 v[92:93], v[92:93], v[96:97]
	s_nop 0
	v_pk_mul_f32 v[84:85], v[84:85], v[92:93]
	v_pk_mul_f32 v[94:95], v[94:95], v[98:99]
	v_mul_f32_e32 v92, 0xbfb8aa3b, v88
	v_pk_mul_f32 v[86:87], v[86:87], v[94:95]
	v_mul_f32_e32 v93, 0xbfb8aa3b, v89
	v_mul_f32_e32 v94, 0xbfb8aa3b, v90
	v_mul_f32_e32 v95, 0xbfb8aa3b, v91
	v_exp_f32_e32 v92, v92
	v_exp_f32_e32 v93, v93
	v_exp_f32_e32 v94, v94
	v_exp_f32_e32 v95, v95
	v_add_f32_e32 v92, 1.0, v92
	v_add_f32_e32 v93, 1.0, v93
	v_add_f32_e32 v94, 1.0, v94
	v_add_f32_e32 v95, 1.0, v95
	v_rcp_f32_e32 v92, v92
	v_rcp_f32_e32 v93, v93
	v_rcp_f32_e32 v94, v94
	v_rcp_f32_e32 v95, v95
	v_pk_mul_f32 v[88:89], v[88:89], v[92:93]
	v_pk_mul_f32 v[90:91], v[90:91], v[94:95]
	s_nop 0
	v_pk_mul_f32 v[90:91], v[82:83], v[90:91]
	v_pk_mul_f32 v[82:83], v[80:81], v[88:89]
	v_cvt_pk_bf16_f32 v80, v84, v85
	v_mad_i64_i32 v[84:85], s[14:15], v160, s68, v[112:113]
	v_cvt_pk_bf16_f32 v81, v86, v87
	v_cvt_pk_bf16_f32 v82, v82, v83
	v_cvt_pk_bf16_f32 v83, v90, v91
	v_lshl_add_u64 v[84:85], v[84:85], 0, v[114:115]
	global_store_dwordx4 v[84:85], v[80:83], off
	s_nop 1
	v_mul_f32_e32 v80, 0xbfb8aa3b, v76
	v_mul_f32_e32 v81, 0xbfb8aa3b, v77
	v_mul_f32_e32 v82, 0xbfb8aa3b, v78
	v_mul_f32_e32 v83, 0xbfb8aa3b, v79
	v_exp_f32_e32 v80, v80
	v_exp_f32_e32 v81, v81
	v_exp_f32_e32 v82, v82
	v_exp_f32_e32 v83, v83
	v_add_f32_e32 v80, 1.0, v80
	v_add_f32_e32 v81, 1.0, v81
	v_add_f32_e32 v82, 1.0, v82
	v_add_f32_e32 v83, 1.0, v83
	v_rcp_f32_e32 v80, v80
	v_rcp_f32_e32 v81, v81
	v_rcp_f32_e32 v82, v82
	v_rcp_f32_e32 v83, v83
	v_pk_mul_f32 v[76:77], v[76:77], v[80:81]
	s_nop 0
	v_pk_mul_f32 v[68:69], v[68:69], v[76:77]
	v_pk_mul_f32 v[78:79], v[78:79], v[82:83]
	v_mul_f32_e32 v76, 0xbfb8aa3b, v72
	v_pk_mul_f32 v[70:71], v[70:71], v[78:79]
	v_mul_f32_e32 v77, 0xbfb8aa3b, v73
	v_mul_f32_e32 v78, 0xbfb8aa3b, v74
	v_mul_f32_e32 v79, 0xbfb8aa3b, v75
	v_exp_f32_e32 v76, v76
	v_exp_f32_e32 v77, v77
	v_exp_f32_e32 v78, v78
	v_exp_f32_e32 v79, v79
	v_add_f32_e32 v76, 1.0, v76
	v_add_f32_e32 v77, 1.0, v77
	v_add_f32_e32 v78, 1.0, v78
	v_add_f32_e32 v79, 1.0, v79
	v_rcp_f32_e32 v76, v76
	v_rcp_f32_e32 v77, v77
	v_rcp_f32_e32 v78, v78
	v_rcp_f32_e32 v79, v79
	v_pk_mul_f32 v[72:73], v[72:73], v[76:77]
	v_pk_mul_f32 v[74:75], v[74:75], v[78:79]
	s_nop 0
	v_pk_mul_f32 v[74:75], v[66:67], v[74:75]
	v_pk_mul_f32 v[66:67], v[64:65], v[72:73]
	v_cvt_pk_bf16_f32 v64, v68, v69
	v_mad_i64_i32 v[68:69], s[14:15], v156, s68, v[112:113]
	v_cvt_pk_bf16_f32 v65, v70, v71
	v_cvt_pk_bf16_f32 v66, v66, v67
	v_cvt_pk_bf16_f32 v67, v74, v75
	v_lshl_add_u64 v[68:69], v[68:69], 0, v[114:115]
	global_store_dwordx4 v[68:69], v[64:67], off
	s_branch .Lhh1_epi_end
; __device__ __forceinline__ f32x4 silu4(f32x4 v) { return (f32x4){silu_f(v[0]), silu_f(v[1]), silu_f(v[2]), silu_f(v[3])}; }
; __device__ __forceinline__ u32x4 pack8(f32x4 a, f32x4 b) { u32x4 w; w.x = cvt_pk_bf16(a[0], a[1]); w.y = cvt_pk_bf16(a[2], a[3]); w.z = cvt_pk_bf16(b[0], b[1]); w.w = cvt_pk_bf16(b[2], b[3]); return w; }
;     __device__ __forceinline__ void operator()(const f32x4 (&acc)[2][2][4][2], const Unit& u, int wr, int wc, int fr, int fq) const {
;     ...
;         for (int ai = 0; ai < 2; ++ai)
; #pragma unroll
;             for (int m = 0; m < 4; ++m) {
;                 const int row = u.pm * BM + ai * HALF + wr * 64 + m * 16 + fr;
;                 const float rstd = rs[ai][m];
;                 const f32x4 a0 = silu4(acc[ai][0][m][0] * rstd) * (acc[ai][1][m][0] * rstd);
;                 const f32x4 a1 = silu4(acc[ai][0][m][1] * rstd) * (acc[ai][1][m][1] * rstd);
;                 *(u32x4*)(ACT + (size_t)row * 2816 + col0) = pack8(a0, a1);
;             }
; template <class Epi, class Sched, bool ALIGN_EPI = false, bool SP2 = false>
; __device__ __forceinline__ void gemm_phase(PG8_LAS unsigned char* lds, const Gemm g, const Sched& S, const Epi& E, int tid_in) {
;     ...
;         if constexpr (!Epi::AFTER_DRAIN) { E(acc, cur, wr, wc, fr, fq); S.done(cur); }
;         if (!has_next) break;
	s_nop 1
	v_mul_f32_e32 v64, 0xbfb8aa3b, v60
	v_mul_f32_e32 v65, 0xbfb8aa3b, v61
	v_mul_f32_e32 v66, 0xbfb8aa3b, v62
	v_mul_f32_e32 v67, 0xbfb8aa3b, v63
	v_exp_f32_e32 v64, v64
	v_exp_f32_e32 v65, v65
	v_exp_f32_e32 v66, v66
	v_exp_f32_e32 v67, v67
	v_add_f32_e32 v64, 1.0, v64
	v_add_f32_e32 v65, 1.0, v65
	v_add_f32_e32 v66, 1.0, v66
	v_add_f32_e32 v67, 1.0, v67
	v_rcp_f32_e32 v64, v64
	v_rcp_f32_e32 v65, v65
	v_rcp_f32_e32 v66, v66
	v_rcp_f32_e32 v67, v67
	v_pk_mul_f32 v[60:61], v[60:61], v[64:65]
	s_nop 0
	v_pk_mul_f32 v[52:53], v[52:53], v[60:61]
	v_pk_mul_f32 v[62:63], v[62:63], v[66:67]
	v_mul_f32_e32 v60, 0xbfb8aa3b, v56
	v_pk_mul_f32 v[54:55], v[54:55], v[62:63]
	v_mul_f32_e32 v61, 0xbfb8aa3b, v57
	v_mul_f32_e32 v62, 0xbfb8aa3b, v58
	v_mul_f32_e32 v63, 0xbfb8aa3b, v59
	v_exp_f32_e32 v60, v60
	v_exp_f32_e32 v61, v61
	v_exp_f32_e32 v62, v62
	v_exp_f32_e32 v63, v63
	v_add_f32_e32 v60, 1.0, v60
	v_add_f32_e32 v61, 1.0, v61
	v_add_f32_e32 v62, 1.0, v62
	v_add_f32_e32 v63, 1.0, v63
	v_rcp_f32_e32 v60, v60
	v_rcp_f32_e32 v61, v61
	v_rcp_f32_e32 v62, v62
	v_rcp_f32_e32 v63, v63
	v_pk_mul_f32 v[56:57], v[56:57], v[60:61]
	v_pk_mul_f32 v[58:59], v[58:59], v[62:63]
	s_nop 0
	v_pk_mul_f32 v[58:59], v[50:51], v[58:59]
	v_pk_mul_f32 v[50:51], v[48:49], v[56:57]
	v_cvt_pk_bf16_f32 v48, v52, v53
	v_mad_i64_i32 v[52:53], s[14:15], v152, s68, v[112:113]
	v_cvt_pk_bf16_f32 v49, v54, v55
	v_cvt_pk_bf16_f32 v50, v50, v51
	v_cvt_pk_bf16_f32 v51, v58, v59
	v_lshl_add_u64 v[52:53], v[52:53], 0, v[114:115]
	global_store_dwordx4 v[52:53], v[48:51], off
	s_nop 1
	v_mul_f32_e32 v48, 0xbfb8aa3b, v44
	v_mul_f32_e32 v49, 0xbfb8aa3b, v45
	v_mul_f32_e32 v50, 0xbfb8aa3b, v46
	v_mul_f32_e32 v51, 0xbfb8aa3b, v47
	v_exp_f32_e32 v48, v48
	v_exp_f32_e32 v49, v49
	v_exp_f32_e32 v50, v50
	v_exp_f32_e32 v51, v51
	v_add_f32_e32 v48, 1.0, v48
	v_add_f32_e32 v49, 1.0, v49
	v_add_f32_e32 v50, 1.0, v50
	v_add_f32_e32 v51, 1.0, v51
	v_rcp_f32_e32 v48, v48
	v_rcp_f32_e32 v49, v49
	v_rcp_f32_e32 v50, v50
	v_rcp_f32_e32 v51, v51
	v_pk_mul_f32 v[44:45], v[44:45], v[48:49]
	s_nop 0
	v_pk_mul_f32 v[36:37], v[36:37], v[44:45]
	v_pk_mul_f32 v[46:47], v[46:47], v[50:51]
	v_mul_f32_e32 v44, 0xbfb8aa3b, v40
	v_pk_mul_f32 v[38:39], v[38:39], v[46:47]
	v_mul_f32_e32 v45, 0xbfb8aa3b, v41
	v_mul_f32_e32 v46, 0xbfb8aa3b, v42
	v_mul_f32_e32 v47, 0xbfb8aa3b, v43
	v_exp_f32_e32 v44, v44
	v_exp_f32_e32 v45, v45
	v_exp_f32_e32 v46, v46
	v_exp_f32_e32 v47, v47
	v_add_f32_e32 v44, 1.0, v44
	v_add_f32_e32 v45, 1.0, v45
	v_add_f32_e32 v46, 1.0, v46
	v_add_f32_e32 v47, 1.0, v47
	v_rcp_f32_e32 v44, v44
	v_rcp_f32_e32 v45, v45
	v_rcp_f32_e32 v46, v46
	v_rcp_f32_e32 v47, v47
	v_pk_mul_f32 v[40:41], v[40:41], v[44:45]
	v_pk_mul_f32 v[42:43], v[42:43], v[46:47]
	s_nop 0
	v_pk_mul_f32 v[42:43], v[34:35], v[42:43]
	v_pk_mul_f32 v[34:35], v[32:33], v[40:41]
	v_cvt_pk_bf16_f32 v32, v36, v37
	v_mad_i64_i32 v[36:37], s[14:15], v150, s68, v[112:113]
	v_cvt_pk_bf16_f32 v33, v38, v39
	v_cvt_pk_bf16_f32 v34, v34, v35
	v_cvt_pk_bf16_f32 v35, v42, v43
	v_lshl_add_u64 v[36:37], v[36:37], 0, v[114:115]
	global_store_dwordx4 v[36:37], v[32:35], off
	s_nop 1
	v_mul_f32_e32 v32, 0xbfb8aa3b, v28
	v_mul_f32_e32 v33, 0xbfb8aa3b, v29
	v_mul_f32_e32 v34, 0xbfb8aa3b, v30
	v_mul_f32_e32 v35, 0xbfb8aa3b, v31
	v_exp_f32_e32 v32, v32
	v_exp_f32_e32 v33, v33
	v_exp_f32_e32 v34, v34
	v_exp_f32_e32 v35, v35
	v_add_f32_e32 v32, 1.0, v32
	v_add_f32_e32 v33, 1.0, v33
	v_add_f32_e32 v34, 1.0, v34
	v_add_f32_e32 v35, 1.0, v35
	v_rcp_f32_e32 v32, v32
	v_rcp_f32_e32 v33, v33
	v_rcp_f32_e32 v34, v34
	v_rcp_f32_e32 v35, v35
	v_pk_mul_f32 v[28:29], v[28:29], v[32:33]
	s_nop 0
	v_pk_mul_f32 v[20:21], v[20:21], v[28:29]
	v_pk_mul_f32 v[30:31], v[30:31], v[34:35]
	v_mul_f32_e32 v28, 0xbfb8aa3b, v24
	v_pk_mul_f32 v[22:23], v[22:23], v[30:31]
	v_mul_f32_e32 v29, 0xbfb8aa3b, v25
	v_mul_f32_e32 v30, 0xbfb8aa3b, v26
	v_mul_f32_e32 v31, 0xbfb8aa3b, v27
	v_exp_f32_e32 v28, v28
	v_exp_f32_e32 v29, v29
	v_exp_f32_e32 v30, v30
	v_exp_f32_e32 v31, v31
	v_add_f32_e32 v28, 1.0, v28
	v_add_f32_e32 v29, 1.0, v29
	v_add_f32_e32 v30, 1.0, v30
	v_add_f32_e32 v31, 1.0, v31
	v_rcp_f32_e32 v28, v28
	v_rcp_f32_e32 v29, v29
	v_rcp_f32_e32 v30, v30
	v_rcp_f32_e32 v31, v31
	v_pk_mul_f32 v[24:25], v[24:25], v[28:29]
	v_pk_mul_f32 v[26:27], v[26:27], v[30:31]
	s_nop 0
	v_pk_mul_f32 v[26:27], v[18:19], v[26:27]
	v_pk_mul_f32 v[18:19], v[16:17], v[24:25]
	v_cvt_pk_bf16_f32 v16, v20, v21
	v_mad_i64_i32 v[20:21], s[14:15], v148, s68, v[112:113]
	v_cvt_pk_bf16_f32 v17, v22, v23
	v_cvt_pk_bf16_f32 v18, v18, v19
	v_cvt_pk_bf16_f32 v19, v26, v27
	v_lshl_add_u64 v[20:21], v[20:21], 0, v[114:115]
	global_store_dwordx4 v[20:21], v[16:19], off
	s_nop 1
	v_mul_f32_e32 v16, 0xbfb8aa3b, v12
	v_mul_f32_e32 v17, 0xbfb8aa3b, v13
	v_mul_f32_e32 v18, 0xbfb8aa3b, v14
	v_mul_f32_e32 v19, 0xbfb8aa3b, v15
	v_exp_f32_e32 v16, v16
	v_exp_f32_e32 v17, v17
	v_exp_f32_e32 v18, v18
	v_exp_f32_e32 v19, v19
	v_add_f32_e32 v16, 1.0, v16
	v_add_f32_e32 v17, 1.0, v17
	v_add_f32_e32 v18, 1.0, v18
	v_add_f32_e32 v19, 1.0, v19
	v_rcp_f32_e32 v16, v16
	v_rcp_f32_e32 v17, v17
	v_rcp_f32_e32 v18, v18
	v_rcp_f32_e32 v19, v19
	v_pk_mul_f32 v[12:13], v[12:13], v[16:17]
	s_nop 0
	v_pk_mul_f32 v[4:5], v[4:5], v[12:13]
	v_pk_mul_f32 v[14:15], v[14:15], v[18:19]
	v_mul_f32_e32 v12, 0xbfb8aa3b, v8
	v_pk_mul_f32 v[6:7], v[6:7], v[14:15]
	v_mul_f32_e32 v13, 0xbfb8aa3b, v9
	v_mul_f32_e32 v14, 0xbfb8aa3b, v10
	v_mul_f32_e32 v15, 0xbfb8aa3b, v11
	v_exp_f32_e32 v12, v12
	v_exp_f32_e32 v13, v13
	v_exp_f32_e32 v14, v14
	v_exp_f32_e32 v15, v15
	v_add_f32_e32 v12, 1.0, v12
	v_add_f32_e32 v13, 1.0, v13
	v_add_f32_e32 v14, 1.0, v14
	v_add_f32_e32 v15, 1.0, v15
	v_rcp_f32_e32 v12, v12
	v_rcp_f32_e32 v13, v13
	v_rcp_f32_e32 v14, v14
	v_rcp_f32_e32 v15, v15
	v_pk_mul_f32 v[8:9], v[8:9], v[12:13]
	v_pk_mul_f32 v[10:11], v[10:11], v[14:15]
	s_nop 0
	v_pk_mul_f32 v[10:11], v[2:3], v[10:11]
	v_pk_mul_f32 v[2:3], v[0:1], v[8:9]
	v_cvt_pk_bf16_f32 v0, v4, v5
	v_mad_i64_i32 v[4:5], s[14:15], v146, s68, v[112:113]
	v_lshl_add_u64 v[4:5], v[4:5], 0, v[114:115]
	v_cvt_pk_bf16_f32 v1, v6, v7
	v_cvt_pk_bf16_f32 v2, v2, v3
	v_cvt_pk_bf16_f32 v3, v10, v11
	global_store_dwordx4 v[4:5], v[0:3], off
.Lhh1_epi_end:
	s_cbranch_vccnz .LBB0_992
	s_andn2_b64 vcc, exec, s[18:19]
	s_cbranch_vccnz .LBB0_991
	s_barrier
	s_branch .LBB0_991

;     __device__ bool next(int i, Unit& u) const { if (i > 0) return false; const int t = c - first; if (t < 0 || t >= nM * nN) return false; u.pm = t % nM; u.pn = t / nM; return true; }
;     __host__ __device__ bool next(int i, Unit& u) const {
;         const long L = (long)i * G + c; if (L >= nwg) return false;
;         int wgid = (int)L; { const int q = nwg / NXCD, r = nwg % NXCD, xcd = wgid % NXCD, off = wgid / NXCD; wgid = (xcd < r ? xcd * (q + 1) : r * (q + 1) + (xcd - r) * q) + off; }
;         const int nig = WGM * nN, gid = wgid / nig, fm = gid * WGM, gsz = (nM - fm) < WGM ? (nM - fm) : WGM;
;         u.pm = fm + ((wgid % nig) % gsz); u.pn = (wgid % nig) / gsz; return true;
;     }
; template <class Epi, class Sched, bool ALIGN_EPI = false, bool SP2 = false>
; __device__ __forceinline__ void gemm_phase(PG8_LAS unsigned char* lds, const Gemm g, const Sched& S, const Epi& E, int tid_in) {
;     ...
; #pragma unroll
;         for (int a = 0; a < 2; ++a)
; #pragma unroll
;             for (int b = 0; b < 2; ++b)
; #pragma unroll
;                 for (int m = 0; m < 4; ++m)
; #pragma unroll
;                     for (int n = 0; n < 2; ++n) acc[a][b][m][n] = (f32x4){0.f, 0.f, 0.f, 0.f};
;         cur = nxt; cA = nA; cB = nB; ++ui;
.LBB0_1585:
	s_add_i32 s53, s53, 1
	s_mul_i32 s4, s53, s56
	s_mul_hi_u32 s5, s53, s57
	s_add_i32 s5, s5, s4
	s_mul_i32 s4, s53, s57
	s_add_u32 s26, s4, s2
	s_addc_u32 s27, s5, s13
	s_cmp_ge_u32 s26, 0x580
	s_cselect_b32 s99, 0x40000, 0
	s_cselect_b32 s98, 0x80, 0
	s_sub_u32 s26, s26, s98
	v_cmp_gt_i64_e32 vcc, s[26:27], v[144:145]
	v_cmp_lt_i64_e64 s[8:9], s[26:27], v[142:143]
	s_cbranch_vccnz .LBB0_1587
	s_ashr_i32 s4, s26, 31
	s_lshr_b32 s4, s4, 29
	s_add_i32 s4, s26, s4
	s_ashr_i32 s5, s4, 3
	s_and_b32 s4, s4, -8
	s_sub_i32 s4, s26, s4
	s_cmp_lt_i32 s4, 0
	s_cselect_b32 s22, s33, 0xb0
	s_mul_i32 s4, s22, s4
	s_add_i32 s4, s4, s5
	s_mul_hi_i32 s5, s4, 0x2e8ba2e9
	s_lshr_b32 s22, s5, 31
	s_ashr_i32 s5, s5, 5
	s_add_i32 s5, s5, s22
	s_lshl_b32 s23, s5, 3
	s_sub_i32 s22, 64, s23
	s_min_i32 s24, s22, 8
	s_abs_i32 s22, s24
	v_cvt_f32_u32_e32 v0, s22
	s_sub_i32 s26, 0, s22
	s_mulk_i32 s5, 0xb0
	s_sub_i32 s4, s4, s5
	v_rcp_iflag_f32_e32 v0, v0
	s_abs_i32 s5, s4
	s_xor_b32 s25, s4, s24
	s_ashr_i32 s25, s25, 31
	v_mul_f32_e32 v0, 0x4f7ffffe, v0
	v_cvt_u32_f32_e32 v0, v0
	s_nop 0
	v_readfirstlane_b32 s27, v0
	s_mul_i32 s26, s26, s27
	s_mul_hi_u32 s26, s27, s26
	s_add_i32 s27, s27, s26
	s_mul_hi_u32 s26, s5, s27
	s_mul_i32 s27, s26, s22
	s_sub_i32 s5, s5, s27
	s_add_i32 s42, s26, 1
	s_sub_i32 s27, s5, s22
	s_cmp_ge_u32 s5, s22
	s_cselect_b32 s26, s42, s26
	s_cselect_b32 s5, s27, s5
	s_add_i32 s27, s26, 1
	s_cmp_ge_u32 s5, s22
	s_cselect_b32 s5, s27, s26
	s_xor_b32 s5, s5, s25
	s_sub_i32 s22, s5, s25
	s_mul_i32 s5, s22, s24
	s_sub_i32 s4, s4, s5
	s_add_i32 s24, s4, s23
.LBB0_1587:
	s_ashr_i32 s25, s24, 31
	s_lshl_b64 s[26:27], s[24:25], 19
	s_add_u32 s26, s0, s26
	s_addc_u32 s27, s3, s27
	s_add_u32 s26, s26, s99
	s_addc_u32 s27, s27, 0
	s_and_b64 s[42:43], s[8:9], exec
	s_cselect_b32 s25, s27, s49
	s_cselect_b32 s62, s26, s48
	s_ashr_i32 s23, s22, 31
	s_lshl_b64 s[42:43], s[22:23], 19
	s_add_u32 s42, s6, s42
	s_addc_u32 s43, s7, s43
	s_and_b64 s[50:51], s[8:9], exec
	s_cselect_b32 s23, s43, s47
	s_cselect_b32 s63, s42, s46
	s_add_u32 s64, s46, 0x100
	s_addc_u32 s65, s47, 0
	s_add_u32 s46, s48, 0x40080
	v_mov_b32_e32 v0, 0
	s_addc_u32 s47, s49, 0
	s_mov_b32 s66, -2
	v_mov_b32_e32 v1, v0
	v_mov_b32_e32 v2, v0
	v_mov_b32_e32 v3, v0
	v_mov_b32_e32 v4, v0
	v_mov_b32_e32 v5, v0
	v_mov_b32_e32 v6, v0
	v_mov_b32_e32 v7, v0
	v_mov_b32_e32 v16, v0
	v_mov_b32_e32 v17, v0
	v_mov_b32_e32 v18, v0
	v_mov_b32_e32 v19, v0
	v_mov_b32_e32 v20, v0
	v_mov_b32_e32 v21, v0
	v_mov_b32_e32 v22, v0
	v_mov_b32_e32 v23, v0
	v_mov_b32_e32 v32, v0
	v_mov_b32_e32 v33, v0
	v_mov_b32_e32 v34, v0
	v_mov_b32_e32 v35, v0
	v_mov_b32_e32 v36, v0
	v_mov_b32_e32 v37, v0
	v_mov_b32_e32 v38, v0
	v_mov_b32_e32 v39, v0
	v_mov_b32_e32 v48, v0
	v_mov_b32_e32 v49, v0
	v_mov_b32_e32 v50, v0
	v_mov_b32_e32 v51, v0
	v_mov_b32_e32 v52, v0
	v_mov_b32_e32 v53, v0
	v_mov_b32_e32 v54, v0
	v_mov_b32_e32 v55, v0
	v_mov_b32_e32 v8, v0
	v_mov_b32_e32 v9, v0
	v_mov_b32_e32 v10, v0
	v_mov_b32_e32 v11, v0
	v_mov_b32_e32 v12, v0
	v_mov_b32_e32 v13, v0
	v_mov_b32_e32 v14, v0
	v_mov_b32_e32 v15, v0
	v_mov_b32_e32 v24, v0
	v_mov_b32_e32 v25, v0
	v_mov_b32_e32 v26, v0
	v_mov_b32_e32 v27, v0
	v_mov_b32_e32 v28, v0
	v_mov_b32_e32 v29, v0
	v_mov_b32_e32 v30, v0
	v_mov_b32_e32 v31, v0
	v_mov_b32_e32 v40, v0
	v_mov_b32_e32 v41, v0
	v_mov_b32_e32 v42, v0
	v_mov_b32_e32 v43, v0
	v_mov_b32_e32 v44, v0
	v_mov_b32_e32 v45, v0
	v_mov_b32_e32 v46, v0
	v_mov_b32_e32 v47, v0
	v_mov_b32_e32 v56, v0
	v_mov_b32_e32 v57, v0
	v_mov_b32_e32 v58, v0
	v_mov_b32_e32 v59, v0
	v_mov_b32_e32 v60, v0
	v_mov_b32_e32 v61, v0
	v_mov_b32_e32 v62, v0
	v_mov_b32_e32 v63, v0
	v_mov_b32_e32 v64, v0
	v_mov_b32_e32 v65, v0
	v_mov_b32_e32 v66, v0
	v_mov_b32_e32 v67, v0
	v_mov_b32_e32 v68, v0
	v_mov_b32_e32 v69, v0
	v_mov_b32_e32 v70, v0
	v_mov_b32_e32 v71, v0
	v_mov_b32_e32 v80, v0
	v_mov_b32_e32 v81, v0
	v_mov_b32_e32 v82, v0
	v_mov_b32_e32 v83, v0
	v_mov_b32_e32 v84, v0
	v_mov_b32_e32 v85, v0
	v_mov_b32_e32 v86, v0
	v_mov_b32_e32 v87, v0
	v_mov_b32_e32 v96, v0
	v_mov_b32_e32 v97, v0
	v_mov_b32_e32 v98, v0
	v_mov_b32_e32 v99, v0
	v_mov_b32_e32 v100, v0
	v_mov_b32_e32 v101, v0
	v_mov_b32_e32 v102, v0
	v_mov_b32_e32 v103, v0
	v_mov_b32_e32 v112, v0
	v_mov_b32_e32 v113, v0
	v_mov_b32_e32 v114, v0
	v_mov_b32_e32 v115, v0
	v_mov_b32_e32 v116, v0
	v_mov_b32_e32 v117, v0
	v_mov_b32_e32 v118, v0
	v_mov_b32_e32 v119, v0
	v_mov_b32_e32 v72, v0
	v_mov_b32_e32 v73, v0
	v_mov_b32_e32 v74, v0
	v_mov_b32_e32 v75, v0
	v_mov_b32_e32 v76, v0
	v_mov_b32_e32 v77, v0
	v_mov_b32_e32 v78, v0
	v_mov_b32_e32 v79, v0
	v_mov_b32_e32 v88, v0
	v_mov_b32_e32 v89, v0
	v_mov_b32_e32 v90, v0
	v_mov_b32_e32 v91, v0
	v_mov_b32_e32 v92, v0
	v_mov_b32_e32 v93, v0
	v_mov_b32_e32 v94, v0
	v_mov_b32_e32 v95, v0
	v_mov_b32_e32 v104, v0
	v_mov_b32_e32 v105, v0
	v_mov_b32_e32 v106, v0
	v_mov_b32_e32 v107, v0
	v_mov_b32_e32 v108, v0
	v_mov_b32_e32 v109, v0
	v_mov_b32_e32 v110, v0
	v_mov_b32_e32 v111, v0
	v_mov_b32_e32 v120, v0
	v_mov_b32_e32 v121, v0
	v_mov_b32_e32 v122, v0
	v_mov_b32_e32 v123, v0
	v_mov_b32_e32 v124, v0
	v_mov_b32_e32 v125, v0
	v_mov_b32_e32 v126, v0
	v_mov_b32_e32 v127, v0
	v_readlane_b32 s98, v252, 5
	s_nop 1
	s_lshl_b32 s98, s98, 5
	s_add_i32 m0, s98, 0x20080
	s_lshl_b32 s98, s44, 14
	s_add_u32 s98, s100, s98
	s_addc_u32 s99, s101, 0
	global_load_lds_dwordx4 v238, s[98:99]
	global_load_lds_dwordx4 v238, s[98:99] offset:1024
	s_cmp_eq_u32 s53, 6
	s_cbranch_scc1 .Lhh2_1588

; #define PG8_STAGE(bufoff, gbase, voff) do { _Pragma("unroll") for (int _i = 0; _i < 2; ++_i) \
;         __builtin_amdgcn_global_load_lds((const unsigned*)((const char*)(gbase) + (voff)[_i]), (PG8_LAS unsigned*)(lds + (bufoff) + ldsw + _i * 8192), 16, 0, 0); } while (0)
; #define PG8_LDA(dst, b, h) do { _Pragma("unroll") for (int m = 0; m < 4; ++m) _Pragma("unroll") for (int k = 0; k < 2; ++k) dst[m][k] = *(const PG8_LAS bf16x8*)(lds + PG8_SA(b, h) + aoff + m * 2048 + k * 1024); } while (0)
; #define PG8_WAIT_V(n) asm volatile("s_waitcnt vmcnt(" #n ")" ::: "memory")
; #define PG8_WAIT_L(n) asm volatile("s_waitcnt lgkmcnt(" #n ")" ::: "memory")
; #define PG8_BAR __builtin_amdgcn_s_barrier()
; template <class Epi, class Sched, bool ALIGN_EPI = false, bool SP2 = false>
; __device__ __forceinline__ void gemm_phase(PG8_LAS unsigned char* lds, const Gemm g, const Sched& S, const Epi& E, int tid_in) {
;     ...
;         for (int t = 0; t < nt; t += 2) {
;             const bool last = (t == nt - 2);
;             const char* a1 = cA + (size_t)(t + 1) * kstep;
;             const char* a2 = last ? nA : cA + (size_t)(t + 2) * kstep; const char* b2 = last ? nB : cB + (size_t)(t + 2) * kstep;
;             const char* a3 = a2 + kstep; const char* b3 = b2 + kstep;
;             if (last && has_next) S.a_ready(nxt);
;             if constexpr (SP2) {
;             PG8_LDB(B0, 0, 0); PG8_LDB(B1, 0, 1); PG8_SCHED; PG8_LDA(At, 0, 0); PG8_STAGE(PG8_SA(1, 1), a1 + hstep, voffA);
;             PG8_WAIT_V(8); PG8_WAIT_L(0); PG8_BAR; PG8_MMA(0, 0, At, B0); PG8_MMA(0, 1, At, B1); PG8_BAR; PG8_SCHED;
;             PG8_LDA(At, 0, 1); PG8_STAGE(PG8_SB(0, 0), b2, voffB); PG8_STAGE(PG8_SB(0, 1), b2 + hstep, voffB); PG8_STAGE(PG8_SA(0, 0), a2, voffA);
;             PG8_WAIT_V(8); PG8_WAIT_L(0); PG8_BAR; PG8_MMA(1, 0, At, B0); PG8_MMA(1, 1, At, B1); PG8_BAR; PG8_SCHED;
;             PG8_LDB(B0, 1, 0); PG8_LDB(B1, 1, 1); PG8_SCHED; PG8_LDA(At, 1, 0); PG8_STAGE(PG8_SA(0, 1), a2 + hstep, voffA);
;             PG8_WAIT_V(8); PG8_WAIT_L(0); PG8_BAR; PG8_MMA(0, 0, At, B0); PG8_MMA(0, 1, At, B1); PG8_BAR; PG8_SCHED;
;             PG8_LDA(At, 1, 1); PG8_STAGE(PG8_SB(1, 0), b3, voffB); PG8_STAGE(PG8_SB(1, 1), b3 + hstep, voffB); PG8_STAGE(PG8_SA(1, 0), a3, voffA);
;             PG8_WAIT_V(8); PG8_WAIT_L(0); PG8_BAR; PG8_MMA(1, 0, At, B0); PG8_MMA(1, 1, At, B1); PG8_BAR; PG8_SCHED;
.Lhh2_1588:
	ds_read_b128 v[146:149], v165
	ds_read_b128 v[176:179], v165 offset:1024
	ds_read_b128 v[180:183], v165 offset:2048
	ds_read_b128 v[184:187], v165 offset:3072
	ds_read_b128 v[188:191], v169
	ds_read_b128 v[192:195], v169 offset:1024
	ds_read_b128 v[196:199], v169 offset:2048
	ds_read_b128 v[202:205], v169 offset:3072
	s_add_u32 s4, s46, 0xfffc0080
	s_addc_u32 s5, s47, -1
	s_cmp_eq_u32 s66, 12
	s_cselect_b32 s51, s25, s5
	s_cselect_b32 s50, s62, s4
	s_cselect_b32 s49, s23, s65
	s_cselect_b32 s48, s63, s64
	v_lshl_add_u64 v[150:151], s[46:47], 0, v[140:141]
	s_add_i32 m0, s40, 0xc000
	ds_read_b128 v[206:209], v173
	ds_read_b128 v[210:213], v173 offset:1024
	ds_read_b128 v[214:217], v173 offset:2048
	ds_read_b128 v[218:221], v173 offset:3072
	ds_read_b128 v[222:225], v173 offset:4096
	ds_read_b128 v[226:229], v173 offset:5120
	ds_read_b128 v[230:233], v173 offset:6144
	ds_read_b128 v[234:237], v173 offset:7168
	global_load_lds_dwordx4 v[150:151], off
	v_lshl_add_u64 v[150:151], s[46:47], 0, v[138:139]
	s_add_i32 m0, s40, 0xe000
	s_nop 0
	global_load_lds_dwordx4 v[150:151], off
	s_waitcnt vmcnt(8)
	s_waitcnt lgkmcnt(0)
	s_barrier
	s_setprio 1
	s_waitcnt lgkmcnt(0)
	v_mfma_f32_16x16x32_bf16 v[124:127], v[146:149], v[206:209], v[124:127]
	v_mfma_f32_16x16x32_bf16 v[120:123], v[180:183], v[206:209], v[120:123]
	v_mfma_f32_16x16x32_bf16 v[108:111], v[146:149], v[214:217], v[108:111]
	v_mfma_f32_16x16x32_bf16 v[104:107], v[180:183], v[214:217], v[104:107]
	v_mfma_f32_16x16x32_bf16 v[92:95], v[146:149], v[222:225], v[92:95]
	v_mfma_f32_16x16x32_bf16 v[88:91], v[180:183], v[222:225], v[88:91]
	v_mfma_f32_16x16x32_bf16 v[76:79], v[146:149], v[230:233], v[76:79]
	v_mfma_f32_16x16x32_bf16 v[72:75], v[180:183], v[230:233], v[72:75]
	v_mfma_f32_16x16x32_bf16 v[124:127], v[176:179], v[210:213], v[124:127]
	v_mfma_f32_16x16x32_bf16 v[120:123], v[184:187], v[210:213], v[120:123]
	v_mfma_f32_16x16x32_bf16 v[108:111], v[176:179], v[218:221], v[108:111]
	v_mfma_f32_16x16x32_bf16 v[104:107], v[184:187], v[218:221], v[104:107]
	v_mfma_f32_16x16x32_bf16 v[92:95], v[176:179], v[226:229], v[92:95]
	v_mfma_f32_16x16x32_bf16 v[88:91], v[184:187], v[226:229], v[88:91]
	v_mfma_f32_16x16x32_bf16 v[76:79], v[176:179], v[234:237], v[76:79]
	v_mfma_f32_16x16x32_bf16 v[72:75], v[184:187], v[234:237], v[72:75]
	s_setprio 0
	s_setprio 1
	v_mfma_f32_16x16x32_bf16 v[116:119], v[188:191], v[206:209], v[116:119]
	v_mfma_f32_16x16x32_bf16 v[112:115], v[196:199], v[206:209], v[112:115]
	v_mfma_f32_16x16x32_bf16 v[100:103], v[188:191], v[214:217], v[100:103]
	v_mfma_f32_16x16x32_bf16 v[96:99], v[196:199], v[214:217], v[96:99]
	v_mfma_f32_16x16x32_bf16 v[84:87], v[188:191], v[222:225], v[84:87]
	v_mfma_f32_16x16x32_bf16 v[80:83], v[196:199], v[222:225], v[80:83]
	v_mfma_f32_16x16x32_bf16 v[68:71], v[188:191], v[230:233], v[68:71]
	v_mfma_f32_16x16x32_bf16 v[64:67], v[196:199], v[230:233], v[64:67]
	v_mfma_f32_16x16x32_bf16 v[116:119], v[192:195], v[210:213], v[116:119]
	v_mfma_f32_16x16x32_bf16 v[112:115], v[202:205], v[210:213], v[112:115]
	v_mfma_f32_16x16x32_bf16 v[100:103], v[192:195], v[218:221], v[100:103]
	v_mfma_f32_16x16x32_bf16 v[96:99], v[202:205], v[218:221], v[96:99]
	v_mfma_f32_16x16x32_bf16 v[84:87], v[192:195], v[226:229], v[84:87]
	v_mfma_f32_16x16x32_bf16 v[80:83], v[202:205], v[226:229], v[80:83]
	v_mfma_f32_16x16x32_bf16 v[68:71], v[192:195], v[234:237], v[68:71]
	v_mfma_f32_16x16x32_bf16 v[64:67], v[202:205], v[234:237], v[64:67]
	s_setprio 0
	s_barrier
	s_add_i32 s4, s58, s12
	v_lshl_add_u64 v[150:151], s[48:49], 0, v[132:133]
	s_mov_b32 m0, s4
	s_nop 0
	global_load_lds_dwordx4 v[150:151], off
	s_add_i32 m0, s4, 0x2000
	s_add_u32 s68, s48, 0x40000
	v_lshl_add_u64 v[154:155], s[48:49], 0, v[128:129]
	s_addc_u32 s69, s49, 0
	s_add_i32 s4, s59, s12
	global_load_lds_dwordx4 v[154:155], off
	v_lshl_add_u64 v[158:159], s[68:69], 0, v[132:133]
	s_mov_b32 m0, s4
	v_lshl_add_u64 v[162:163], s[50:51], 0, v[130:131]
	global_load_lds_dwordx4 v[158:159], off
	v_lshl_add_u64 v[158:159], s[68:69], 0, v[128:129]
	s_add_i32 m0, s4, 0x2000
	s_nop 0
	global_load_lds_dwordx4 v[158:159], off
	v_lshl_add_u64 v[158:159], s[50:51], 0, v[134:135]
	s_mov_b32 m0, s40
	s_nop 0
	global_load_lds_dwordx4 v[158:159], off
	s_mov_b32 m0, s41
	s_nop 0
	global_load_lds_dwordx4 v[162:163], off
	s_waitcnt vmcnt(8)
	s_waitcnt lgkmcnt(0)
	s_barrier
	s_setprio 1
	s_waitcnt lgkmcnt(0)
	s_setprio 0
	s_setprio 1
	s_setprio 0
	s_barrier
	s_add_i32 s4, 0, 0x18000
	v_add_u32_e32 v152, s4, v157
	s_add_i32 s5, 0, 0x1c000
	ds_read_b128 v[146:149], v152
	ds_read_b128 v[176:179], v152 offset:1024
	ds_read_b128 v[180:183], v152 offset:2048
	ds_read_b128 v[184:187], v152 offset:3072
	v_add_u32_e32 v152, s5, v157
	ds_read_b128 v[188:191], v152
	ds_read_b128 v[192:195], v152 offset:1024
	ds_read_b128 v[196:199], v152 offset:2048
	ds_read_b128 v[202:205], v152 offset:3072
	s_add_u32 s50, s50, 0x40000
	s_addc_u32 s51, s51, 0
	s_mov_b32 m0, s45
	v_lshl_add_u64 v[166:167], s[50:51], 0, v[134:135]
	ds_read_b128 v[206:209], v173 offset:32768
	ds_read_b128 v[210:213], v173 offset:33792
	ds_read_b128 v[214:217], v173 offset:34816
	ds_read_b128 v[218:221], v173 offset:35840
	ds_read_b128 v[222:225], v173 offset:36864
	ds_read_b128 v[226:229], v173 offset:37888
	ds_read_b128 v[230:233], v173 offset:38912
	ds_read_b128 v[234:237], v173 offset:39936
	global_load_lds_dwordx4 v[166:167], off
	v_lshl_add_u64 v[166:167], s[50:51], 0, v[130:131]
	s_mov_b32 m0, s52
	s_nop 0
	global_load_lds_dwordx4 v[166:167], off
	s_waitcnt vmcnt(8)
	s_waitcnt lgkmcnt(0)
	s_barrier
; __device__ __forceinline__ float row_part(const float* ss, int row, int fq) { const f32x4 a = ((const f32x4*)(ss + (size_t)row * 16))[fq]; return (a[0] + a[1]) + (a[2] + a[3]); }
; __device__ __forceinline__ float row_finish(float t) { t += shx(t, 16); t += shx(t, 32); return __builtin_amdgcn_rsqf(t * (1.0f / 1024.0f) + RMS_EPS); }
; #define PG8_STAGE(bufoff, gbase, voff) do { _Pragma("unroll") for (int _i = 0; _i < 2; ++_i) \
;         __builtin_amdgcn_global_load_lds((const unsigned*)((const char*)(gbase) + (voff)[_i]), (PG8_LAS unsigned*)(lds + (bufoff) + ldsw + _i * 8192), 16, 0, 0); } while (0)
; #define PG8_LDA(dst, b, h) do { _Pragma("unroll") for (int m = 0; m < 4; ++m) _Pragma("unroll") for (int k = 0; k < 2; ++k) dst[m][k] = *(const PG8_LAS bf16x8*)(lds + PG8_SA(b, h) + aoff + m * 2048 + k * 1024); } while (0)
; #define PG8_WAIT_V(n) asm volatile("s_waitcnt vmcnt(" #n ")" ::: "memory")
; #define PG8_WAIT_L(n) asm volatile("s_waitcnt lgkmcnt(" #n ")" ::: "memory")
;     __device__ __forceinline__ void operator()(const f32x4 (&acc)[2][2][4][2], const Unit& u, int wr, int wc, int fr, int fq) const {
;         const int col0 = u.pn * 128 + 32 * wc + 8 * fq;
;         float rs[2][4];
; #pragma unroll
;         for (int ai = 0; ai < 2; ++ai)
; #pragma unroll
;             for (int m = 0; m < 4; ++m) rs[ai][m] = row_part(ss, u.pm * BM + ai * HALF + wr * 64 + m * 16 + fr, fq);
; #pragma unroll
;         for (int ai = 0; ai < 2; ++ai)
; #pragma unroll
;             for (int m = 0; m < 4; ++m) rs[ai][m] = row_finish(rs[ai][m]);
; template <class Epi, class Sched, bool ALIGN_EPI = false, bool SP2 = false>
; __device__ __forceinline__ void gemm_phase(PG8_LAS unsigned char* lds, const Gemm g, const Sched& S, const Epi& E, int tid_in) {
;     ...
;             PG8_WAIT_V(8); PG8_WAIT_L(0); PG8_BAR; PG8_MMA(1, 0, At, B0); PG8_MMA(1, 1, At, B1); PG8_BAR; PG8_SCHED;
;             PG8_LDB(B0, 1, 0); PG8_LDB(B1, 1, 1); PG8_SCHED; PG8_LDA(At, 1, 0); PG8_STAGE(PG8_SA(0, 1), a2 + hstep, voffA);
;             PG8_WAIT_V(8); PG8_WAIT_L(0); PG8_BAR; PG8_MMA(0, 0, At, B0); PG8_MMA(0, 1, At, B1); PG8_BAR; PG8_SCHED;
;             PG8_LDA(At, 1, 1); PG8_STAGE(PG8_SB(1, 0), b3, voffB); PG8_STAGE(PG8_SB(1, 1), b3 + hstep, voffB); PG8_STAGE(PG8_SA(1, 0), a3, voffA);
;             PG8_WAIT_V(8); PG8_WAIT_L(0); PG8_BAR; PG8_MMA(1, 0, At, B0); PG8_MMA(1, 1, At, B1); PG8_BAR; PG8_SCHED;
	s_setprio 1
	s_waitcnt lgkmcnt(0)
	v_mfma_f32_16x16x32_bf16 v[124:127], v[146:149], v[206:209], v[124:127]
	v_mfma_f32_16x16x32_bf16 v[120:123], v[180:183], v[206:209], v[120:123]
	v_mfma_f32_16x16x32_bf16 v[108:111], v[146:149], v[214:217], v[108:111]
	v_mfma_f32_16x16x32_bf16 v[104:107], v[180:183], v[214:217], v[104:107]
	v_mfma_f32_16x16x32_bf16 v[92:95], v[146:149], v[222:225], v[92:95]
	v_mfma_f32_16x16x32_bf16 v[88:91], v[180:183], v[222:225], v[88:91]
	v_mfma_f32_16x16x32_bf16 v[76:79], v[146:149], v[230:233], v[76:79]
	v_mfma_f32_16x16x32_bf16 v[72:75], v[180:183], v[230:233], v[72:75]
	v_mfma_f32_16x16x32_bf16 v[124:127], v[176:179], v[210:213], v[124:127]
	v_mfma_f32_16x16x32_bf16 v[120:123], v[184:187], v[210:213], v[120:123]
	v_mfma_f32_16x16x32_bf16 v[108:111], v[176:179], v[218:221], v[108:111]
	v_mfma_f32_16x16x32_bf16 v[104:107], v[184:187], v[218:221], v[104:107]
	v_mfma_f32_16x16x32_bf16 v[92:95], v[176:179], v[226:229], v[92:95]
	v_mfma_f32_16x16x32_bf16 v[88:91], v[184:187], v[226:229], v[88:91]
	v_mfma_f32_16x16x32_bf16 v[76:79], v[176:179], v[234:237], v[76:79]
	v_mfma_f32_16x16x32_bf16 v[72:75], v[184:187], v[234:237], v[72:75]
	s_setprio 0
	s_setprio 1
	v_mfma_f32_16x16x32_bf16 v[116:119], v[188:191], v[206:209], v[116:119]
	v_mfma_f32_16x16x32_bf16 v[112:115], v[196:199], v[206:209], v[112:115]
	v_mfma_f32_16x16x32_bf16 v[100:103], v[188:191], v[214:217], v[100:103]
	v_mfma_f32_16x16x32_bf16 v[96:99], v[196:199], v[214:217], v[96:99]
	v_mfma_f32_16x16x32_bf16 v[84:87], v[188:191], v[222:225], v[84:87]
	v_mfma_f32_16x16x32_bf16 v[80:83], v[196:199], v[222:225], v[80:83]
	v_mfma_f32_16x16x32_bf16 v[68:71], v[188:191], v[230:233], v[68:71]
	v_mfma_f32_16x16x32_bf16 v[64:67], v[196:199], v[230:233], v[64:67]
	v_mfma_f32_16x16x32_bf16 v[116:119], v[192:195], v[210:213], v[116:119]
	v_mfma_f32_16x16x32_bf16 v[112:115], v[202:205], v[210:213], v[112:115]
	v_mfma_f32_16x16x32_bf16 v[100:103], v[192:195], v[218:221], v[100:103]
	v_mfma_f32_16x16x32_bf16 v[96:99], v[202:205], v[218:221], v[96:99]
	v_mfma_f32_16x16x32_bf16 v[84:87], v[192:195], v[226:229], v[84:87]
	v_mfma_f32_16x16x32_bf16 v[80:83], v[202:205], v[226:229], v[80:83]
	v_mfma_f32_16x16x32_bf16 v[68:71], v[192:195], v[234:237], v[68:71]
	v_mfma_f32_16x16x32_bf16 v[64:67], v[202:205], v[234:237], v[64:67]
	s_setprio 0
	s_barrier
	s_add_i32 s4, s4, s12
	v_lshl_add_u64 v[150:151], v[150:151], 0, s[18:19]
	s_mov_b32 m0, s4
	s_nop 0
	global_load_lds_dwordx4 v[150:151], off
	s_add_i32 m0, s4, 0x2000
	s_add_u32 s48, s48, 0x40080
	v_lshl_add_u64 v[150:151], v[154:155], 0, s[18:19]
	s_addc_u32 s49, s49, 0
	s_add_i32 s4, s5, s12
	global_load_lds_dwordx4 v[150:151], off
	v_lshl_add_u64 v[150:151], s[48:49], 0, v[132:133]
	s_mov_b32 m0, s4
	s_nop 0
	global_load_lds_dwordx4 v[150:151], off
	v_lshl_add_u64 v[150:151], s[48:49], 0, v[128:129]
	s_add_i32 m0, s4, 0x2000
	s_nop 0
	global_load_lds_dwordx4 v[150:151], off
	v_lshl_add_u64 v[150:151], v[158:159], 0, s[18:19]
	s_mov_b32 m0, s54
	s_nop 0
	global_load_lds_dwordx4 v[150:151], off
	v_lshl_add_u64 v[150:151], v[162:163], 0, s[18:19]
	s_mov_b32 m0, s55
	s_nop 0
	global_load_lds_dwordx4 v[150:151], off
	s_waitcnt vmcnt(8)
	s_waitcnt lgkmcnt(0)
	s_barrier
	s_setprio 1
	s_waitcnt lgkmcnt(0)
	s_setprio 0
	s_setprio 1
	s_setprio 0
	s_barrier
	s_add_i32 s66, s66, 2
	s_add_u32 s64, s64, 0x100
	s_addc_u32 s65, s65, 0
	s_add_u32 s46, s46, 0x100
	s_addc_u32 s47, s47, 0
	s_cmp_gt_u32 s66, 13
	s_cbranch_scc0 .Lhh2_1588
	s_and_b64 vcc, exec, s[20:21]
	s_cbranch_vccz .Lhh2_1591
	s_barrier
.Lhh2_1591:
	v_lshl_add_u32 v170, s44, 8, v153
	s_cmp_ge_u32 s2, 0x80
	s_cselect_b32 s98, 0x80, 0
	v_add_u32_e32 v170, s98, v170
	s_lshl_b32 s99, s98, 6
	v_add_u32_e32 v241, s99, v239
	v_ashrrev_i32_e32 v171, 31, v170
	v_or_b32_e32 v166, 16, v170
	v_lshlrev_b64 v[146:147], 6, v[170:171]
	v_ashrrev_i32_e32 v167, 31, v166
	v_lshl_add_u64 v[146:147], v[136:137], 0, v[146:147]
	v_lshlrev_b64 v[148:149], 6, v[166:167]
	v_lshl_add_u64 v[148:149], v[136:137], 0, v[148:149]
	ds_read_b128 v[176:179], v241
	ds_read_b128 v[180:183], v241 offset:1024
	v_or_b32_e32 v162, 32, v170
	v_ashrrev_i32_e32 v163, 31, v162
	v_or_b32_e32 v158, 48, v170
	v_lshlrev_b64 v[146:147], 6, v[162:163]
	v_ashrrev_i32_e32 v159, 31, v158
	v_lshl_add_u64 v[146:147], v[136:137], 0, v[146:147]
	v_lshlrev_b64 v[148:149], 6, v[158:159]
	v_lshl_add_u64 v[148:149], v[136:137], 0, v[148:149]
	ds_read_b128 v[184:187], v241 offset:2048
	ds_read_b128 v[188:191], v241 offset:3072
	v_add_u32_e32 v154, 0x80, v170
	v_ashrrev_i32_e32 v155, 31, v154
	v_add_u32_e32 v150, 0x90, v170
	v_lshlrev_b64 v[146:147], 6, v[154:155]
	v_ashrrev_i32_e32 v151, 31, v150
	v_lshl_add_u64 v[146:147], v[136:137], 0, v[146:147]
	v_lshlrev_b64 v[148:149], 6, v[150:151]
	v_lshl_add_u64 v[148:149], v[136:137], 0, v[148:149]
	ds_read_b128 v[192:195], v241 offset:8192
	ds_read_b128 v[196:199], v241 offset:9216
	v_add_u32_e32 v148, 0xa0, v170
	v_ashrrev_i32_e32 v149, 31, v148
	v_lshlrev_b64 v[146:147], 6, v[148:149]
	v_lshl_add_u64 v[146:147], v[136:137], 0, v[146:147]
	ds_read_b128 v[202:205], v241 offset:10240
	v_add_u32_e32 v146, 0xb0, v170
	v_ashrrev_i32_e32 v147, 31, v146
	v_lshlrev_b64 v[206:207], 6, v[146:147]
	v_lshl_add_u64 v[206:207], v[136:137], 0, v[206:207]
	ds_read_b128 v[206:209], v241 offset:11264
	v_mov_b32_e32 v147, v201
	v_mov_b32_e32 v149, v201
	v_lshlrev_b32_e32 v147, 2, v147
	v_mov_b32_e32 v151, v201
	v_xor_b32_e32 v147, 64, v147
	s_andn2_b64 vcc, exec, s[8:9]
	v_lshlrev_b32_e32 v151, 2, v151
	v_xor_b32_e32 v151, 64, v151
	v_lshlrev_b32_e32 v149, 2, v149
	v_xor_b32_e32 v149, 0x80, v149
	s_mov_b64 s[8:9], -1
	s_waitcnt lgkmcnt(0)
; __device__ __forceinline__ float row_part(const float* ss, int row, int fq) { const f32x4 a = ((const f32x4*)(ss + (size_t)row * 16))[fq]; return (a[0] + a[1]) + (a[2] + a[3]); }
; __device__ __forceinline__ float row_finish(float t) { t += shx(t, 16); t += shx(t, 32); return __builtin_amdgcn_rsqf(t * (1.0f / 1024.0f) + RMS_EPS); }
;     __device__ __forceinline__ void operator()(const f32x4 (&acc)[2][2][4][2], const Unit& u, int wr, int wc, int fr, int fq) const {
;     ...
;         float rs[2][4];
; #pragma unroll
;         for (int ai = 0; ai < 2; ++ai)
; #pragma unroll
;             for (int m = 0; m < 4; ++m) rs[ai][m] = row_part(ss, u.pm * BM + ai * HALF + wr * 64 + m * 16 + fr, fq);
; #pragma unroll
;         for (int ai = 0; ai < 2; ++ai)
; #pragma unroll
;             for (int m = 0; m < 4; ++m) rs[ai][m] = row_finish(rs[ai][m]);
	v_mov_b32_e32 v210, v177
	v_mov_b32_e32 v211, v178
	v_mov_b32_e32 v177, v179
	v_pk_add_f32 v[176:177], v[210:211], v[176:177]
	v_mov_b32_e32 v178, v181
	v_add_f32_e32 v152, v176, v177
	v_mov_b32_e32 v179, v182
	v_mov_b32_e32 v181, v183
	ds_bpermute_b32 v147, v147, v152
	v_pk_add_f32 v[176:177], v[178:179], v[180:181]
	v_mov_b32_e32 v182, v185
	v_add_f32_e32 v155, v176, v177
	ds_bpermute_b32 v151, v151, v155
	s_waitcnt lgkmcnt(1)
	v_add_f32_e32 v147, v152, v147
	v_mov_b32_e32 v152, v201
	ds_bpermute_b32 v149, v149, v147
	s_waitcnt lgkmcnt(1)
	v_add_f32_e32 v151, v155, v151
	v_lshlrev_b32_e32 v152, 2, v152
	v_xor_b32_e32 v152, 0x80, v152
	ds_bpermute_b32 v152, v152, v151
	s_waitcnt lgkmcnt(1)
	v_add_f32_e32 v147, v147, v149
	v_mov_b32_e32 v149, v201
	v_mov_b32_e32 v183, v186
	v_mov_b32_e32 v185, v187
	v_pk_add_f32 v[178:179], v[182:183], v[184:185]
	v_fmamk_f32 v147, v147, 0x3a800000, v175
	v_lshlrev_b32_e32 v149, 2, v149
	v_add_f32_e32 v156, v178, v179
	v_rsq_f32_e32 v176, v147
	s_waitcnt lgkmcnt(0)
	v_add_f32_e32 v147, v151, v152
	v_xor_b32_e32 v149, 64, v149
	v_mov_b32_e32 v151, v201
	v_mov_b32_e32 v152, v201
	v_mov_b32_e32 v186, v189
	v_mov_b32_e32 v187, v190
	v_mov_b32_e32 v189, v191
	ds_bpermute_b32 v149, v149, v156
	v_pk_add_f32 v[180:181], v[186:187], v[188:189]
	v_lshlrev_b32_e32 v152, 2, v152
	v_add_f32_e32 v159, v180, v181
	v_xor_b32_e32 v152, 64, v152
	ds_bpermute_b32 v152, v152, v159
	s_waitcnt lgkmcnt(1)
	v_add_f32_e32 v149, v156, v149
	v_lshlrev_b32_e32 v151, 2, v151
	v_mov_b32_e32 v156, v201
	v_xor_b32_e32 v151, 0x80, v151
	ds_bpermute_b32 v151, v151, v149
	v_lshlrev_b32_e32 v156, 2, v156
	s_waitcnt lgkmcnt(1)
	v_add_f32_e32 v152, v159, v152
	v_xor_b32_e32 v156, 0x80, v156
	ds_bpermute_b32 v156, v156, v152
	v_fmamk_f32 v147, v147, 0x3a800000, v175
	v_rsq_f32_e32 v174, v147
	s_waitcnt lgkmcnt(1)
	v_add_f32_e32 v147, v149, v151
	v_mov_b32_e32 v149, v201
	v_mov_b32_e32 v190, v193
	v_mov_b32_e32 v191, v194
	v_mov_b32_e32 v193, v195
	v_fmamk_f32 v147, v147, 0x3a800000, v175
	v_pk_add_f32 v[182:183], v[190:191], v[192:193]
	v_rsq_f32_e32 v172, v147
	s_waitcnt lgkmcnt(0)
	v_add_f32_e32 v147, v152, v156
	v_lshlrev_b32_e32 v149, 2, v149
	v_mov_b32_e32 v151, v201
	v_mov_b32_e32 v152, v201
	v_mov_b32_e32 v194, v197
	v_mov_b32_e32 v195, v198
	v_mov_b32_e32 v197, v199
	v_add_f32_e32 v160, v182, v183
	v_xor_b32_e32 v149, 64, v149
	v_pk_add_f32 v[184:185], v[194:195], v[196:197]
	ds_bpermute_b32 v149, v149, v160
	v_lshlrev_b32_e32 v152, 2, v152
	v_add_f32_e32 v163, v184, v185
	v_xor_b32_e32 v152, 64, v152
	ds_bpermute_b32 v152, v152, v163
	v_lshlrev_b32_e32 v151, 2, v151
	v_mov_b32_e32 v156, v201
	s_waitcnt lgkmcnt(1)
	v_add_f32_e32 v149, v160, v149
	v_xor_b32_e32 v151, 0x80, v151
	ds_bpermute_b32 v151, v151, v149
	v_lshlrev_b32_e32 v156, 2, v156
	s_waitcnt lgkmcnt(1)
	v_add_f32_e32 v152, v163, v152
	v_xor_b32_e32 v156, 0x80, v156
	ds_bpermute_b32 v156, v156, v152
	v_fmamk_f32 v147, v147, 0x3a800000, v175
	v_rsq_f32_e32 v168, v147
	s_waitcnt lgkmcnt(1)
	v_add_f32_e32 v147, v149, v151
	v_fmamk_f32 v147, v147, 0x3a800000, v175
	v_rsq_f32_e32 v164, v147
	s_waitcnt lgkmcnt(0)
	v_add_f32_e32 v147, v152, v156
	v_mov_b32_e32 v149, v201
	v_mov_b32_e32 v151, v201
	v_mov_b32_e32 v152, v201
	v_mov_b32_e32 v198, v203
	v_mov_b32_e32 v199, v204
	v_mov_b32_e32 v203, v205
	v_mov_b32_e32 v204, v207
	v_mov_b32_e32 v205, v208
	v_mov_b32_e32 v207, v209
	v_pk_add_f32 v[188:189], v[204:205], v[206:207]
	v_lshlrev_b32_e32 v152, 2, v152
	v_pk_add_f32 v[186:187], v[198:199], v[202:203]
	v_add_f32_e32 v155, v188, v189
	v_lshlrev_b32_e32 v149, 2, v149
	v_xor_b32_e32 v152, 64, v152
	v_add_f32_e32 v167, v186, v187
	v_xor_b32_e32 v149, 64, v149
	ds_bpermute_b32 v152, v152, v155
	ds_bpermute_b32 v149, v149, v167
	v_lshlrev_b32_e32 v151, 2, v151
	v_xor_b32_e32 v151, 0x80, v151
	v_fmamk_f32 v147, v147, 0x3a800000, v175
	s_waitcnt lgkmcnt(1)
	v_add_f32_e32 v152, v155, v152
	v_mov_b32_e32 v155, v201
	s_waitcnt lgkmcnt(0)
	v_add_f32_e32 v149, v167, v149
	ds_bpermute_b32 v151, v151, v149
	v_lshlrev_b32_e32 v155, 2, v155
	v_xor_b32_e32 v155, 0x80, v155
	ds_bpermute_b32 v155, v155, v152
	v_rsq_f32_e32 v160, v147
	s_waitcnt lgkmcnt(1)
	v_add_f32_e32 v147, v149, v151
	v_fmamk_f32 v147, v147, 0x3a800000, v175
	v_rsq_f32_e32 v156, v147
	s_waitcnt lgkmcnt(0)
; __device__ __forceinline__ f32x4 silu4(f32x4 v) { return (f32x4){silu_f(v[0]), silu_f(v[1]), silu_f(v[2]), silu_f(v[3])}; }
; __device__ __forceinline__ u32x4 pack8(f32x4 a, f32x4 b) { u32x4 w; w.x = cvt_pk_bf16(a[0], a[1]); w.y = cvt_pk_bf16(a[2], a[3]); w.z = cvt_pk_bf16(b[0], b[1]); w.w = cvt_pk_bf16(b[2], b[3]); return w; }
;     __device__ __forceinline__ void operator()(const f32x4 (&acc)[2][2][4][2], const Unit& u, int wr, int wc, int fr, int fq) const {
;     ...
; #pragma unroll
;         for (int ai = 0; ai < 2; ++ai)
; #pragma unroll
;             for (int m = 0; m < 4; ++m) {
;                 const int row = u.pm * BM + ai * HALF + wr * 64 + m * 16 + fr;
;                 const float rstd = rs[ai][m];
;                 const f32x4 a0 = silu4(acc[ai][0][m][0] * rstd) * (acc[ai][1][m][0] * rstd);
;                 const f32x4 a1 = silu4(acc[ai][0][m][1] * rstd) * (acc[ai][1][m][1] * rstd);
;                 *(u32x4*)(ACT + (size_t)row * 2816 + col0) = pack8(a0, a1);
;             }
	v_add_f32_e32 v147, v152, v155
	v_fmamk_f32 v147, v147, 0x3a800000, v175
	v_pk_mul_f32 v[124:125], v[124:125], v[176:177] op_sel_hi:[1,0]
	v_rsq_f32_e32 v152, v147
	v_mul_f32_e32 v147, 0xbfb8aa3b, v124
	v_exp_f32_e32 v147, v147
	v_mul_f32_e32 v149, 0xbfb8aa3b, v125
	v_exp_f32_e32 v149, v149
	v_pk_mul_f32 v[126:127], v[126:127], v[176:177] op_sel_hi:[1,0]
	v_add_f32_e32 v147, 1.0, v147
	v_rcp_f32_e32 v178, v147
	v_add_f32_e32 v147, 1.0, v149
	v_mul_f32_e32 v149, 0xbfb8aa3b, v126
	v_exp_f32_e32 v149, v149
	v_mul_f32_e32 v151, 0xbfb8aa3b, v127
	v_exp_f32_e32 v151, v151
	v_rcp_f32_e32 v179, v147
	v_add_f32_e32 v147, 1.0, v149
	v_rcp_f32_e32 v180, v147
	v_add_f32_e32 v147, 1.0, v151
	v_pk_mul_f32 v[120:121], v[120:121], v[176:177] op_sel_hi:[1,0]
	v_rcp_f32_e32 v181, v147
	v_mul_f32_e32 v147, 0xbfb8aa3b, v120
	v_exp_f32_e32 v147, v147
	v_mul_f32_e32 v149, 0xbfb8aa3b, v121
	v_exp_f32_e32 v149, v149
	v_pk_mul_f32 v[122:123], v[122:123], v[176:177] op_sel_hi:[1,0]
	v_add_f32_e32 v147, 1.0, v147
	v_pk_mul_f32 v[124:125], v[124:125], v[178:179]
	v_rcp_f32_e32 v178, v147
	v_add_f32_e32 v147, 1.0, v149
	v_mul_f32_e32 v149, 0xbfb8aa3b, v122
	v_exp_f32_e32 v149, v149
	v_mul_f32_e32 v151, 0xbfb8aa3b, v123
	v_exp_f32_e32 v151, v151
	v_rcp_f32_e32 v179, v147
	v_add_f32_e32 v147, 1.0, v149
	v_pk_mul_f32 v[126:127], v[126:127], v[180:181]
	v_rcp_f32_e32 v180, v147
	v_add_f32_e32 v147, 1.0, v151
	v_rcp_f32_e32 v181, v147
	v_pk_mul_f32 v[116:117], v[116:117], v[176:177] op_sel_hi:[1,0]
	v_pk_mul_f32 v[118:119], v[118:119], v[176:177] op_sel_hi:[1,0]
	v_pk_mul_f32 v[120:121], v[120:121], v[178:179]
	v_pk_mul_f32 v[112:113], v[112:113], v[176:177] op_sel_hi:[1,0]
	v_lshl_or_b32 v182, s61, 7, v161
	v_pk_mul_f32 v[118:119], v[118:119], v[126:127]
	v_pk_mul_f32 v[116:117], v[116:117], v[124:125]
	v_pk_mul_f32 v[122:123], v[122:123], v[180:181]
	v_pk_mul_f32 v[114:115], v[114:115], v[176:177] op_sel_hi:[1,0]
	v_pk_mul_f32 v[112:113], v[112:113], v[120:121]
	v_ashrrev_i32_e32 v183, 31, v182
	v_pk_mul_f32 v[114:115], v[114:115], v[122:123]
	v_cvt_pk_bf16_f32 v116, v116, v117
	v_cvt_pk_bf16_f32 v117, v118, v119
	v_cvt_pk_bf16_f32 v118, v112, v113
	v_mov_b64_e32 v[112:113], s[16:17]
	v_cvt_pk_bf16_f32 v119, v114, v115
	v_mad_i64_i32 v[120:121], s[46:47], v170, s60, v[112:113]
	v_lshlrev_b64 v[114:115], 1, v[182:183]
	v_pk_mul_f32 v[108:109], v[108:109], v[174:175] op_sel_hi:[1,0]
	v_pk_mul_f32 v[110:111], v[110:111], v[174:175] op_sel_hi:[1,0]
	v_mul_f32_e32 v122, 0xbfb8aa3b, v108
	v_mul_f32_e32 v123, 0xbfb8aa3b, v109
	v_lshl_add_u64 v[120:121], v[120:121], 0, v[114:115]
	v_pk_mul_f32 v[104:105], v[104:105], v[174:175] op_sel_hi:[1,0]
	v_pk_mul_f32 v[106:107], v[106:107], v[174:175] op_sel_hi:[1,0]
	v_exp_f32_e32 v122, v122
	v_exp_f32_e32 v123, v123
	v_mul_f32_e32 v124, 0xbfb8aa3b, v110
	v_mul_f32_e32 v125, 0xbfb8aa3b, v111
	global_store_dwordx4 v[120:121], v[116:119], off
	v_exp_f32_e32 v124, v124
	v_exp_f32_e32 v125, v125
	v_mul_f32_e32 v116, 0xbfb8aa3b, v104
	v_mul_f32_e32 v117, 0xbfb8aa3b, v105
	v_mul_f32_e32 v118, 0xbfb8aa3b, v106
	v_mul_f32_e32 v119, 0xbfb8aa3b, v107
	v_exp_f32_e32 v116, v116
	v_exp_f32_e32 v117, v117
	v_exp_f32_e32 v118, v118
	v_exp_f32_e32 v119, v119
	v_add_f32_e32 v122, 1.0, v122
	v_add_f32_e32 v123, 1.0, v123
	v_rcp_f32_e32 v122, v122
	v_rcp_f32_e32 v123, v123
	v_add_f32_e32 v124, 1.0, v124
	v_add_f32_e32 v125, 1.0, v125
	v_add_f32_e32 v116, 1.0, v116
	v_add_f32_e32 v117, 1.0, v117
	v_add_f32_e32 v118, 1.0, v118
	v_add_f32_e32 v119, 1.0, v119
	v_rcp_f32_e32 v124, v124
	v_rcp_f32_e32 v125, v125
	v_rcp_f32_e32 v116, v116
	v_rcp_f32_e32 v117, v117
	v_rcp_f32_e32 v118, v118
	v_rcp_f32_e32 v119, v119
	v_pk_mul_f32 v[108:109], v[108:109], v[122:123]
	v_pk_mul_f32 v[100:101], v[100:101], v[174:175] op_sel_hi:[1,0]
	v_pk_mul_f32 v[110:111], v[110:111], v[124:125]
	v_pk_mul_f32 v[102:103], v[102:103], v[174:175] op_sel_hi:[1,0]
	v_pk_mul_f32 v[100:101], v[100:101], v[108:109]
	v_pk_mul_f32 v[104:105], v[104:105], v[116:117]
	v_pk_mul_f32 v[106:107], v[106:107], v[118:119]
	v_pk_mul_f32 v[96:97], v[96:97], v[174:175] op_sel_hi:[1,0]
	v_pk_mul_f32 v[98:99], v[98:99], v[174:175] op_sel_hi:[1,0]
	v_pk_mul_f32 v[102:103], v[102:103], v[110:111]
	v_pk_mul_f32 v[106:107], v[98:99], v[106:107]
	v_pk_mul_f32 v[98:99], v[96:97], v[104:105]
	v_cvt_pk_bf16_f32 v96, v100, v101
	v_mad_i64_i32 v[100:101], s[46:47], v166, s60, v[112:113]
	v_pk_mul_f32 v[92:93], v[92:93], v[172:173] op_sel_hi:[1,0]
	v_cvt_pk_bf16_f32 v97, v102, v103
	v_cvt_pk_bf16_f32 v98, v98, v99
	v_cvt_pk_bf16_f32 v99, v106, v107
	v_pk_mul_f32 v[94:95], v[94:95], v[172:173] op_sel_hi:[1,0]
	v_mul_f32_e32 v102, 0xbfb8aa3b, v92
	v_mul_f32_e32 v103, 0xbfb8aa3b, v93
	v_lshl_add_u64 v[100:101], v[100:101], 0, v[114:115]
	v_pk_mul_f32 v[88:89], v[88:89], v[172:173] op_sel_hi:[1,0]
	v_pk_mul_f32 v[90:91], v[90:91], v[172:173] op_sel_hi:[1,0]
	v_exp_f32_e32 v102, v102
	v_exp_f32_e32 v103, v103
	v_mul_f32_e32 v104, 0xbfb8aa3b, v94
	v_mul_f32_e32 v105, 0xbfb8aa3b, v95
	global_store_dwordx4 v[100:101], v[96:99], off
	v_exp_f32_e32 v104, v104
	v_exp_f32_e32 v105, v105
	v_mul_f32_e32 v96, 0xbfb8aa3b, v88
	v_mul_f32_e32 v97, 0xbfb8aa3b, v89
	v_mul_f32_e32 v98, 0xbfb8aa3b, v90
	v_mul_f32_e32 v99, 0xbfb8aa3b, v91
	v_exp_f32_e32 v96, v96
	v_exp_f32_e32 v97, v97
	v_exp_f32_e32 v98, v98
	v_exp_f32_e32 v99, v99
	v_add_f32_e32 v102, 1.0, v102
	v_add_f32_e32 v103, 1.0, v103
	v_rcp_f32_e32 v102, v102
	v_rcp_f32_e32 v103, v103
	v_add_f32_e32 v104, 1.0, v104
	v_add_f32_e32 v105, 1.0, v105
	v_add_f32_e32 v96, 1.0, v96
	v_add_f32_e32 v97, 1.0, v97
	v_add_f32_e32 v98, 1.0, v98
	v_add_f32_e32 v99, 1.0, v99
	v_rcp_f32_e32 v104, v104
; __device__ __forceinline__ f32x4 silu4(f32x4 v) { return (f32x4){silu_f(v[0]), silu_f(v[1]), silu_f(v[2]), silu_f(v[3])}; }
; __device__ __forceinline__ u32x4 pack8(f32x4 a, f32x4 b) { u32x4 w; w.x = cvt_pk_bf16(a[0], a[1]); w.y = cvt_pk_bf16(a[2], a[3]); w.z = cvt_pk_bf16(b[0], b[1]); w.w = cvt_pk_bf16(b[2], b[3]); return w; }
;     __device__ __forceinline__ void operator()(const f32x4 (&acc)[2][2][4][2], const Unit& u, int wr, int wc, int fr, int fq) const {
;     ...
;         for (int ai = 0; ai < 2; ++ai)
; #pragma unroll
;             for (int m = 0; m < 4; ++m) {
;                 const int row = u.pm * BM + ai * HALF + wr * 64 + m * 16 + fr;
;                 const float rstd = rs[ai][m];
;                 const f32x4 a0 = silu4(acc[ai][0][m][0] * rstd) * (acc[ai][1][m][0] * rstd);
;                 const f32x4 a1 = silu4(acc[ai][0][m][1] * rstd) * (acc[ai][1][m][1] * rstd);
;                 *(u32x4*)(ACT + (size_t)row * 2816 + col0) = pack8(a0, a1);
;             }
	v_rcp_f32_e32 v105, v105
	v_rcp_f32_e32 v96, v96
	v_rcp_f32_e32 v97, v97
	v_rcp_f32_e32 v98, v98
	v_rcp_f32_e32 v99, v99
	v_pk_mul_f32 v[92:93], v[92:93], v[102:103]
	v_pk_mul_f32 v[84:85], v[84:85], v[172:173] op_sel_hi:[1,0]
	v_pk_mul_f32 v[94:95], v[94:95], v[104:105]
	v_pk_mul_f32 v[86:87], v[86:87], v[172:173] op_sel_hi:[1,0]
	v_pk_mul_f32 v[84:85], v[84:85], v[92:93]
	v_pk_mul_f32 v[88:89], v[88:89], v[96:97]
	v_pk_mul_f32 v[90:91], v[90:91], v[98:99]
	v_pk_mul_f32 v[80:81], v[80:81], v[172:173] op_sel_hi:[1,0]
	v_pk_mul_f32 v[82:83], v[82:83], v[172:173] op_sel_hi:[1,0]
	v_pk_mul_f32 v[86:87], v[86:87], v[94:95]
	v_pk_mul_f32 v[90:91], v[82:83], v[90:91]
	v_pk_mul_f32 v[82:83], v[80:81], v[88:89]
	v_cvt_pk_bf16_f32 v80, v84, v85
	v_mad_i64_i32 v[84:85], s[46:47], v162, s60, v[112:113]
	v_pk_mul_f32 v[76:77], v[76:77], v[168:169] op_sel_hi:[1,0]
	v_cvt_pk_bf16_f32 v81, v86, v87
	v_cvt_pk_bf16_f32 v82, v82, v83
	v_cvt_pk_bf16_f32 v83, v90, v91
	v_pk_mul_f32 v[78:79], v[78:79], v[168:169] op_sel_hi:[1,0]
	v_mul_f32_e32 v86, 0xbfb8aa3b, v76
	v_mul_f32_e32 v87, 0xbfb8aa3b, v77
	v_lshl_add_u64 v[84:85], v[84:85], 0, v[114:115]
	v_pk_mul_f32 v[72:73], v[72:73], v[168:169] op_sel_hi:[1,0]
	v_pk_mul_f32 v[74:75], v[74:75], v[168:169] op_sel_hi:[1,0]
	v_exp_f32_e32 v86, v86
	v_exp_f32_e32 v87, v87
	v_mul_f32_e32 v88, 0xbfb8aa3b, v78
	v_mul_f32_e32 v89, 0xbfb8aa3b, v79
	global_store_dwordx4 v[84:85], v[80:83], off
	v_exp_f32_e32 v88, v88
	v_exp_f32_e32 v89, v89
	v_mul_f32_e32 v80, 0xbfb8aa3b, v72
	v_mul_f32_e32 v81, 0xbfb8aa3b, v73
	v_mul_f32_e32 v82, 0xbfb8aa3b, v74
	v_mul_f32_e32 v83, 0xbfb8aa3b, v75
	v_exp_f32_e32 v80, v80
	v_exp_f32_e32 v81, v81
	v_exp_f32_e32 v82, v82
	v_exp_f32_e32 v83, v83
	v_add_f32_e32 v86, 1.0, v86
	v_add_f32_e32 v87, 1.0, v87
	v_rcp_f32_e32 v86, v86
	v_rcp_f32_e32 v87, v87
	v_add_f32_e32 v88, 1.0, v88
	v_add_f32_e32 v89, 1.0, v89
	v_add_f32_e32 v80, 1.0, v80
	v_add_f32_e32 v81, 1.0, v81
	v_add_f32_e32 v82, 1.0, v82
	v_add_f32_e32 v83, 1.0, v83
	v_rcp_f32_e32 v88, v88
	v_rcp_f32_e32 v89, v89
	v_rcp_f32_e32 v80, v80
	v_rcp_f32_e32 v81, v81
	v_rcp_f32_e32 v82, v82
	v_rcp_f32_e32 v83, v83
	v_pk_mul_f32 v[76:77], v[76:77], v[86:87]
	v_pk_mul_f32 v[68:69], v[68:69], v[168:169] op_sel_hi:[1,0]
	v_pk_mul_f32 v[78:79], v[78:79], v[88:89]
	v_pk_mul_f32 v[70:71], v[70:71], v[168:169] op_sel_hi:[1,0]
	v_pk_mul_f32 v[68:69], v[68:69], v[76:77]
	v_pk_mul_f32 v[72:73], v[72:73], v[80:81]
	v_pk_mul_f32 v[74:75], v[74:75], v[82:83]
	v_pk_mul_f32 v[64:65], v[64:65], v[168:169] op_sel_hi:[1,0]
	v_pk_mul_f32 v[66:67], v[66:67], v[168:169] op_sel_hi:[1,0]
	v_pk_mul_f32 v[70:71], v[70:71], v[78:79]
	v_pk_mul_f32 v[74:75], v[66:67], v[74:75]
	v_pk_mul_f32 v[66:67], v[64:65], v[72:73]
	v_cvt_pk_bf16_f32 v64, v68, v69
	v_mad_i64_i32 v[68:69], s[46:47], v158, s60, v[112:113]
	v_pk_mul_f32 v[60:61], v[60:61], v[164:165] op_sel_hi:[1,0]
	v_cvt_pk_bf16_f32 v65, v70, v71
	v_cvt_pk_bf16_f32 v66, v66, v67
	v_cvt_pk_bf16_f32 v67, v74, v75
	v_pk_mul_f32 v[62:63], v[62:63], v[164:165] op_sel_hi:[1,0]
	v_mul_f32_e32 v70, 0xbfb8aa3b, v60
	v_mul_f32_e32 v71, 0xbfb8aa3b, v61
	v_lshl_add_u64 v[68:69], v[68:69], 0, v[114:115]
	v_pk_mul_f32 v[56:57], v[56:57], v[164:165] op_sel_hi:[1,0]
	v_pk_mul_f32 v[58:59], v[58:59], v[164:165] op_sel_hi:[1,0]
	v_exp_f32_e32 v70, v70
	v_exp_f32_e32 v71, v71
	v_mul_f32_e32 v72, 0xbfb8aa3b, v62
	v_mul_f32_e32 v73, 0xbfb8aa3b, v63
	global_store_dwordx4 v[68:69], v[64:67], off
	s_branch .Lhh2_epi_end
	v_exp_f32_e32 v72, v72
	v_exp_f32_e32 v73, v73
	v_mul_f32_e32 v64, 0xbfb8aa3b, v56
	v_mul_f32_e32 v65, 0xbfb8aa3b, v57
	v_mul_f32_e32 v66, 0xbfb8aa3b, v58
	v_mul_f32_e32 v67, 0xbfb8aa3b, v59
	v_exp_f32_e32 v64, v64
	v_exp_f32_e32 v65, v65
	v_exp_f32_e32 v66, v66
	v_exp_f32_e32 v67, v67
	v_add_f32_e32 v70, 1.0, v70
	v_add_f32_e32 v71, 1.0, v71
	v_rcp_f32_e32 v70, v70
	v_rcp_f32_e32 v71, v71
	v_add_f32_e32 v72, 1.0, v72
	v_add_f32_e32 v73, 1.0, v73
	v_add_f32_e32 v64, 1.0, v64
	v_add_f32_e32 v65, 1.0, v65
	v_add_f32_e32 v66, 1.0, v66
	v_add_f32_e32 v67, 1.0, v67
	v_rcp_f32_e32 v72, v72
	v_rcp_f32_e32 v73, v73
	v_rcp_f32_e32 v64, v64
	v_rcp_f32_e32 v65, v65
	v_rcp_f32_e32 v66, v66
	v_rcp_f32_e32 v67, v67
	v_pk_mul_f32 v[60:61], v[60:61], v[70:71]
	v_pk_mul_f32 v[52:53], v[52:53], v[164:165] op_sel_hi:[1,0]
	v_pk_mul_f32 v[62:63], v[62:63], v[72:73]
	v_pk_mul_f32 v[54:55], v[54:55], v[164:165] op_sel_hi:[1,0]
	v_pk_mul_f32 v[52:53], v[52:53], v[60:61]
	v_pk_mul_f32 v[56:57], v[56:57], v[64:65]
	v_pk_mul_f32 v[58:59], v[58:59], v[66:67]
	v_pk_mul_f32 v[48:49], v[48:49], v[164:165] op_sel_hi:[1,0]
	v_pk_mul_f32 v[50:51], v[50:51], v[164:165] op_sel_hi:[1,0]
	v_pk_mul_f32 v[54:55], v[54:55], v[62:63]
	v_pk_mul_f32 v[58:59], v[50:51], v[58:59]
	v_pk_mul_f32 v[50:51], v[48:49], v[56:57]
	v_cvt_pk_bf16_f32 v48, v52, v53
	v_mad_i64_i32 v[52:53], s[46:47], v154, s60, v[112:113]
	v_pk_mul_f32 v[44:45], v[44:45], v[160:161] op_sel_hi:[1,0]
	v_cvt_pk_bf16_f32 v49, v54, v55
	v_cvt_pk_bf16_f32 v50, v50, v51
	v_cvt_pk_bf16_f32 v51, v58, v59
	v_pk_mul_f32 v[46:47], v[46:47], v[160:161] op_sel_hi:[1,0]
	v_mul_f32_e32 v54, 0xbfb8aa3b, v44
	v_mul_f32_e32 v55, 0xbfb8aa3b, v45
	v_lshl_add_u64 v[52:53], v[52:53], 0, v[114:115]
	v_pk_mul_f32 v[40:41], v[40:41], v[160:161] op_sel_hi:[1,0]
	v_pk_mul_f32 v[42:43], v[42:43], v[160:161] op_sel_hi:[1,0]
	v_exp_f32_e32 v54, v54
	v_exp_f32_e32 v55, v55
	v_mul_f32_e32 v56, 0xbfb8aa3b, v46
	v_mul_f32_e32 v57, 0xbfb8aa3b, v47
	global_store_dwordx4 v[52:53], v[48:51], off
	v_exp_f32_e32 v56, v56
	v_exp_f32_e32 v57, v57
	v_mul_f32_e32 v48, 0xbfb8aa3b, v40
	v_mul_f32_e32 v49, 0xbfb8aa3b, v41
; __device__ __forceinline__ f32x4 silu4(f32x4 v) { return (f32x4){silu_f(v[0]), silu_f(v[1]), silu_f(v[2]), silu_f(v[3])}; }
; __device__ __forceinline__ u32x4 pack8(f32x4 a, f32x4 b) { u32x4 w; w.x = cvt_pk_bf16(a[0], a[1]); w.y = cvt_pk_bf16(a[2], a[3]); w.z = cvt_pk_bf16(b[0], b[1]); w.w = cvt_pk_bf16(b[2], b[3]); return w; }
;     __device__ __forceinline__ void operator()(const f32x4 (&acc)[2][2][4][2], const Unit& u, int wr, int wc, int fr, int fq) const {
;     ...
;         for (int ai = 0; ai < 2; ++ai)
; #pragma unroll
;             for (int m = 0; m < 4; ++m) {
;                 const int row = u.pm * BM + ai * HALF + wr * 64 + m * 16 + fr;
;                 const float rstd = rs[ai][m];
;                 const f32x4 a0 = silu4(acc[ai][0][m][0] * rstd) * (acc[ai][1][m][0] * rstd);
;                 const f32x4 a1 = silu4(acc[ai][0][m][1] * rstd) * (acc[ai][1][m][1] * rstd);
;                 *(u32x4*)(ACT + (size_t)row * 2816 + col0) = pack8(a0, a1);
;             }
; template <class Epi, class Sched, bool ALIGN_EPI = false, bool SP2 = false>
; __device__ __forceinline__ void gemm_phase(PG8_LAS unsigned char* lds, const Gemm g, const Sched& S, const Epi& E, int tid_in) {
;     ...
;         if constexpr (!Epi::AFTER_DRAIN) { E(acc, cur, wr, wc, fr, fq); S.done(cur); }
;         if (!has_next) break;
	v_mul_f32_e32 v50, 0xbfb8aa3b, v42
	v_mul_f32_e32 v51, 0xbfb8aa3b, v43
	v_exp_f32_e32 v48, v48
	v_exp_f32_e32 v49, v49
	v_exp_f32_e32 v50, v50
	v_exp_f32_e32 v51, v51
	v_add_f32_e32 v54, 1.0, v54
	v_add_f32_e32 v55, 1.0, v55
	v_rcp_f32_e32 v54, v54
	v_rcp_f32_e32 v55, v55
	v_add_f32_e32 v56, 1.0, v56
	v_add_f32_e32 v57, 1.0, v57
	v_add_f32_e32 v48, 1.0, v48
	v_add_f32_e32 v49, 1.0, v49
	v_add_f32_e32 v50, 1.0, v50
	v_add_f32_e32 v51, 1.0, v51
	v_rcp_f32_e32 v56, v56
	v_rcp_f32_e32 v57, v57
	v_rcp_f32_e32 v48, v48
	v_rcp_f32_e32 v49, v49
	v_rcp_f32_e32 v50, v50
	v_rcp_f32_e32 v51, v51
	v_pk_mul_f32 v[44:45], v[44:45], v[54:55]
	v_pk_mul_f32 v[36:37], v[36:37], v[160:161] op_sel_hi:[1,0]
	v_pk_mul_f32 v[46:47], v[46:47], v[56:57]
	v_pk_mul_f32 v[38:39], v[38:39], v[160:161] op_sel_hi:[1,0]
	v_pk_mul_f32 v[36:37], v[36:37], v[44:45]
	v_pk_mul_f32 v[40:41], v[40:41], v[48:49]
	v_pk_mul_f32 v[42:43], v[42:43], v[50:51]
	v_pk_mul_f32 v[32:33], v[32:33], v[160:161] op_sel_hi:[1,0]
	v_pk_mul_f32 v[34:35], v[34:35], v[160:161] op_sel_hi:[1,0]
	v_pk_mul_f32 v[38:39], v[38:39], v[46:47]
	v_pk_mul_f32 v[42:43], v[34:35], v[42:43]
	v_pk_mul_f32 v[34:35], v[32:33], v[40:41]
	v_cvt_pk_bf16_f32 v32, v36, v37
	v_mad_i64_i32 v[36:37], s[46:47], v150, s60, v[112:113]
	v_pk_mul_f32 v[28:29], v[28:29], v[156:157] op_sel_hi:[1,0]
	v_cvt_pk_bf16_f32 v33, v38, v39
	v_cvt_pk_bf16_f32 v34, v34, v35
	v_cvt_pk_bf16_f32 v35, v42, v43
	v_pk_mul_f32 v[30:31], v[30:31], v[156:157] op_sel_hi:[1,0]
	v_mul_f32_e32 v38, 0xbfb8aa3b, v28
	v_mul_f32_e32 v39, 0xbfb8aa3b, v29
	v_lshl_add_u64 v[36:37], v[36:37], 0, v[114:115]
	v_pk_mul_f32 v[24:25], v[24:25], v[156:157] op_sel_hi:[1,0]
	v_pk_mul_f32 v[26:27], v[26:27], v[156:157] op_sel_hi:[1,0]
	v_exp_f32_e32 v38, v38
	v_exp_f32_e32 v39, v39
	v_mul_f32_e32 v40, 0xbfb8aa3b, v30
	v_mul_f32_e32 v41, 0xbfb8aa3b, v31
	global_store_dwordx4 v[36:37], v[32:35], off
	v_exp_f32_e32 v40, v40
	v_exp_f32_e32 v41, v41
	v_mul_f32_e32 v32, 0xbfb8aa3b, v24
	v_mul_f32_e32 v33, 0xbfb8aa3b, v25
	v_mul_f32_e32 v34, 0xbfb8aa3b, v26
	v_mul_f32_e32 v35, 0xbfb8aa3b, v27
	v_exp_f32_e32 v32, v32
	v_exp_f32_e32 v33, v33
	v_exp_f32_e32 v34, v34
	v_exp_f32_e32 v35, v35
	v_add_f32_e32 v38, 1.0, v38
	v_add_f32_e32 v39, 1.0, v39
	v_rcp_f32_e32 v38, v38
	v_rcp_f32_e32 v39, v39
	v_add_f32_e32 v40, 1.0, v40
	v_add_f32_e32 v41, 1.0, v41
	v_add_f32_e32 v32, 1.0, v32
	v_add_f32_e32 v33, 1.0, v33
	v_add_f32_e32 v34, 1.0, v34
	v_add_f32_e32 v35, 1.0, v35
	v_rcp_f32_e32 v40, v40
	v_rcp_f32_e32 v41, v41
	v_rcp_f32_e32 v32, v32
	v_rcp_f32_e32 v33, v33
	v_rcp_f32_e32 v34, v34
	v_rcp_f32_e32 v35, v35
	v_pk_mul_f32 v[28:29], v[28:29], v[38:39]
	v_pk_mul_f32 v[20:21], v[20:21], v[156:157] op_sel_hi:[1,0]
	v_pk_mul_f32 v[30:31], v[30:31], v[40:41]
	v_pk_mul_f32 v[22:23], v[22:23], v[156:157] op_sel_hi:[1,0]
	v_pk_mul_f32 v[20:21], v[20:21], v[28:29]
	v_pk_mul_f32 v[24:25], v[24:25], v[32:33]
	v_pk_mul_f32 v[26:27], v[26:27], v[34:35]
	v_pk_mul_f32 v[16:17], v[16:17], v[156:157] op_sel_hi:[1,0]
	v_pk_mul_f32 v[18:19], v[18:19], v[156:157] op_sel_hi:[1,0]
	v_pk_mul_f32 v[22:23], v[22:23], v[30:31]
	v_pk_mul_f32 v[26:27], v[18:19], v[26:27]
	v_pk_mul_f32 v[18:19], v[16:17], v[24:25]
	v_cvt_pk_bf16_f32 v16, v20, v21
	v_mad_i64_i32 v[20:21], s[46:47], v148, s60, v[112:113]
	v_pk_mul_f32 v[12:13], v[12:13], v[152:153] op_sel_hi:[1,0]
	v_cvt_pk_bf16_f32 v17, v22, v23
	v_cvt_pk_bf16_f32 v18, v18, v19
	v_cvt_pk_bf16_f32 v19, v26, v27
	v_lshl_add_u64 v[20:21], v[20:21], 0, v[114:115]
	v_mul_f32_e32 v22, 0xbfb8aa3b, v12
	v_mul_f32_e32 v23, 0xbfb8aa3b, v13
	v_pk_mul_f32 v[8:9], v[8:9], v[152:153] op_sel_hi:[1,0]
	v_pk_mul_f32 v[10:11], v[10:11], v[152:153] op_sel_hi:[1,0]
	v_exp_f32_e32 v22, v22
	v_exp_f32_e32 v23, v23
	global_store_dwordx4 v[20:21], v[16:19], off
	v_pk_mul_f32 v[14:15], v[14:15], v[152:153] op_sel_hi:[1,0]
	v_add_f32_e32 v22, 1.0, v22
	v_mul_f32_e32 v16, 0xbfb8aa3b, v8
	v_mul_f32_e32 v17, 0xbfb8aa3b, v9
	v_mul_f32_e32 v18, 0xbfb8aa3b, v10
	v_mul_f32_e32 v19, 0xbfb8aa3b, v11
	v_exp_f32_e32 v16, v16
	v_exp_f32_e32 v17, v17
	v_exp_f32_e32 v18, v18
	v_exp_f32_e32 v19, v19
	v_mul_f32_e32 v24, 0xbfb8aa3b, v14
	v_mul_f32_e32 v25, 0xbfb8aa3b, v15
	v_exp_f32_e32 v24, v24
	v_exp_f32_e32 v25, v25
	v_add_f32_e32 v23, 1.0, v23
	v_rcp_f32_e32 v22, v22
	v_rcp_f32_e32 v23, v23
	v_add_f32_e32 v16, 1.0, v16
	v_add_f32_e32 v17, 1.0, v17
	v_add_f32_e32 v18, 1.0, v18
	v_add_f32_e32 v19, 1.0, v19
	v_rcp_f32_e32 v16, v16
	v_rcp_f32_e32 v17, v17
	v_rcp_f32_e32 v18, v18
	v_rcp_f32_e32 v19, v19
	v_add_f32_e32 v24, 1.0, v24
	v_add_f32_e32 v25, 1.0, v25
	v_rcp_f32_e32 v24, v24
	v_rcp_f32_e32 v25, v25
	v_pk_mul_f32 v[12:13], v[12:13], v[22:23]
	v_pk_mul_f32 v[4:5], v[4:5], v[152:153] op_sel_hi:[1,0]
	v_pk_mul_f32 v[8:9], v[8:9], v[16:17]
	v_pk_mul_f32 v[4:5], v[4:5], v[12:13]
	v_pk_mul_f32 v[10:11], v[10:11], v[18:19]
	v_pk_mul_f32 v[0:1], v[0:1], v[152:153] op_sel_hi:[1,0]
	v_pk_mul_f32 v[2:3], v[2:3], v[152:153] op_sel_hi:[1,0]
	v_pk_mul_f32 v[14:15], v[14:15], v[24:25]
	v_pk_mul_f32 v[10:11], v[2:3], v[10:11]
	v_pk_mul_f32 v[2:3], v[0:1], v[8:9]
	v_cvt_pk_bf16_f32 v0, v4, v5
	v_mad_i64_i32 v[4:5], s[46:47], v146, s60, v[112:113]
	v_pk_mul_f32 v[6:7], v[6:7], v[152:153] op_sel_hi:[1,0]
	v_lshl_add_u64 v[4:5], v[4:5], 0, v[114:115]
	v_pk_mul_f32 v[6:7], v[6:7], v[14:15]
	s_nop 0
	v_cvt_pk_bf16_f32 v1, v6, v7
	v_cvt_pk_bf16_f32 v2, v2, v3
	v_cvt_pk_bf16_f32 v3, v10, v11
	global_store_dwordx4 v[4:5], v[0:3], off
.Lhh2_epi_end:
	s_cbranch_vccnz .LBB0_1584
	s_andn2_b64 vcc, exec, s[14:15]
	s_cbranch_vccnz .LBB0_1583
	s_barrier
	s_branch .LBB0_1583

;     __device__ bool next(int i, Unit& u) const { if (i > 0) return false; const int t = c - first; if (t < 0 || t >= nM * nN) return false; u.pm = t % nM; u.pn = t / nM; return true; }
;     __host__ __device__ bool next(int i, Unit& u) const {
;         const long L = (long)i * G + c; if (L >= nwg) return false;
;         int wgid = (int)L; { const int q = nwg / NXCD, r = nwg % NXCD, xcd = wgid % NXCD, off = wgid / NXCD; wgid = (xcd < r ? xcd * (q + 1) : r * (q + 1) + (xcd - r) * q) + off; }
;         const int nig = WGM * nN, gid = wgid / nig, fm = gid * WGM, gsz = (nM - fm) < WGM ? (nM - fm) : WGM;
;         u.pm = fm + ((wgid % nig) % gsz); u.pn = (wgid % nig) / gsz; return true;
;     }
; template <class Epi, class Sched, bool ALIGN_EPI = false, bool SP2 = false>
; __device__ __forceinline__ void gemm_phase(PG8_LAS unsigned char* lds, const Gemm g, const Sched& S, const Epi& E, int tid_in) {
;     ...
; #pragma unroll
;         for (int a = 0; a < 2; ++a)
; #pragma unroll
;             for (int b = 0; b < 2; ++b)
; #pragma unroll
;                 for (int m = 0; m < 4; ++m)
; #pragma unroll
;                     for (int n = 0; n < 2; ++n) acc[a][b][m][n] = (f32x4){0.f, 0.f, 0.f, 0.f};
;         cur = nxt; cA = nA; cB = nB; ++ui;
.LBB0_2037:
	s_add_i32 s40, s40, 1
	s_mul_i32 s6, s40, s43
	s_mul_hi_u32 s7, s40, s44
	s_add_i32 s7, s7, s6
	s_mul_i32 s6, s40, s44
	s_add_u32 s20, s6, s2
	s_addc_u32 s21, s7, s30
	s_cmp_ge_u32 s20, 0x580
	s_cselect_b32 s99, 0x40000, 0
	s_cselect_b32 s98, 0x80, 0
	s_sub_u32 s20, s20, s98
	v_cmp_gt_i64_e32 vcc, s[20:21], v[144:145]
	v_cmp_lt_i64_e64 s[6:7], s[20:21], v[142:143]
	s_cbranch_vccnz .LBB0_2039
	s_ashr_i32 s16, s20, 31
	s_lshr_b32 s16, s16, 29
	s_add_i32 s16, s20, s16
	s_ashr_i32 s17, s16, 3
	s_and_b32 s16, s16, -8
	s_sub_i32 s16, s20, s16
	s_cmp_lt_i32 s16, 0
	s_cselect_b32 s18, s31, 0xb0
	s_mul_i32 s16, s18, s16
	s_add_i32 s16, s16, s17
	s_mul_hi_i32 s17, s16, 0x2e8ba2e9
	s_lshr_b32 s18, s17, 31
	s_ashr_i32 s17, s17, 5
	s_add_i32 s17, s17, s18
	s_lshl_b32 s18, s17, 3
	s_sub_i32 s19, 64, s18
	s_min_i32 s19, s19, 8
	s_abs_i32 s20, s19
	v_cvt_f32_u32_e32 v0, s20
	s_sub_i32 s22, 0, s20
	s_mulk_i32 s17, 0xb0
	s_sub_i32 s17, s16, s17
	v_rcp_iflag_f32_e32 v0, v0
	s_abs_i32 s16, s17
	s_xor_b32 s21, s17, s19
	s_ashr_i32 s21, s21, 31
	v_mul_f32_e32 v0, 0x4f7ffffe, v0
	v_cvt_u32_f32_e32 v0, v0
	s_nop 0
	v_readfirstlane_b32 s23, v0
	s_mul_i32 s22, s22, s23
	s_mul_hi_u32 s22, s23, s22
	s_add_i32 s23, s23, s22
	s_mul_hi_u32 s22, s16, s23
	s_mul_i32 s23, s22, s20
	s_sub_i32 s16, s16, s23
	s_add_i32 s36, s22, 1
	s_sub_i32 s23, s16, s20
	s_cmp_ge_u32 s16, s20
	s_cselect_b32 s22, s36, s22
	s_cselect_b32 s16, s23, s16
	s_add_i32 s23, s22, 1
	s_cmp_ge_u32 s16, s20
	s_cselect_b32 s16, s23, s22
	s_xor_b32 s16, s16, s21
	s_sub_i32 s16, s16, s21
	s_mul_i32 s19, s16, s19
	s_sub_i32 s17, s17, s19
	s_add_i32 s18, s17, s18
.LBB0_2039:
	s_ashr_i32 s19, s18, 31
	s_lshl_b64 s[20:21], s[18:19], 19
	s_add_u32 s20, s0, s20
	s_addc_u32 s21, s1, s21
	s_add_u32 s20, s20, s99
	s_addc_u32 s21, s21, 0
	s_and_b64 s[22:23], s[6:7], exec
	s_cselect_b32 s19, s21, s35
	s_cselect_b32 s49, s20, s34
	s_ashr_i32 s17, s16, 31
	s_lshl_b64 s[22:23], s[16:17], 19
	s_add_u32 s22, s3, s22
	s_addc_u32 s23, s4, s23
	s_and_b64 s[36:37], s[6:7], exec
	s_cselect_b32 s17, s23, s27
	s_cselect_b32 s50, s22, s26
	s_add_u32 s51, s26, 0x100
	s_addc_u32 s52, s27, 0
	s_add_u32 s26, s34, 0x40080
	v_mov_b32_e32 v0, 0
	s_addc_u32 s27, s35, 0
	s_mov_b32 s53, -2
	v_mov_b32_e32 v1, v0
	v_mov_b32_e32 v2, v0
	v_mov_b32_e32 v3, v0
	v_mov_b32_e32 v4, v0
	v_mov_b32_e32 v5, v0
	v_mov_b32_e32 v6, v0
	v_mov_b32_e32 v7, v0
	v_mov_b32_e32 v16, v0
	v_mov_b32_e32 v17, v0
	v_mov_b32_e32 v18, v0
	v_mov_b32_e32 v19, v0
	v_mov_b32_e32 v20, v0
	v_mov_b32_e32 v21, v0
	v_mov_b32_e32 v22, v0
	v_mov_b32_e32 v23, v0
	v_mov_b32_e32 v32, v0
	v_mov_b32_e32 v33, v0
	v_mov_b32_e32 v34, v0
	v_mov_b32_e32 v35, v0
	v_mov_b32_e32 v36, v0
	v_mov_b32_e32 v37, v0
	v_mov_b32_e32 v38, v0
	v_mov_b32_e32 v39, v0
	v_mov_b32_e32 v48, v0
	v_mov_b32_e32 v49, v0
	v_mov_b32_e32 v50, v0
	v_mov_b32_e32 v51, v0
	v_mov_b32_e32 v52, v0
	v_mov_b32_e32 v53, v0
	v_mov_b32_e32 v54, v0
	v_mov_b32_e32 v55, v0
	v_mov_b32_e32 v8, v0
	v_mov_b32_e32 v9, v0
	v_mov_b32_e32 v10, v0
	v_mov_b32_e32 v11, v0
	v_mov_b32_e32 v12, v0
	v_mov_b32_e32 v13, v0
	v_mov_b32_e32 v14, v0
	v_mov_b32_e32 v15, v0
	v_mov_b32_e32 v24, v0
	v_mov_b32_e32 v25, v0
	v_mov_b32_e32 v26, v0
	v_mov_b32_e32 v27, v0
	v_mov_b32_e32 v28, v0
	v_mov_b32_e32 v29, v0
	v_mov_b32_e32 v30, v0
	v_mov_b32_e32 v31, v0
	v_mov_b32_e32 v40, v0
	v_mov_b32_e32 v41, v0
	v_mov_b32_e32 v42, v0
	v_mov_b32_e32 v43, v0
	v_mov_b32_e32 v44, v0
	v_mov_b32_e32 v45, v0
	v_mov_b32_e32 v46, v0
	v_mov_b32_e32 v47, v0
	v_mov_b32_e32 v56, v0
	v_mov_b32_e32 v57, v0
	v_mov_b32_e32 v58, v0
	v_mov_b32_e32 v59, v0
	v_mov_b32_e32 v60, v0
	v_mov_b32_e32 v61, v0
	v_mov_b32_e32 v62, v0
	v_mov_b32_e32 v63, v0
	v_mov_b32_e32 v64, v0
	v_mov_b32_e32 v65, v0
	v_mov_b32_e32 v66, v0
	v_mov_b32_e32 v67, v0
	v_mov_b32_e32 v68, v0
	v_mov_b32_e32 v69, v0
	v_mov_b32_e32 v70, v0
	v_mov_b32_e32 v71, v0
	v_mov_b32_e32 v80, v0
	v_mov_b32_e32 v81, v0
	v_mov_b32_e32 v82, v0
	v_mov_b32_e32 v83, v0
	v_mov_b32_e32 v84, v0
	v_mov_b32_e32 v85, v0
	v_mov_b32_e32 v86, v0
	v_mov_b32_e32 v87, v0
	v_mov_b32_e32 v96, v0
	v_mov_b32_e32 v97, v0
	v_mov_b32_e32 v98, v0
	v_mov_b32_e32 v99, v0
	v_mov_b32_e32 v100, v0
	v_mov_b32_e32 v101, v0
	v_mov_b32_e32 v102, v0
	v_mov_b32_e32 v103, v0
	v_mov_b32_e32 v112, v0
	v_mov_b32_e32 v113, v0
	v_mov_b32_e32 v114, v0
	v_mov_b32_e32 v115, v0
	v_mov_b32_e32 v116, v0
	v_mov_b32_e32 v117, v0
	v_mov_b32_e32 v118, v0
	v_mov_b32_e32 v119, v0
	v_mov_b32_e32 v72, v0
	v_mov_b32_e32 v73, v0
	v_mov_b32_e32 v74, v0
	v_mov_b32_e32 v75, v0
	v_mov_b32_e32 v76, v0
	v_mov_b32_e32 v77, v0
	v_mov_b32_e32 v78, v0
	v_mov_b32_e32 v79, v0
	v_mov_b32_e32 v88, v0
	v_mov_b32_e32 v89, v0
	v_mov_b32_e32 v90, v0
	v_mov_b32_e32 v91, v0
	v_mov_b32_e32 v92, v0
	v_mov_b32_e32 v93, v0
	v_mov_b32_e32 v94, v0
	v_mov_b32_e32 v95, v0
	v_mov_b32_e32 v104, v0
	v_mov_b32_e32 v105, v0
	v_mov_b32_e32 v106, v0
	v_mov_b32_e32 v107, v0
	v_mov_b32_e32 v108, v0
	v_mov_b32_e32 v109, v0
	v_mov_b32_e32 v110, v0
	v_mov_b32_e32 v111, v0
	v_mov_b32_e32 v120, v0
	v_mov_b32_e32 v121, v0
	v_mov_b32_e32 v122, v0
	v_mov_b32_e32 v123, v0
	v_mov_b32_e32 v124, v0
	v_mov_b32_e32 v125, v0
	v_mov_b32_e32 v126, v0
	v_mov_b32_e32 v127, v0
	v_readlane_b32 s98, v252, 5
	s_nop 1
	s_lshl_b32 s98, s98, 5
	s_add_i32 m0, s98, 0x20080
	s_lshl_b32 s98, s24, 14
	s_add_u32 s98, s100, s98
	s_addc_u32 s99, s101, 0
	global_load_lds_dwordx4 v238, s[98:99]
	global_load_lds_dwordx4 v238, s[98:99] offset:1024
	s_cmp_eq_u32 s40, 6
	s_cbranch_scc1 .Lhh3_2040

; #define PG8_STAGE(bufoff, gbase, voff) do { _Pragma("unroll") for (int _i = 0; _i < 2; ++_i) \
;         __builtin_amdgcn_global_load_lds((const unsigned*)((const char*)(gbase) + (voff)[_i]), (PG8_LAS unsigned*)(lds + (bufoff) + ldsw + _i * 8192), 16, 0, 0); } while (0)
; #define PG8_LDA(dst, b, h) do { _Pragma("unroll") for (int m = 0; m < 4; ++m) _Pragma("unroll") for (int k = 0; k < 2; ++k) dst[m][k] = *(const PG8_LAS bf16x8*)(lds + PG8_SA(b, h) + aoff + m * 2048 + k * 1024); } while (0)
; #define PG8_WAIT_V(n) asm volatile("s_waitcnt vmcnt(" #n ")" ::: "memory")
; #define PG8_WAIT_L(n) asm volatile("s_waitcnt lgkmcnt(" #n ")" ::: "memory")
; #define PG8_BAR __builtin_amdgcn_s_barrier()
; template <class Epi, class Sched, bool ALIGN_EPI = false, bool SP2 = false>
; __device__ __forceinline__ void gemm_phase(PG8_LAS unsigned char* lds, const Gemm g, const Sched& S, const Epi& E, int tid_in) {
;     ...
;         for (int t = 0; t < nt; t += 2) {
;             const bool last = (t == nt - 2);
;             const char* a1 = cA + (size_t)(t + 1) * kstep;
;             const char* a2 = last ? nA : cA + (size_t)(t + 2) * kstep; const char* b2 = last ? nB : cB + (size_t)(t + 2) * kstep;
;             const char* a3 = a2 + kstep; const char* b3 = b2 + kstep;
;             if (last && has_next) S.a_ready(nxt);
;             if constexpr (SP2) {
;             PG8_LDB(B0, 0, 0); PG8_LDB(B1, 0, 1); PG8_SCHED; PG8_LDA(At, 0, 0); PG8_STAGE(PG8_SA(1, 1), a1 + hstep, voffA);
;             PG8_WAIT_V(8); PG8_WAIT_L(0); PG8_BAR; PG8_MMA(0, 0, At, B0); PG8_MMA(0, 1, At, B1); PG8_BAR; PG8_SCHED;
;             PG8_LDA(At, 0, 1); PG8_STAGE(PG8_SB(0, 0), b2, voffB); PG8_STAGE(PG8_SB(0, 1), b2 + hstep, voffB); PG8_STAGE(PG8_SA(0, 0), a2, voffA);
;             PG8_WAIT_V(8); PG8_WAIT_L(0); PG8_BAR; PG8_MMA(1, 0, At, B0); PG8_MMA(1, 1, At, B1); PG8_BAR; PG8_SCHED;
;             PG8_LDB(B0, 1, 0); PG8_LDB(B1, 1, 1); PG8_SCHED; PG8_LDA(At, 1, 0); PG8_STAGE(PG8_SA(0, 1), a2 + hstep, voffA);
;             PG8_WAIT_V(8); PG8_WAIT_L(0); PG8_BAR; PG8_MMA(0, 0, At, B0); PG8_MMA(0, 1, At, B1); PG8_BAR; PG8_SCHED;
;             PG8_LDA(At, 1, 1); PG8_STAGE(PG8_SB(1, 0), b3, voffB); PG8_STAGE(PG8_SB(1, 1), b3 + hstep, voffB); PG8_STAGE(PG8_SA(1, 0), a3, voffA);
;             PG8_WAIT_V(8); PG8_WAIT_L(0); PG8_BAR; PG8_MMA(1, 0, At, B0); PG8_MMA(1, 1, At, B1); PG8_BAR; PG8_SCHED;
.Lhh3_2040:
	ds_read_b128 v[146:149], v165
	ds_read_b128 v[176:179], v165 offset:1024
	ds_read_b128 v[180:183], v165 offset:2048
	ds_read_b128 v[184:187], v165 offset:3072
	ds_read_b128 v[188:191], v169
	ds_read_b128 v[192:195], v169 offset:1024
	ds_read_b128 v[196:199], v169 offset:2048
	ds_read_b128 v[202:205], v169 offset:3072
	s_add_u32 s34, s26, 0xfffc0080
	s_addc_u32 s35, s27, -1
	s_cmp_eq_u32 s53, 12
	s_cselect_b32 s37, s19, s35
	s_cselect_b32 s36, s49, s34
	s_cselect_b32 s35, s17, s52
	s_cselect_b32 s34, s50, s51
	v_lshl_add_u64 v[150:151], s[26:27], 0, v[140:141]
	s_add_i32 m0, s25, 0xc000
	ds_read_b128 v[206:209], v173
	ds_read_b128 v[210:213], v173 offset:1024
	ds_read_b128 v[214:217], v173 offset:2048
	ds_read_b128 v[218:221], v173 offset:3072
	ds_read_b128 v[222:225], v173 offset:4096
	ds_read_b128 v[226:229], v173 offset:5120
	ds_read_b128 v[230:233], v173 offset:6144
	ds_read_b128 v[234:237], v173 offset:7168
	global_load_lds_dwordx4 v[150:151], off
	v_lshl_add_u64 v[150:151], s[26:27], 0, v[138:139]
	s_add_i32 m0, s25, 0xe000
	s_nop 0
	global_load_lds_dwordx4 v[150:151], off
	s_waitcnt vmcnt(8)
	s_waitcnt lgkmcnt(0)
	s_barrier
	s_setprio 1
	s_waitcnt lgkmcnt(0)
	v_mfma_f32_16x16x32_bf16 v[124:127], v[146:149], v[206:209], v[124:127]
	v_mfma_f32_16x16x32_bf16 v[120:123], v[180:183], v[206:209], v[120:123]
	v_mfma_f32_16x16x32_bf16 v[108:111], v[146:149], v[214:217], v[108:111]
	v_mfma_f32_16x16x32_bf16 v[104:107], v[180:183], v[214:217], v[104:107]
	v_mfma_f32_16x16x32_bf16 v[92:95], v[146:149], v[222:225], v[92:95]
	v_mfma_f32_16x16x32_bf16 v[88:91], v[180:183], v[222:225], v[88:91]
	v_mfma_f32_16x16x32_bf16 v[76:79], v[146:149], v[230:233], v[76:79]
	v_mfma_f32_16x16x32_bf16 v[72:75], v[180:183], v[230:233], v[72:75]
	v_mfma_f32_16x16x32_bf16 v[124:127], v[176:179], v[210:213], v[124:127]
	v_mfma_f32_16x16x32_bf16 v[120:123], v[184:187], v[210:213], v[120:123]
	v_mfma_f32_16x16x32_bf16 v[108:111], v[176:179], v[218:221], v[108:111]
	v_mfma_f32_16x16x32_bf16 v[104:107], v[184:187], v[218:221], v[104:107]
	v_mfma_f32_16x16x32_bf16 v[92:95], v[176:179], v[226:229], v[92:95]
	v_mfma_f32_16x16x32_bf16 v[88:91], v[184:187], v[226:229], v[88:91]
	v_mfma_f32_16x16x32_bf16 v[76:79], v[176:179], v[234:237], v[76:79]
	v_mfma_f32_16x16x32_bf16 v[72:75], v[184:187], v[234:237], v[72:75]
	s_setprio 0
	s_setprio 1
	v_mfma_f32_16x16x32_bf16 v[116:119], v[188:191], v[206:209], v[116:119]
	v_mfma_f32_16x16x32_bf16 v[112:115], v[196:199], v[206:209], v[112:115]
	v_mfma_f32_16x16x32_bf16 v[100:103], v[188:191], v[214:217], v[100:103]
	v_mfma_f32_16x16x32_bf16 v[96:99], v[196:199], v[214:217], v[96:99]
	v_mfma_f32_16x16x32_bf16 v[84:87], v[188:191], v[222:225], v[84:87]
	v_mfma_f32_16x16x32_bf16 v[80:83], v[196:199], v[222:225], v[80:83]
	v_mfma_f32_16x16x32_bf16 v[68:71], v[188:191], v[230:233], v[68:71]
	v_mfma_f32_16x16x32_bf16 v[64:67], v[196:199], v[230:233], v[64:67]
	v_mfma_f32_16x16x32_bf16 v[116:119], v[192:195], v[210:213], v[116:119]
	v_mfma_f32_16x16x32_bf16 v[112:115], v[202:205], v[210:213], v[112:115]
	v_mfma_f32_16x16x32_bf16 v[100:103], v[192:195], v[218:221], v[100:103]
	v_mfma_f32_16x16x32_bf16 v[96:99], v[202:205], v[218:221], v[96:99]
	v_mfma_f32_16x16x32_bf16 v[84:87], v[192:195], v[226:229], v[84:87]
	v_mfma_f32_16x16x32_bf16 v[80:83], v[202:205], v[226:229], v[80:83]
	v_mfma_f32_16x16x32_bf16 v[68:71], v[192:195], v[234:237], v[68:71]
	v_mfma_f32_16x16x32_bf16 v[64:67], v[202:205], v[234:237], v[64:67]
	s_setprio 0
	s_barrier
	s_add_i32 s54, s45, s5
	v_lshl_add_u64 v[150:151], s[34:35], 0, v[132:133]
	s_mov_b32 m0, s54
	s_nop 0
	global_load_lds_dwordx4 v[150:151], off
	s_add_i32 m0, s54, 0x2000
	s_add_u32 s54, s34, 0x40000
	v_lshl_add_u64 v[154:155], s[34:35], 0, v[128:129]
	s_addc_u32 s55, s35, 0
	s_add_i32 s56, s46, s5
	global_load_lds_dwordx4 v[154:155], off
	v_lshl_add_u64 v[158:159], s[54:55], 0, v[132:133]
	s_mov_b32 m0, s56
	v_lshl_add_u64 v[162:163], s[36:37], 0, v[130:131]
	global_load_lds_dwordx4 v[158:159], off
	v_lshl_add_u64 v[158:159], s[54:55], 0, v[128:129]
	s_add_i32 m0, s56, 0x2000
	s_nop 0
	global_load_lds_dwordx4 v[158:159], off
	v_lshl_add_u64 v[158:159], s[36:37], 0, v[134:135]
	s_mov_b32 m0, s25
	s_nop 0
	global_load_lds_dwordx4 v[158:159], off
	s_mov_b32 m0, s33
	s_nop 0
	global_load_lds_dwordx4 v[162:163], off
	s_waitcnt vmcnt(8)
	s_waitcnt lgkmcnt(0)
	s_barrier
	s_setprio 1
	s_waitcnt lgkmcnt(0)
	s_setprio 0
	s_setprio 1
	s_setprio 0
	s_barrier
	s_add_i32 s54, 0, 0x18000
	v_add_u32_e32 v152, s54, v157
	s_add_i32 s55, 0, 0x1c000
	ds_read_b128 v[146:149], v152
	ds_read_b128 v[176:179], v152 offset:1024
	ds_read_b128 v[180:183], v152 offset:2048
	ds_read_b128 v[184:187], v152 offset:3072
	v_add_u32_e32 v152, s55, v157
	ds_read_b128 v[188:191], v152
	ds_read_b128 v[192:195], v152 offset:1024
	ds_read_b128 v[196:199], v152 offset:2048
	ds_read_b128 v[202:205], v152 offset:3072
	s_add_u32 s36, s36, 0x40000
	s_addc_u32 s37, s37, 0
	s_mov_b32 m0, s38
	v_lshl_add_u64 v[166:167], s[36:37], 0, v[134:135]
	ds_read_b128 v[206:209], v173 offset:32768
	ds_read_b128 v[210:213], v173 offset:33792
	ds_read_b128 v[214:217], v173 offset:34816
	ds_read_b128 v[218:221], v173 offset:35840
	ds_read_b128 v[222:225], v173 offset:36864
	ds_read_b128 v[226:229], v173 offset:37888
	ds_read_b128 v[230:233], v173 offset:38912
	ds_read_b128 v[234:237], v173 offset:39936
	global_load_lds_dwordx4 v[166:167], off
	v_lshl_add_u64 v[166:167], s[36:37], 0, v[130:131]
	s_mov_b32 m0, s39
	s_nop 0
	global_load_lds_dwordx4 v[166:167], off
	s_waitcnt vmcnt(8)
	s_waitcnt lgkmcnt(0)
	s_barrier
; __device__ __forceinline__ float row_part(const float* ss, int row, int fq) { const f32x4 a = ((const f32x4*)(ss + (size_t)row * 16))[fq]; return (a[0] + a[1]) + (a[2] + a[3]); }
; __device__ __forceinline__ float row_finish(float t) { t += shx(t, 16); t += shx(t, 32); return __builtin_amdgcn_rsqf(t * (1.0f / 1024.0f) + RMS_EPS); }
; #define PG8_STAGE(bufoff, gbase, voff) do { _Pragma("unroll") for (int _i = 0; _i < 2; ++_i) \
;         __builtin_amdgcn_global_load_lds((const unsigned*)((const char*)(gbase) + (voff)[_i]), (PG8_LAS unsigned*)(lds + (bufoff) + ldsw + _i * 8192), 16, 0, 0); } while (0)
; #define PG8_LDA(dst, b, h) do { _Pragma("unroll") for (int m = 0; m < 4; ++m) _Pragma("unroll") for (int k = 0; k < 2; ++k) dst[m][k] = *(const PG8_LAS bf16x8*)(lds + PG8_SA(b, h) + aoff + m * 2048 + k * 1024); } while (0)
; #define PG8_WAIT_V(n) asm volatile("s_waitcnt vmcnt(" #n ")" ::: "memory")
; #define PG8_WAIT_L(n) asm volatile("s_waitcnt lgkmcnt(" #n ")" ::: "memory")
;     __device__ __forceinline__ void operator()(const f32x4 (&acc)[2][2][4][2], const Unit& u, int wr, int wc, int fr, int fq) const {
;         const int col0 = u.pn * 128 + 32 * wc + 8 * fq;
;         float rs[2][4];
; #pragma unroll
;         for (int ai = 0; ai < 2; ++ai)
; #pragma unroll
;             for (int m = 0; m < 4; ++m) rs[ai][m] = row_part(ss, u.pm * BM + ai * HALF + wr * 64 + m * 16 + fr, fq);
; #pragma unroll
;         for (int ai = 0; ai < 2; ++ai)
; #pragma unroll
;             for (int m = 0; m < 4; ++m) rs[ai][m] = row_finish(rs[ai][m]);
; template <class Epi, class Sched, bool ALIGN_EPI = false, bool SP2 = false>
; __device__ __forceinline__ void gemm_phase(PG8_LAS unsigned char* lds, const Gemm g, const Sched& S, const Epi& E, int tid_in) {
;     ...
;             PG8_WAIT_V(8); PG8_WAIT_L(0); PG8_BAR; PG8_MMA(1, 0, At, B0); PG8_MMA(1, 1, At, B1); PG8_BAR; PG8_SCHED;
;             PG8_LDB(B0, 1, 0); PG8_LDB(B1, 1, 1); PG8_SCHED; PG8_LDA(At, 1, 0); PG8_STAGE(PG8_SA(0, 1), a2 + hstep, voffA);
;             PG8_WAIT_V(8); PG8_WAIT_L(0); PG8_BAR; PG8_MMA(0, 0, At, B0); PG8_MMA(0, 1, At, B1); PG8_BAR; PG8_SCHED;
;             PG8_LDA(At, 1, 1); PG8_STAGE(PG8_SB(1, 0), b3, voffB); PG8_STAGE(PG8_SB(1, 1), b3 + hstep, voffB); PG8_STAGE(PG8_SA(1, 0), a3, voffA);
;             PG8_WAIT_V(8); PG8_WAIT_L(0); PG8_BAR; PG8_MMA(1, 0, At, B0); PG8_MMA(1, 1, At, B1); PG8_BAR; PG8_SCHED;
	s_setprio 1
	s_waitcnt lgkmcnt(0)
	v_mfma_f32_16x16x32_bf16 v[124:127], v[146:149], v[206:209], v[124:127]
	v_mfma_f32_16x16x32_bf16 v[120:123], v[180:183], v[206:209], v[120:123]
	v_mfma_f32_16x16x32_bf16 v[108:111], v[146:149], v[214:217], v[108:111]
	v_mfma_f32_16x16x32_bf16 v[104:107], v[180:183], v[214:217], v[104:107]
	v_mfma_f32_16x16x32_bf16 v[92:95], v[146:149], v[222:225], v[92:95]
	v_mfma_f32_16x16x32_bf16 v[88:91], v[180:183], v[222:225], v[88:91]
	v_mfma_f32_16x16x32_bf16 v[76:79], v[146:149], v[230:233], v[76:79]
	v_mfma_f32_16x16x32_bf16 v[72:75], v[180:183], v[230:233], v[72:75]
	v_mfma_f32_16x16x32_bf16 v[124:127], v[176:179], v[210:213], v[124:127]
	v_mfma_f32_16x16x32_bf16 v[120:123], v[184:187], v[210:213], v[120:123]
	v_mfma_f32_16x16x32_bf16 v[108:111], v[176:179], v[218:221], v[108:111]
	v_mfma_f32_16x16x32_bf16 v[104:107], v[184:187], v[218:221], v[104:107]
	v_mfma_f32_16x16x32_bf16 v[92:95], v[176:179], v[226:229], v[92:95]
	v_mfma_f32_16x16x32_bf16 v[88:91], v[184:187], v[226:229], v[88:91]
	v_mfma_f32_16x16x32_bf16 v[76:79], v[176:179], v[234:237], v[76:79]
	v_mfma_f32_16x16x32_bf16 v[72:75], v[184:187], v[234:237], v[72:75]
	s_setprio 0
	s_setprio 1
	v_mfma_f32_16x16x32_bf16 v[116:119], v[188:191], v[206:209], v[116:119]
	v_mfma_f32_16x16x32_bf16 v[112:115], v[196:199], v[206:209], v[112:115]
	v_mfma_f32_16x16x32_bf16 v[100:103], v[188:191], v[214:217], v[100:103]
	v_mfma_f32_16x16x32_bf16 v[96:99], v[196:199], v[214:217], v[96:99]
	v_mfma_f32_16x16x32_bf16 v[84:87], v[188:191], v[222:225], v[84:87]
	v_mfma_f32_16x16x32_bf16 v[80:83], v[196:199], v[222:225], v[80:83]
	v_mfma_f32_16x16x32_bf16 v[68:71], v[188:191], v[230:233], v[68:71]
	v_mfma_f32_16x16x32_bf16 v[64:67], v[196:199], v[230:233], v[64:67]
	v_mfma_f32_16x16x32_bf16 v[116:119], v[192:195], v[210:213], v[116:119]
	v_mfma_f32_16x16x32_bf16 v[112:115], v[202:205], v[210:213], v[112:115]
	v_mfma_f32_16x16x32_bf16 v[100:103], v[192:195], v[218:221], v[100:103]
	v_mfma_f32_16x16x32_bf16 v[96:99], v[202:205], v[218:221], v[96:99]
	v_mfma_f32_16x16x32_bf16 v[84:87], v[192:195], v[226:229], v[84:87]
	v_mfma_f32_16x16x32_bf16 v[80:83], v[202:205], v[226:229], v[80:83]
	v_mfma_f32_16x16x32_bf16 v[68:71], v[192:195], v[234:237], v[68:71]
	v_mfma_f32_16x16x32_bf16 v[64:67], v[202:205], v[234:237], v[64:67]
	s_setprio 0
	s_barrier
	s_add_i32 s36, s54, s5
	v_lshl_add_u64 v[150:151], v[150:151], 0, s[12:13]
	s_mov_b32 m0, s36
	s_nop 0
	global_load_lds_dwordx4 v[150:151], off
	s_add_i32 m0, s36, 0x2000
	s_add_u32 s34, s34, 0x40080
	v_lshl_add_u64 v[150:151], v[154:155], 0, s[12:13]
	s_addc_u32 s35, s35, 0
	s_add_i32 s36, s55, s5
	global_load_lds_dwordx4 v[150:151], off
	v_lshl_add_u64 v[150:151], s[34:35], 0, v[132:133]
	s_mov_b32 m0, s36
	s_nop 0
	global_load_lds_dwordx4 v[150:151], off
	v_lshl_add_u64 v[150:151], s[34:35], 0, v[128:129]
	s_add_i32 m0, s36, 0x2000
	s_nop 0
	global_load_lds_dwordx4 v[150:151], off
	v_lshl_add_u64 v[150:151], v[158:159], 0, s[12:13]
	s_mov_b32 m0, s41
	s_nop 0
	global_load_lds_dwordx4 v[150:151], off
	v_lshl_add_u64 v[150:151], v[162:163], 0, s[12:13]
	s_mov_b32 m0, s42
	s_nop 0
	global_load_lds_dwordx4 v[150:151], off
	s_waitcnt vmcnt(8)
	s_waitcnt lgkmcnt(0)
	s_barrier
	s_setprio 1
	s_waitcnt lgkmcnt(0)
	s_setprio 0
	s_setprio 1
	s_setprio 0
	s_barrier
	s_add_i32 s53, s53, 2
	s_add_u32 s51, s51, 0x100
	s_addc_u32 s52, s52, 0
	s_add_u32 s26, s26, 0x100
	s_addc_u32 s27, s27, 0
	s_cmp_gt_u32 s53, 13
	s_cbranch_scc0 .Lhh3_2040
	s_and_b64 vcc, exec, s[14:15]
	s_cbranch_vccz .Lhh3_2043
	s_barrier
.Lhh3_2043:
	v_lshl_add_u32 v170, s24, 8, v153
	s_cmp_ge_u32 s2, 0x80
	s_cselect_b32 s98, 0x80, 0
	v_add_u32_e32 v170, s98, v170
	s_lshl_b32 s99, s98, 6
	v_add_u32_e32 v241, s99, v239
	v_ashrrev_i32_e32 v171, 31, v170
	v_or_b32_e32 v166, 16, v170
	v_lshlrev_b64 v[146:147], 6, v[170:171]
	v_ashrrev_i32_e32 v167, 31, v166
	v_lshl_add_u64 v[146:147], v[136:137], 0, v[146:147]
	v_lshlrev_b64 v[148:149], 6, v[166:167]
	v_lshl_add_u64 v[148:149], v[136:137], 0, v[148:149]
	ds_read_b128 v[176:179], v241
	ds_read_b128 v[180:183], v241 offset:1024
	v_or_b32_e32 v162, 32, v170
	v_ashrrev_i32_e32 v163, 31, v162
	v_or_b32_e32 v158, 48, v170
	v_lshlrev_b64 v[146:147], 6, v[162:163]
	v_ashrrev_i32_e32 v159, 31, v158
	v_lshl_add_u64 v[146:147], v[136:137], 0, v[146:147]
	v_lshlrev_b64 v[148:149], 6, v[158:159]
	v_lshl_add_u64 v[148:149], v[136:137], 0, v[148:149]
	ds_read_b128 v[184:187], v241 offset:2048
	ds_read_b128 v[188:191], v241 offset:3072
	v_add_u32_e32 v154, 0x80, v170
	v_ashrrev_i32_e32 v155, 31, v154
	v_add_u32_e32 v150, 0x90, v170
	v_lshlrev_b64 v[146:147], 6, v[154:155]
	v_ashrrev_i32_e32 v151, 31, v150
	v_lshl_add_u64 v[146:147], v[136:137], 0, v[146:147]
	v_lshlrev_b64 v[148:149], 6, v[150:151]
	v_lshl_add_u64 v[148:149], v[136:137], 0, v[148:149]
	ds_read_b128 v[192:195], v241 offset:8192
	ds_read_b128 v[196:199], v241 offset:9216
	v_add_u32_e32 v148, 0xa0, v170
	v_ashrrev_i32_e32 v149, 31, v148
	v_lshlrev_b64 v[146:147], 6, v[148:149]
	v_lshl_add_u64 v[146:147], v[136:137], 0, v[146:147]
	ds_read_b128 v[202:205], v241 offset:10240
	v_add_u32_e32 v146, 0xb0, v170
	v_ashrrev_i32_e32 v147, 31, v146
	v_lshlrev_b64 v[206:207], 6, v[146:147]
	v_lshl_add_u64 v[206:207], v[136:137], 0, v[206:207]
	ds_read_b128 v[206:209], v241 offset:11264
	v_mov_b32_e32 v147, v201
	v_mov_b32_e32 v149, v201
	v_lshlrev_b32_e32 v147, 2, v147
	v_mov_b32_e32 v151, v201
	v_xor_b32_e32 v147, 64, v147
	s_andn2_b64 vcc, exec, s[6:7]
	v_lshlrev_b32_e32 v151, 2, v151
	v_xor_b32_e32 v151, 64, v151
	v_lshlrev_b32_e32 v149, 2, v149
	v_xor_b32_e32 v149, 0x80, v149
	s_mov_b64 s[6:7], -1
	s_waitcnt lgkmcnt(0)
; __device__ __forceinline__ float row_part(const float* ss, int row, int fq) { const f32x4 a = ((const f32x4*)(ss + (size_t)row * 16))[fq]; return (a[0] + a[1]) + (a[2] + a[3]); }
; __device__ __forceinline__ float row_finish(float t) { t += shx(t, 16); t += shx(t, 32); return __builtin_amdgcn_rsqf(t * (1.0f / 1024.0f) + RMS_EPS); }
;     __device__ __forceinline__ void operator()(const f32x4 (&acc)[2][2][4][2], const Unit& u, int wr, int wc, int fr, int fq) const {
;     ...
;         float rs[2][4];
; #pragma unroll
;         for (int ai = 0; ai < 2; ++ai)
; #pragma unroll
;             for (int m = 0; m < 4; ++m) rs[ai][m] = row_part(ss, u.pm * BM + ai * HALF + wr * 64 + m * 16 + fr, fq);
; #pragma unroll
;         for (int ai = 0; ai < 2; ++ai)
; #pragma unroll
;             for (int m = 0; m < 4; ++m) rs[ai][m] = row_finish(rs[ai][m]);
	v_mov_b32_e32 v210, v177
	v_mov_b32_e32 v211, v178
	v_mov_b32_e32 v177, v179
	v_pk_add_f32 v[176:177], v[210:211], v[176:177]
	v_mov_b32_e32 v178, v181
	v_add_f32_e32 v152, v176, v177
	v_mov_b32_e32 v179, v182
	v_mov_b32_e32 v181, v183
	ds_bpermute_b32 v147, v147, v152
	v_pk_add_f32 v[176:177], v[178:179], v[180:181]
	v_mov_b32_e32 v182, v185
	v_add_f32_e32 v155, v176, v177
	ds_bpermute_b32 v151, v151, v155
	s_waitcnt lgkmcnt(1)
	v_add_f32_e32 v147, v152, v147
	v_mov_b32_e32 v152, v201
	ds_bpermute_b32 v149, v149, v147
	s_waitcnt lgkmcnt(1)
	v_add_f32_e32 v151, v155, v151
	v_lshlrev_b32_e32 v152, 2, v152
	v_xor_b32_e32 v152, 0x80, v152
	ds_bpermute_b32 v152, v152, v151
	s_waitcnt lgkmcnt(1)
	v_add_f32_e32 v147, v147, v149
	v_mov_b32_e32 v149, v201
	v_mov_b32_e32 v183, v186
	v_mov_b32_e32 v185, v187
	v_pk_add_f32 v[178:179], v[182:183], v[184:185]
	v_fmamk_f32 v147, v147, 0x3a800000, v175
	v_lshlrev_b32_e32 v149, 2, v149
	v_add_f32_e32 v156, v178, v179
	v_rsq_f32_e32 v176, v147
	s_waitcnt lgkmcnt(0)
	v_add_f32_e32 v147, v151, v152
	v_xor_b32_e32 v149, 64, v149
	v_mov_b32_e32 v151, v201
	v_mov_b32_e32 v152, v201
	v_mov_b32_e32 v186, v189
	v_mov_b32_e32 v187, v190
	v_mov_b32_e32 v189, v191
	ds_bpermute_b32 v149, v149, v156
	v_pk_add_f32 v[180:181], v[186:187], v[188:189]
	v_lshlrev_b32_e32 v152, 2, v152
	v_add_f32_e32 v159, v180, v181
	v_xor_b32_e32 v152, 64, v152
	ds_bpermute_b32 v152, v152, v159
	s_waitcnt lgkmcnt(1)
	v_add_f32_e32 v149, v156, v149
	v_lshlrev_b32_e32 v151, 2, v151
	v_mov_b32_e32 v156, v201
	v_xor_b32_e32 v151, 0x80, v151
	ds_bpermute_b32 v151, v151, v149
	v_lshlrev_b32_e32 v156, 2, v156
	s_waitcnt lgkmcnt(1)
	v_add_f32_e32 v152, v159, v152
	v_xor_b32_e32 v156, 0x80, v156
	ds_bpermute_b32 v156, v156, v152
	v_fmamk_f32 v147, v147, 0x3a800000, v175
	v_rsq_f32_e32 v174, v147
	s_waitcnt lgkmcnt(1)
	v_add_f32_e32 v147, v149, v151
	v_mov_b32_e32 v149, v201
	v_mov_b32_e32 v190, v193
	v_mov_b32_e32 v191, v194
	v_mov_b32_e32 v193, v195
	v_fmamk_f32 v147, v147, 0x3a800000, v175
	v_pk_add_f32 v[182:183], v[190:191], v[192:193]
	v_rsq_f32_e32 v172, v147
	s_waitcnt lgkmcnt(0)
	v_add_f32_e32 v147, v152, v156
	v_lshlrev_b32_e32 v149, 2, v149
	v_mov_b32_e32 v151, v201
	v_mov_b32_e32 v152, v201
	v_mov_b32_e32 v194, v197
	v_mov_b32_e32 v195, v198
	v_mov_b32_e32 v197, v199
	v_add_f32_e32 v160, v182, v183
	v_xor_b32_e32 v149, 64, v149
	v_pk_add_f32 v[184:185], v[194:195], v[196:197]
	ds_bpermute_b32 v149, v149, v160
	v_lshlrev_b32_e32 v152, 2, v152
	v_add_f32_e32 v163, v184, v185
	v_xor_b32_e32 v152, 64, v152
	ds_bpermute_b32 v152, v152, v163
	v_lshlrev_b32_e32 v151, 2, v151
	v_mov_b32_e32 v156, v201
	s_waitcnt lgkmcnt(1)
	v_add_f32_e32 v149, v160, v149
	v_xor_b32_e32 v151, 0x80, v151
	ds_bpermute_b32 v151, v151, v149
	v_lshlrev_b32_e32 v156, 2, v156
	s_waitcnt lgkmcnt(1)
	v_add_f32_e32 v152, v163, v152
	v_xor_b32_e32 v156, 0x80, v156
	ds_bpermute_b32 v156, v156, v152
	v_fmamk_f32 v147, v147, 0x3a800000, v175
	v_rsq_f32_e32 v168, v147
	s_waitcnt lgkmcnt(1)
	v_add_f32_e32 v147, v149, v151
	v_fmamk_f32 v147, v147, 0x3a800000, v175
	v_rsq_f32_e32 v164, v147
	s_waitcnt lgkmcnt(0)
	v_add_f32_e32 v147, v152, v156
	v_mov_b32_e32 v149, v201
	v_mov_b32_e32 v151, v201
	v_mov_b32_e32 v152, v201
	v_mov_b32_e32 v198, v203
	v_mov_b32_e32 v199, v204
	v_mov_b32_e32 v203, v205
	v_mov_b32_e32 v204, v207
	v_mov_b32_e32 v205, v208
	v_mov_b32_e32 v207, v209
	v_pk_add_f32 v[188:189], v[204:205], v[206:207]
	v_lshlrev_b32_e32 v152, 2, v152
	v_pk_add_f32 v[186:187], v[198:199], v[202:203]
	v_add_f32_e32 v155, v188, v189
	v_lshlrev_b32_e32 v149, 2, v149
	v_xor_b32_e32 v152, 64, v152
	v_add_f32_e32 v167, v186, v187
	v_xor_b32_e32 v149, 64, v149
	ds_bpermute_b32 v152, v152, v155
	ds_bpermute_b32 v149, v149, v167
	v_lshlrev_b32_e32 v151, 2, v151
	v_xor_b32_e32 v151, 0x80, v151
	v_fmamk_f32 v147, v147, 0x3a800000, v175
	s_waitcnt lgkmcnt(1)
	v_add_f32_e32 v152, v155, v152
	v_mov_b32_e32 v155, v201
	s_waitcnt lgkmcnt(0)
	v_add_f32_e32 v149, v167, v149
	ds_bpermute_b32 v151, v151, v149
	v_lshlrev_b32_e32 v155, 2, v155
	v_xor_b32_e32 v155, 0x80, v155
	ds_bpermute_b32 v155, v155, v152
	v_rsq_f32_e32 v160, v147
	s_waitcnt lgkmcnt(1)
	v_add_f32_e32 v147, v149, v151
	v_fmamk_f32 v147, v147, 0x3a800000, v175
	v_rsq_f32_e32 v156, v147
	s_waitcnt lgkmcnt(0)
; __device__ __forceinline__ f32x4 silu4(f32x4 v) { return (f32x4){silu_f(v[0]), silu_f(v[1]), silu_f(v[2]), silu_f(v[3])}; }
; __device__ __forceinline__ u32x4 pack8(f32x4 a, f32x4 b) { u32x4 w; w.x = cvt_pk_bf16(a[0], a[1]); w.y = cvt_pk_bf16(a[2], a[3]); w.z = cvt_pk_bf16(b[0], b[1]); w.w = cvt_pk_bf16(b[2], b[3]); return w; }
; __device__ __forceinline__ float row_finish(float t) { t += shx(t, 16); t += shx(t, 32); return __builtin_amdgcn_rsqf(t * (1.0f / 1024.0f) + RMS_EPS); }
; __device__ __forceinline__ float silu_f(float v) { return v * __builtin_amdgcn_rcpf(1.0f + __builtin_amdgcn_exp2f(v * -1.4426950408889634f)); }
;     __device__ __forceinline__ void operator()(const f32x4 (&acc)[2][2][4][2], const Unit& u, int wr, int wc, int fr, int fq) const {
;     ...
;             for (int m = 0; m < 4; ++m) rs[ai][m] = row_finish(rs[ai][m]);
; #pragma unroll
;         for (int ai = 0; ai < 2; ++ai)
; #pragma unroll
;             for (int m = 0; m < 4; ++m) {
;                 const int row = u.pm * BM + ai * HALF + wr * 64 + m * 16 + fr;
;                 const float rstd = rs[ai][m];
;                 const f32x4 a0 = silu4(acc[ai][0][m][0] * rstd) * (acc[ai][1][m][0] * rstd);
;                 const f32x4 a1 = silu4(acc[ai][0][m][1] * rstd) * (acc[ai][1][m][1] * rstd);
;                 *(u32x4*)(ACT + (size_t)row * 2816 + col0) = pack8(a0, a1);
	v_add_f32_e32 v147, v152, v155
	v_fmamk_f32 v147, v147, 0x3a800000, v175
	v_pk_mul_f32 v[124:125], v[124:125], v[176:177] op_sel_hi:[1,0]
	v_rsq_f32_e32 v152, v147
	v_mul_f32_e32 v147, 0xbfb8aa3b, v124
	v_exp_f32_e32 v147, v147
	v_mul_f32_e32 v149, 0xbfb8aa3b, v125
	v_exp_f32_e32 v149, v149
	v_pk_mul_f32 v[126:127], v[126:127], v[176:177] op_sel_hi:[1,0]
	v_add_f32_e32 v147, 1.0, v147
	v_rcp_f32_e32 v178, v147
	v_add_f32_e32 v147, 1.0, v149
	v_mul_f32_e32 v149, 0xbfb8aa3b, v126
	v_exp_f32_e32 v149, v149
	v_mul_f32_e32 v151, 0xbfb8aa3b, v127
	v_exp_f32_e32 v151, v151
	v_rcp_f32_e32 v179, v147
	v_add_f32_e32 v147, 1.0, v149
	v_rcp_f32_e32 v180, v147
	v_add_f32_e32 v147, 1.0, v151
	v_pk_mul_f32 v[120:121], v[120:121], v[176:177] op_sel_hi:[1,0]
	v_rcp_f32_e32 v181, v147
	v_mul_f32_e32 v147, 0xbfb8aa3b, v120
	v_exp_f32_e32 v147, v147
	v_mul_f32_e32 v149, 0xbfb8aa3b, v121
	v_exp_f32_e32 v149, v149
	v_pk_mul_f32 v[122:123], v[122:123], v[176:177] op_sel_hi:[1,0]
	v_add_f32_e32 v147, 1.0, v147
	v_pk_mul_f32 v[124:125], v[124:125], v[178:179]
	v_rcp_f32_e32 v178, v147
	v_add_f32_e32 v147, 1.0, v149
	v_mul_f32_e32 v149, 0xbfb8aa3b, v122
	v_exp_f32_e32 v149, v149
	v_mul_f32_e32 v151, 0xbfb8aa3b, v123
	v_exp_f32_e32 v151, v151
	v_rcp_f32_e32 v179, v147
	v_add_f32_e32 v147, 1.0, v149
	v_pk_mul_f32 v[126:127], v[126:127], v[180:181]
	v_rcp_f32_e32 v180, v147
	v_add_f32_e32 v147, 1.0, v151
	v_rcp_f32_e32 v181, v147
	v_pk_mul_f32 v[116:117], v[116:117], v[176:177] op_sel_hi:[1,0]
	v_pk_mul_f32 v[118:119], v[118:119], v[176:177] op_sel_hi:[1,0]
	v_pk_mul_f32 v[120:121], v[120:121], v[178:179]
	v_pk_mul_f32 v[112:113], v[112:113], v[176:177] op_sel_hi:[1,0]
	v_lshl_or_b32 v182, s48, 7, v161
	v_pk_mul_f32 v[118:119], v[118:119], v[126:127]
	v_pk_mul_f32 v[116:117], v[116:117], v[124:125]
	v_pk_mul_f32 v[122:123], v[122:123], v[180:181]
	v_pk_mul_f32 v[114:115], v[114:115], v[176:177] op_sel_hi:[1,0]
	v_pk_mul_f32 v[112:113], v[112:113], v[120:121]
	v_ashrrev_i32_e32 v183, 31, v182
	v_pk_mul_f32 v[114:115], v[114:115], v[122:123]
	v_cvt_pk_bf16_f32 v116, v116, v117
	v_cvt_pk_bf16_f32 v117, v118, v119
	v_cvt_pk_bf16_f32 v118, v112, v113
	v_mov_b64_e32 v[112:113], s[10:11]
	v_cvt_pk_bf16_f32 v119, v114, v115
	v_mad_i64_i32 v[120:121], s[26:27], v170, s47, v[112:113]
	v_lshlrev_b64 v[114:115], 1, v[182:183]
	v_pk_mul_f32 v[108:109], v[108:109], v[174:175] op_sel_hi:[1,0]
	v_pk_mul_f32 v[110:111], v[110:111], v[174:175] op_sel_hi:[1,0]
	v_mul_f32_e32 v122, 0xbfb8aa3b, v108
	v_mul_f32_e32 v123, 0xbfb8aa3b, v109
	v_lshl_add_u64 v[120:121], v[120:121], 0, v[114:115]
	v_pk_mul_f32 v[104:105], v[104:105], v[174:175] op_sel_hi:[1,0]
	v_pk_mul_f32 v[106:107], v[106:107], v[174:175] op_sel_hi:[1,0]
	v_exp_f32_e32 v122, v122
	v_exp_f32_e32 v123, v123
	v_mul_f32_e32 v124, 0xbfb8aa3b, v110
	v_mul_f32_e32 v125, 0xbfb8aa3b, v111
	global_store_dwordx4 v[120:121], v[116:119], off
	v_exp_f32_e32 v124, v124
	v_exp_f32_e32 v125, v125
	v_mul_f32_e32 v116, 0xbfb8aa3b, v104
	v_mul_f32_e32 v117, 0xbfb8aa3b, v105
	v_mul_f32_e32 v118, 0xbfb8aa3b, v106
	v_mul_f32_e32 v119, 0xbfb8aa3b, v107
	v_exp_f32_e32 v116, v116
	v_exp_f32_e32 v117, v117
	v_exp_f32_e32 v118, v118
	v_exp_f32_e32 v119, v119
	v_add_f32_e32 v122, 1.0, v122
	v_add_f32_e32 v123, 1.0, v123
	v_rcp_f32_e32 v122, v122
	v_rcp_f32_e32 v123, v123
	v_add_f32_e32 v124, 1.0, v124
	v_add_f32_e32 v125, 1.0, v125
	v_add_f32_e32 v116, 1.0, v116
	v_add_f32_e32 v117, 1.0, v117
	v_add_f32_e32 v118, 1.0, v118
	v_add_f32_e32 v119, 1.0, v119
	v_rcp_f32_e32 v124, v124
	v_rcp_f32_e32 v125, v125
	v_rcp_f32_e32 v116, v116
	v_rcp_f32_e32 v117, v117
	v_rcp_f32_e32 v118, v118
	v_rcp_f32_e32 v119, v119
	v_pk_mul_f32 v[108:109], v[108:109], v[122:123]
	v_pk_mul_f32 v[100:101], v[100:101], v[174:175] op_sel_hi:[1,0]
	v_pk_mul_f32 v[110:111], v[110:111], v[124:125]
	v_pk_mul_f32 v[102:103], v[102:103], v[174:175] op_sel_hi:[1,0]
	v_pk_mul_f32 v[100:101], v[100:101], v[108:109]
	v_pk_mul_f32 v[104:105], v[104:105], v[116:117]
	v_pk_mul_f32 v[106:107], v[106:107], v[118:119]
	v_pk_mul_f32 v[96:97], v[96:97], v[174:175] op_sel_hi:[1,0]
	v_pk_mul_f32 v[98:99], v[98:99], v[174:175] op_sel_hi:[1,0]
	v_pk_mul_f32 v[102:103], v[102:103], v[110:111]
	v_pk_mul_f32 v[106:107], v[98:99], v[106:107]
	v_pk_mul_f32 v[98:99], v[96:97], v[104:105]
	v_cvt_pk_bf16_f32 v96, v100, v101
	v_mad_i64_i32 v[100:101], s[26:27], v166, s47, v[112:113]
	v_pk_mul_f32 v[92:93], v[92:93], v[172:173] op_sel_hi:[1,0]
	v_cvt_pk_bf16_f32 v97, v102, v103
	v_cvt_pk_bf16_f32 v98, v98, v99
	v_cvt_pk_bf16_f32 v99, v106, v107
	v_pk_mul_f32 v[94:95], v[94:95], v[172:173] op_sel_hi:[1,0]
	v_mul_f32_e32 v102, 0xbfb8aa3b, v92
	v_mul_f32_e32 v103, 0xbfb8aa3b, v93
	v_lshl_add_u64 v[100:101], v[100:101], 0, v[114:115]
	v_pk_mul_f32 v[88:89], v[88:89], v[172:173] op_sel_hi:[1,0]
	v_pk_mul_f32 v[90:91], v[90:91], v[172:173] op_sel_hi:[1,0]
	v_exp_f32_e32 v102, v102
	v_exp_f32_e32 v103, v103
	v_mul_f32_e32 v104, 0xbfb8aa3b, v94
	v_mul_f32_e32 v105, 0xbfb8aa3b, v95
	global_store_dwordx4 v[100:101], v[96:99], off
	v_exp_f32_e32 v104, v104
	v_exp_f32_e32 v105, v105
	v_mul_f32_e32 v96, 0xbfb8aa3b, v88
	v_mul_f32_e32 v97, 0xbfb8aa3b, v89
	v_mul_f32_e32 v98, 0xbfb8aa3b, v90
	v_mul_f32_e32 v99, 0xbfb8aa3b, v91
	v_exp_f32_e32 v96, v96
	v_exp_f32_e32 v97, v97
	v_exp_f32_e32 v98, v98
	v_exp_f32_e32 v99, v99
	v_add_f32_e32 v102, 1.0, v102
	v_add_f32_e32 v103, 1.0, v103
	v_rcp_f32_e32 v102, v102
	v_rcp_f32_e32 v103, v103
	v_add_f32_e32 v104, 1.0, v104
	v_add_f32_e32 v105, 1.0, v105
	v_add_f32_e32 v96, 1.0, v96
	v_add_f32_e32 v97, 1.0, v97
	v_add_f32_e32 v98, 1.0, v98
	v_add_f32_e32 v99, 1.0, v99
	v_rcp_f32_e32 v104, v104
; __device__ __forceinline__ u32x4 pack8(f32x4 a, f32x4 b) { u32x4 w; w.x = cvt_pk_bf16(a[0], a[1]); w.y = cvt_pk_bf16(a[2], a[3]); w.z = cvt_pk_bf16(b[0], b[1]); w.w = cvt_pk_bf16(b[2], b[3]); return w; }
; __device__ __forceinline__ float silu_f(float v) { return v * __builtin_amdgcn_rcpf(1.0f + __builtin_amdgcn_exp2f(v * -1.4426950408889634f)); }
; __device__ __forceinline__ f32x4 silu4(f32x4 v) { return (f32x4){silu_f(v[0]), silu_f(v[1]), silu_f(v[2]), silu_f(v[3])}; }
;     __device__ __forceinline__ void operator()(const f32x4 (&acc)[2][2][4][2], const Unit& u, int wr, int wc, int fr, int fq) const {
;     ...
;         for (int ai = 0; ai < 2; ++ai)
; #pragma unroll
;             for (int m = 0; m < 4; ++m) {
;                 const int row = u.pm * BM + ai * HALF + wr * 64 + m * 16 + fr;
;                 const float rstd = rs[ai][m];
;                 const f32x4 a0 = silu4(acc[ai][0][m][0] * rstd) * (acc[ai][1][m][0] * rstd);
;                 const f32x4 a1 = silu4(acc[ai][0][m][1] * rstd) * (acc[ai][1][m][1] * rstd);
;                 *(u32x4*)(ACT + (size_t)row * 2816 + col0) = pack8(a0, a1);
	v_rcp_f32_e32 v105, v105
	v_rcp_f32_e32 v96, v96
	v_rcp_f32_e32 v97, v97
	v_rcp_f32_e32 v98, v98
	v_rcp_f32_e32 v99, v99
	v_pk_mul_f32 v[92:93], v[92:93], v[102:103]
	v_pk_mul_f32 v[84:85], v[84:85], v[172:173] op_sel_hi:[1,0]
	v_pk_mul_f32 v[94:95], v[94:95], v[104:105]
	v_pk_mul_f32 v[86:87], v[86:87], v[172:173] op_sel_hi:[1,0]
	v_pk_mul_f32 v[84:85], v[84:85], v[92:93]
	v_pk_mul_f32 v[88:89], v[88:89], v[96:97]
	v_pk_mul_f32 v[90:91], v[90:91], v[98:99]
	v_pk_mul_f32 v[80:81], v[80:81], v[172:173] op_sel_hi:[1,0]
	v_pk_mul_f32 v[82:83], v[82:83], v[172:173] op_sel_hi:[1,0]
	v_pk_mul_f32 v[86:87], v[86:87], v[94:95]
	v_pk_mul_f32 v[90:91], v[82:83], v[90:91]
	v_pk_mul_f32 v[82:83], v[80:81], v[88:89]
	v_cvt_pk_bf16_f32 v80, v84, v85
	v_mad_i64_i32 v[84:85], s[26:27], v162, s47, v[112:113]
	v_pk_mul_f32 v[76:77], v[76:77], v[168:169] op_sel_hi:[1,0]
	v_cvt_pk_bf16_f32 v81, v86, v87
	v_cvt_pk_bf16_f32 v82, v82, v83
	v_cvt_pk_bf16_f32 v83, v90, v91
	v_pk_mul_f32 v[78:79], v[78:79], v[168:169] op_sel_hi:[1,0]
	v_mul_f32_e32 v86, 0xbfb8aa3b, v76
	v_mul_f32_e32 v87, 0xbfb8aa3b, v77
	v_lshl_add_u64 v[84:85], v[84:85], 0, v[114:115]
	v_pk_mul_f32 v[72:73], v[72:73], v[168:169] op_sel_hi:[1,0]
	v_pk_mul_f32 v[74:75], v[74:75], v[168:169] op_sel_hi:[1,0]
	v_exp_f32_e32 v86, v86
	v_exp_f32_e32 v87, v87
	v_mul_f32_e32 v88, 0xbfb8aa3b, v78
	v_mul_f32_e32 v89, 0xbfb8aa3b, v79
	global_store_dwordx4 v[84:85], v[80:83], off
	v_exp_f32_e32 v88, v88
	v_exp_f32_e32 v89, v89
	v_mul_f32_e32 v80, 0xbfb8aa3b, v72
	v_mul_f32_e32 v81, 0xbfb8aa3b, v73
	v_mul_f32_e32 v82, 0xbfb8aa3b, v74
	v_mul_f32_e32 v83, 0xbfb8aa3b, v75
	v_exp_f32_e32 v80, v80
	v_exp_f32_e32 v81, v81
	v_exp_f32_e32 v82, v82
	v_exp_f32_e32 v83, v83
	v_add_f32_e32 v86, 1.0, v86
	v_add_f32_e32 v87, 1.0, v87
	v_rcp_f32_e32 v86, v86
	v_rcp_f32_e32 v87, v87
	v_add_f32_e32 v88, 1.0, v88
	v_add_f32_e32 v89, 1.0, v89
	v_add_f32_e32 v80, 1.0, v80
	v_add_f32_e32 v81, 1.0, v81
	v_add_f32_e32 v82, 1.0, v82
	v_add_f32_e32 v83, 1.0, v83
	v_rcp_f32_e32 v88, v88
	v_rcp_f32_e32 v89, v89
	v_rcp_f32_e32 v80, v80
	v_rcp_f32_e32 v81, v81
	v_rcp_f32_e32 v82, v82
	v_rcp_f32_e32 v83, v83
	v_pk_mul_f32 v[76:77], v[76:77], v[86:87]
	v_pk_mul_f32 v[68:69], v[68:69], v[168:169] op_sel_hi:[1,0]
	v_pk_mul_f32 v[78:79], v[78:79], v[88:89]
	v_pk_mul_f32 v[70:71], v[70:71], v[168:169] op_sel_hi:[1,0]
	v_pk_mul_f32 v[68:69], v[68:69], v[76:77]
	v_pk_mul_f32 v[72:73], v[72:73], v[80:81]
	v_pk_mul_f32 v[74:75], v[74:75], v[82:83]
	v_pk_mul_f32 v[64:65], v[64:65], v[168:169] op_sel_hi:[1,0]
	v_pk_mul_f32 v[66:67], v[66:67], v[168:169] op_sel_hi:[1,0]
	v_pk_mul_f32 v[70:71], v[70:71], v[78:79]
	v_pk_mul_f32 v[74:75], v[66:67], v[74:75]
	v_pk_mul_f32 v[66:67], v[64:65], v[72:73]
	v_cvt_pk_bf16_f32 v64, v68, v69
	v_mad_i64_i32 v[68:69], s[26:27], v158, s47, v[112:113]
	v_pk_mul_f32 v[60:61], v[60:61], v[164:165] op_sel_hi:[1,0]
	v_cvt_pk_bf16_f32 v65, v70, v71
	v_cvt_pk_bf16_f32 v66, v66, v67
	v_cvt_pk_bf16_f32 v67, v74, v75
	v_pk_mul_f32 v[62:63], v[62:63], v[164:165] op_sel_hi:[1,0]
	v_mul_f32_e32 v70, 0xbfb8aa3b, v60
	v_mul_f32_e32 v71, 0xbfb8aa3b, v61
	v_lshl_add_u64 v[68:69], v[68:69], 0, v[114:115]
	v_pk_mul_f32 v[56:57], v[56:57], v[164:165] op_sel_hi:[1,0]
	v_pk_mul_f32 v[58:59], v[58:59], v[164:165] op_sel_hi:[1,0]
	v_exp_f32_e32 v70, v70
	v_exp_f32_e32 v71, v71
	v_mul_f32_e32 v72, 0xbfb8aa3b, v62
	v_mul_f32_e32 v73, 0xbfb8aa3b, v63
	global_store_dwordx4 v[68:69], v[64:67], off
	s_branch .Lhh3_epi_end
	v_exp_f32_e32 v72, v72
	v_exp_f32_e32 v73, v73
	v_mul_f32_e32 v64, 0xbfb8aa3b, v56
	v_mul_f32_e32 v65, 0xbfb8aa3b, v57
	v_mul_f32_e32 v66, 0xbfb8aa3b, v58
	v_mul_f32_e32 v67, 0xbfb8aa3b, v59
	v_exp_f32_e32 v64, v64
	v_exp_f32_e32 v65, v65
	v_exp_f32_e32 v66, v66
	v_exp_f32_e32 v67, v67
	v_add_f32_e32 v70, 1.0, v70
	v_add_f32_e32 v71, 1.0, v71
	v_rcp_f32_e32 v70, v70
	v_rcp_f32_e32 v71, v71
	v_add_f32_e32 v72, 1.0, v72
	v_add_f32_e32 v73, 1.0, v73
	v_add_f32_e32 v64, 1.0, v64
	v_add_f32_e32 v65, 1.0, v65
	v_add_f32_e32 v66, 1.0, v66
	v_add_f32_e32 v67, 1.0, v67
	v_rcp_f32_e32 v72, v72
	v_rcp_f32_e32 v73, v73
	v_rcp_f32_e32 v64, v64
	v_rcp_f32_e32 v65, v65
	v_rcp_f32_e32 v66, v66
	v_rcp_f32_e32 v67, v67
	v_pk_mul_f32 v[60:61], v[60:61], v[70:71]
	v_pk_mul_f32 v[52:53], v[52:53], v[164:165] op_sel_hi:[1,0]
	v_pk_mul_f32 v[62:63], v[62:63], v[72:73]
	v_pk_mul_f32 v[54:55], v[54:55], v[164:165] op_sel_hi:[1,0]
	v_pk_mul_f32 v[52:53], v[52:53], v[60:61]
	v_pk_mul_f32 v[56:57], v[56:57], v[64:65]
	v_pk_mul_f32 v[58:59], v[58:59], v[66:67]
	v_pk_mul_f32 v[48:49], v[48:49], v[164:165] op_sel_hi:[1,0]
	v_pk_mul_f32 v[50:51], v[50:51], v[164:165] op_sel_hi:[1,0]
	v_pk_mul_f32 v[54:55], v[54:55], v[62:63]
	v_pk_mul_f32 v[58:59], v[50:51], v[58:59]
	v_pk_mul_f32 v[50:51], v[48:49], v[56:57]
	v_cvt_pk_bf16_f32 v48, v52, v53
	v_mad_i64_i32 v[52:53], s[26:27], v154, s47, v[112:113]
	v_pk_mul_f32 v[44:45], v[44:45], v[160:161] op_sel_hi:[1,0]
	v_cvt_pk_bf16_f32 v49, v54, v55
	v_cvt_pk_bf16_f32 v50, v50, v51
	v_cvt_pk_bf16_f32 v51, v58, v59
	v_pk_mul_f32 v[46:47], v[46:47], v[160:161] op_sel_hi:[1,0]
	v_mul_f32_e32 v54, 0xbfb8aa3b, v44
	v_mul_f32_e32 v55, 0xbfb8aa3b, v45
	v_lshl_add_u64 v[52:53], v[52:53], 0, v[114:115]
	v_pk_mul_f32 v[40:41], v[40:41], v[160:161] op_sel_hi:[1,0]
	v_pk_mul_f32 v[42:43], v[42:43], v[160:161] op_sel_hi:[1,0]
	v_exp_f32_e32 v54, v54
	v_exp_f32_e32 v55, v55
	v_mul_f32_e32 v56, 0xbfb8aa3b, v46
	v_mul_f32_e32 v57, 0xbfb8aa3b, v47
	global_store_dwordx4 v[52:53], v[48:51], off
	v_exp_f32_e32 v56, v56
	v_exp_f32_e32 v57, v57
	v_mul_f32_e32 v48, 0xbfb8aa3b, v40
	v_mul_f32_e32 v49, 0xbfb8aa3b, v41
; __device__ __forceinline__ f32x4 silu4(f32x4 v) { return (f32x4){silu_f(v[0]), silu_f(v[1]), silu_f(v[2]), silu_f(v[3])}; }
; __device__ __forceinline__ u32x4 pack8(f32x4 a, f32x4 b) { u32x4 w; w.x = cvt_pk_bf16(a[0], a[1]); w.y = cvt_pk_bf16(a[2], a[3]); w.z = cvt_pk_bf16(b[0], b[1]); w.w = cvt_pk_bf16(b[2], b[3]); return w; }
;     __device__ __forceinline__ void operator()(const f32x4 (&acc)[2][2][4][2], const Unit& u, int wr, int wc, int fr, int fq) const {
;     ...
;         for (int ai = 0; ai < 2; ++ai)
; #pragma unroll
;             for (int m = 0; m < 4; ++m) {
;                 const int row = u.pm * BM + ai * HALF + wr * 64 + m * 16 + fr;
;                 const float rstd = rs[ai][m];
;                 const f32x4 a0 = silu4(acc[ai][0][m][0] * rstd) * (acc[ai][1][m][0] * rstd);
;                 const f32x4 a1 = silu4(acc[ai][0][m][1] * rstd) * (acc[ai][1][m][1] * rstd);
;                 *(u32x4*)(ACT + (size_t)row * 2816 + col0) = pack8(a0, a1);
	v_mul_f32_e32 v50, 0xbfb8aa3b, v42
	v_mul_f32_e32 v51, 0xbfb8aa3b, v43
	v_exp_f32_e32 v48, v48
	v_exp_f32_e32 v49, v49
	v_exp_f32_e32 v50, v50
	v_exp_f32_e32 v51, v51
	v_add_f32_e32 v54, 1.0, v54
	v_add_f32_e32 v55, 1.0, v55
	v_rcp_f32_e32 v54, v54
	v_rcp_f32_e32 v55, v55
	v_add_f32_e32 v56, 1.0, v56
	v_add_f32_e32 v57, 1.0, v57
	v_add_f32_e32 v48, 1.0, v48
	v_add_f32_e32 v49, 1.0, v49
	v_add_f32_e32 v50, 1.0, v50
	v_add_f32_e32 v51, 1.0, v51
	v_rcp_f32_e32 v56, v56
	v_rcp_f32_e32 v57, v57
	v_rcp_f32_e32 v48, v48
	v_rcp_f32_e32 v49, v49
	v_rcp_f32_e32 v50, v50
	v_rcp_f32_e32 v51, v51
	v_pk_mul_f32 v[44:45], v[44:45], v[54:55]
	v_pk_mul_f32 v[36:37], v[36:37], v[160:161] op_sel_hi:[1,0]
	v_pk_mul_f32 v[46:47], v[46:47], v[56:57]
	v_pk_mul_f32 v[38:39], v[38:39], v[160:161] op_sel_hi:[1,0]
	v_pk_mul_f32 v[36:37], v[36:37], v[44:45]
	v_pk_mul_f32 v[40:41], v[40:41], v[48:49]
	v_pk_mul_f32 v[42:43], v[42:43], v[50:51]
	v_pk_mul_f32 v[32:33], v[32:33], v[160:161] op_sel_hi:[1,0]
	v_pk_mul_f32 v[34:35], v[34:35], v[160:161] op_sel_hi:[1,0]
	v_pk_mul_f32 v[38:39], v[38:39], v[46:47]
	v_pk_mul_f32 v[42:43], v[34:35], v[42:43]
	v_pk_mul_f32 v[34:35], v[32:33], v[40:41]
	v_cvt_pk_bf16_f32 v32, v36, v37
	v_mad_i64_i32 v[36:37], s[26:27], v150, s47, v[112:113]
	v_pk_mul_f32 v[28:29], v[28:29], v[156:157] op_sel_hi:[1,0]
	v_cvt_pk_bf16_f32 v33, v38, v39
	v_cvt_pk_bf16_f32 v34, v34, v35
	v_cvt_pk_bf16_f32 v35, v42, v43
	v_pk_mul_f32 v[30:31], v[30:31], v[156:157] op_sel_hi:[1,0]
	v_mul_f32_e32 v38, 0xbfb8aa3b, v28
	v_mul_f32_e32 v39, 0xbfb8aa3b, v29
	v_lshl_add_u64 v[36:37], v[36:37], 0, v[114:115]
	v_pk_mul_f32 v[24:25], v[24:25], v[156:157] op_sel_hi:[1,0]
	v_pk_mul_f32 v[26:27], v[26:27], v[156:157] op_sel_hi:[1,0]
	v_exp_f32_e32 v38, v38
	v_exp_f32_e32 v39, v39
	v_mul_f32_e32 v40, 0xbfb8aa3b, v30
	v_mul_f32_e32 v41, 0xbfb8aa3b, v31
	global_store_dwordx4 v[36:37], v[32:35], off
	v_exp_f32_e32 v40, v40
	v_exp_f32_e32 v41, v41
	v_mul_f32_e32 v32, 0xbfb8aa3b, v24
	v_mul_f32_e32 v33, 0xbfb8aa3b, v25
	v_mul_f32_e32 v34, 0xbfb8aa3b, v26
	v_mul_f32_e32 v35, 0xbfb8aa3b, v27
	v_exp_f32_e32 v32, v32
	v_exp_f32_e32 v33, v33
	v_exp_f32_e32 v34, v34
	v_exp_f32_e32 v35, v35
	v_add_f32_e32 v38, 1.0, v38
	v_add_f32_e32 v39, 1.0, v39
	v_rcp_f32_e32 v38, v38
	v_rcp_f32_e32 v39, v39
	v_add_f32_e32 v40, 1.0, v40
	v_add_f32_e32 v41, 1.0, v41
	v_add_f32_e32 v32, 1.0, v32
	v_add_f32_e32 v33, 1.0, v33
	v_add_f32_e32 v34, 1.0, v34
	v_add_f32_e32 v35, 1.0, v35
	v_rcp_f32_e32 v40, v40
	v_rcp_f32_e32 v41, v41
	v_rcp_f32_e32 v32, v32
	v_rcp_f32_e32 v33, v33
	v_rcp_f32_e32 v34, v34
	v_rcp_f32_e32 v35, v35
	v_pk_mul_f32 v[28:29], v[28:29], v[38:39]
	v_pk_mul_f32 v[20:21], v[20:21], v[156:157] op_sel_hi:[1,0]
	v_pk_mul_f32 v[30:31], v[30:31], v[40:41]
	v_pk_mul_f32 v[22:23], v[22:23], v[156:157] op_sel_hi:[1,0]
	v_pk_mul_f32 v[20:21], v[20:21], v[28:29]
	v_pk_mul_f32 v[24:25], v[24:25], v[32:33]
	v_pk_mul_f32 v[26:27], v[26:27], v[34:35]
	v_pk_mul_f32 v[16:17], v[16:17], v[156:157] op_sel_hi:[1,0]
	v_pk_mul_f32 v[18:19], v[18:19], v[156:157] op_sel_hi:[1,0]
	v_pk_mul_f32 v[22:23], v[22:23], v[30:31]
	v_pk_mul_f32 v[26:27], v[18:19], v[26:27]
	v_pk_mul_f32 v[18:19], v[16:17], v[24:25]
	v_cvt_pk_bf16_f32 v16, v20, v21
	v_mad_i64_i32 v[20:21], s[26:27], v148, s47, v[112:113]
	v_pk_mul_f32 v[12:13], v[12:13], v[152:153] op_sel_hi:[1,0]
	v_cvt_pk_bf16_f32 v17, v22, v23
	v_cvt_pk_bf16_f32 v18, v18, v19
	v_cvt_pk_bf16_f32 v19, v26, v27
	v_lshl_add_u64 v[20:21], v[20:21], 0, v[114:115]
	v_mul_f32_e32 v22, 0xbfb8aa3b, v12
	v_mul_f32_e32 v23, 0xbfb8aa3b, v13
	v_pk_mul_f32 v[8:9], v[8:9], v[152:153] op_sel_hi:[1,0]
	v_pk_mul_f32 v[10:11], v[10:11], v[152:153] op_sel_hi:[1,0]
	v_exp_f32_e32 v22, v22
	v_exp_f32_e32 v23, v23
	global_store_dwordx4 v[20:21], v[16:19], off
	v_pk_mul_f32 v[14:15], v[14:15], v[152:153] op_sel_hi:[1,0]
	v_add_f32_e32 v22, 1.0, v22
	v_mul_f32_e32 v16, 0xbfb8aa3b, v8
	v_mul_f32_e32 v17, 0xbfb8aa3b, v9
	v_mul_f32_e32 v18, 0xbfb8aa3b, v10
	v_mul_f32_e32 v19, 0xbfb8aa3b, v11
	v_exp_f32_e32 v16, v16
	v_exp_f32_e32 v17, v17
	v_exp_f32_e32 v18, v18
	v_exp_f32_e32 v19, v19
	v_mul_f32_e32 v24, 0xbfb8aa3b, v14
	v_mul_f32_e32 v25, 0xbfb8aa3b, v15
	v_exp_f32_e32 v24, v24
	v_exp_f32_e32 v25, v25
	v_add_f32_e32 v23, 1.0, v23
	v_rcp_f32_e32 v22, v22
	v_rcp_f32_e32 v23, v23
	v_add_f32_e32 v16, 1.0, v16
	v_add_f32_e32 v17, 1.0, v17
	v_add_f32_e32 v18, 1.0, v18
	v_add_f32_e32 v19, 1.0, v19
	v_rcp_f32_e32 v16, v16
	v_rcp_f32_e32 v17, v17
	v_rcp_f32_e32 v18, v18
	v_rcp_f32_e32 v19, v19
	v_add_f32_e32 v24, 1.0, v24
	v_add_f32_e32 v25, 1.0, v25
	v_rcp_f32_e32 v24, v24
	v_rcp_f32_e32 v25, v25
	v_pk_mul_f32 v[12:13], v[12:13], v[22:23]
	v_pk_mul_f32 v[4:5], v[4:5], v[152:153] op_sel_hi:[1,0]
	v_pk_mul_f32 v[8:9], v[8:9], v[16:17]
	v_pk_mul_f32 v[4:5], v[4:5], v[12:13]
	v_pk_mul_f32 v[10:11], v[10:11], v[18:19]
	v_pk_mul_f32 v[0:1], v[0:1], v[152:153] op_sel_hi:[1,0]
	v_pk_mul_f32 v[2:3], v[2:3], v[152:153] op_sel_hi:[1,0]
	v_pk_mul_f32 v[14:15], v[14:15], v[24:25]
	v_pk_mul_f32 v[10:11], v[2:3], v[10:11]
	v_pk_mul_f32 v[2:3], v[0:1], v[8:9]
	v_cvt_pk_bf16_f32 v0, v4, v5
	v_mad_i64_i32 v[4:5], s[26:27], v146, s47, v[112:113]
	v_pk_mul_f32 v[6:7], v[6:7], v[152:153] op_sel_hi:[1,0]
	v_lshl_add_u64 v[4:5], v[4:5], 0, v[114:115]
	v_pk_mul_f32 v[6:7], v[6:7], v[14:15]
	s_nop 0
	v_cvt_pk_bf16_f32 v1, v6, v7
	v_cvt_pk_bf16_f32 v2, v2, v3
	v_cvt_pk_bf16_f32 v3, v10, v11
	global_store_dwordx4 v[4:5], v[0:3], off
.Lhh3_epi_end:
	s_cbranch_vccnz .LBB0_2036
	s_andn2_b64 vcc, exec, s[8:9]
	s_cbranch_vccnz .LBB0_2035
	s_barrier
	s_branch .LBB0_2035
